# GEMM K loops: just-in-time counted LDS-DMA waits (vmcnt(10) in phases 1,2,4,5,6,8: each stage retired one phase before its reader, every load gets at least five phases to land)
# speedup vs baseline: 1.0019x; 1.0019x over previous
; #define PG8_STAGE(bufoff, gbase, voff) do { _Pragma("unroll") for (int _i = 0; _i < 2; ++_i) \
;     __builtin_amdgcn_global_load_lds((const unsigned*)((const char*)(gbase) + (voff)[_i]), (LAS unsigned*)(lds + (bufoff) + ldsw + _i * 8192), 16, 0, 0); } while (0)
; #define PG8_LDA(dst, b, h) do { _Pragma("unroll") for (int m = 0; m < 4; ++m) _Pragma("unroll") for (int k = 0; k < 2; ++k) dst[m][k] = *(const LAS bf16x8*)(lds + PG8_SA(b, h) + aoff + m * 2048 + k * 1024); } while (0)
; #define PG8_LDB(dst, b, h) do { _Pragma("unroll") for (int n = 0; n < 2; ++n) _Pragma("unroll") for (int k = 0; k < 2; ++k) dst[n][k] = *(const LAS bf16x8*)(lds + PG8_SB(b, h) + boff + n * 2048 + k * 1024); } while (0)
; #define PG8_MMA(ai, bj, At, Bt) do { __builtin_amdgcn_s_setprio(1); _Pragma("unroll") for (int m = 0; m < 4; ++m) _Pragma("unroll") for (int n = 0; n < 2; ++n) _Pragma("unroll") for (int k = 0; k < 2; ++k) \
;     acc[ai][bj][m][n] = __builtin_amdgcn_mfma_f32_16x16x32_bf16(Bt[n][k], At[m][k], acc[ai][bj][m][n], 0, 0, 0); __builtin_amdgcn_s_setprio(0); } while (0)
; #define PG8_WAIT_L(n) asm volatile("s_waitcnt lgkmcnt(" #n ")" ::: "memory")
; #define PG8_BAR __builtin_amdgcn_s_barrier()
; #define PG8_SCHED __builtin_amdgcn_sched_barrier(0)
; template <class Epi, class Sched>
; DI void gemm_phase(LAS unsigned char* lds, const Gemm g, const Sched& S, const Epi& E) {
;     ...
;     for (int t = 0; t < nt; t += 2) {
;       const bool last = (t == nt - 2);
;       const char* a1 = cA + (size_t)(t + 1) * kstep;
;       const char* a2 = last ? nA : cA + (size_t)(t + 2) * kstep; const char* b2 = last ? nB : cB + (size_t)(t + 2) * kstep;
;       const char* a3 = a2 + kstep; const char* b3 = b2 + kstep;
;       PG8_LDB(B0, 0, 0); PG8_SCHED; PG8_LDA(At, 0, 0); PG8_STAGE(PG8_SA(1, 1), a1 + hstep, voffA);
;       PG8_WAIT_L(8); PG8_BAR; PG8_WAIT_L(0); PG8_MMA(0, 0, At, B0); PG8_BAR; PG8_SCHED;
;       PG8_LDB(B1, 0, 1); PG8_STAGE(PG8_SB(0, 0), b2, voffB);
;       PG8_BAR; PG8_WAIT_L(0); PG8_MMA(0, 1, At, B1); PG8_BAR;
;       PG8_LDA(At, 0, 1); PG8_STAGE(PG8_SA(0, 0), a2, voffA);
;       PG8_BAR; PG8_WAIT_L(0); PG8_MMA(1, 0, At, B0); PG8_BAR; PG8_SCHED;
.LBB0_137:
	s_add_i32 s41, s1, 2
	s_add_u32 s18, s16, 0x80
	s_addc_u32 s19, s17, 0
	s_cmp_lg_u32 s40, s1
	s_cselect_b32 s20, s18, 0
	s_cselect_b32 s1, s19, 0
	s_add_u32 s18, s14, s20
	s_addc_u32 s19, s15, s1
	s_add_i32 s42, 16, 0x10000
	v_add_u32_e32 v139, s42, v137
	ds_read_b128 v[140:143], v139
	ds_read_b128 v[144:147], v139 offset:1024
	ds_read_b128 v[150:153], v139 offset:2048
	ds_read_b128 v[154:157], v139 offset:3072
	s_add_u32 s20, s12, s20
	s_addc_u32 s21, s13, s1
	v_lshl_add_u64 v[180:181], v[132:133], 0, s[16:17]
	s_add_i32 m0, s31, 0xc000
	ds_read_b128 v[158:161], v138
	ds_read_b128 v[162:165], v138 offset:1024
	ds_read_b128 v[166:169], v138 offset:2048
	ds_read_b128 v[170:173], v138 offset:3072
	ds_read_b128 v[174:177], v138 offset:4096
	ds_read_b128 v[186:189], v138 offset:5120
	ds_read_b128 v[190:193], v138 offset:6144
	ds_read_b128 v[198:201], v138 offset:7168
	global_load_lds_dwordx4 v[180:181], off
	v_lshl_add_u64 v[180:181], v[134:135], 0, s[16:17]
	s_add_i32 m0, s31, 0xe000
	s_nop 0
	global_load_lds_dwordx4 v[180:181], off
	s_waitcnt lgkmcnt(8)
	s_waitcnt vmcnt(10)
	s_barrier
	s_waitcnt lgkmcnt(0)
	s_waitcnt lgkmcnt(0)
	v_mfma_f32_16x16x32_bf16 v[126:129], v[140:143], v[158:161], v[126:129]
	v_mfma_f32_16x16x32_bf16 v[122:125], v[150:153], v[158:161], v[122:125]
	v_mfma_f32_16x16x32_bf16 v[110:113], v[140:143], v[166:169], v[110:113]
	v_mfma_f32_16x16x32_bf16 v[106:109], v[150:153], v[166:169], v[106:109]
	v_mfma_f32_16x16x32_bf16 v[94:97], v[140:143], v[174:177], v[94:97]
	v_mfma_f32_16x16x32_bf16 v[90:93], v[150:153], v[174:177], v[90:93]
	v_mfma_f32_16x16x32_bf16 v[78:81], v[140:143], v[190:193], v[78:81]
	v_mfma_f32_16x16x32_bf16 v[74:77], v[150:153], v[190:193], v[74:77]
	v_mfma_f32_16x16x32_bf16 v[126:129], v[144:147], v[162:165], v[126:129]
	v_mfma_f32_16x16x32_bf16 v[122:125], v[154:157], v[162:165], v[122:125]
	v_mfma_f32_16x16x32_bf16 v[110:113], v[144:147], v[170:173], v[110:113]
	v_mfma_f32_16x16x32_bf16 v[106:109], v[154:157], v[170:173], v[106:109]
	v_mfma_f32_16x16x32_bf16 v[94:97], v[144:147], v[186:189], v[94:97]
	v_mfma_f32_16x16x32_bf16 v[90:93], v[154:157], v[186:189], v[90:93]
	v_mfma_f32_16x16x32_bf16 v[78:81], v[144:147], v[198:201], v[78:81]
	v_mfma_f32_16x16x32_bf16 v[74:77], v[154:157], v[198:201], v[74:77]
	s_barrier
	s_add_i32 s1, 16, 0x14000
	s_add_i32 s42, s42, s30
	v_add_u32_e32 v139, s1, v137
	v_lshl_add_u64 v[180:181], s[20:21], 0, v[0:1]
	s_mov_b32 m0, s42
	ds_read_b128 v[202:205], v139
	ds_read_b128 v[206:209], v139 offset:1024
	ds_read_b128 v[214:217], v139 offset:2048
	ds_read_b128 v[218:221], v139 offset:3072
	global_load_lds_dwordx4 v[180:181], off
	v_lshl_add_u64 v[182:183], s[20:21], 0, v[130:131]
	s_add_i32 m0, s42, 0x2000
	s_nop 0
	global_load_lds_dwordx4 v[182:183], off
	s_waitcnt vmcnt(10)
	s_barrier
	s_waitcnt lgkmcnt(0)
	s_waitcnt lgkmcnt(0)
	v_mfma_f32_16x16x32_bf16 v[118:121], v[202:205], v[158:161], v[118:121]
	v_mfma_f32_16x16x32_bf16 v[114:117], v[214:217], v[158:161], v[114:117]
	v_mfma_f32_16x16x32_bf16 v[102:105], v[202:205], v[166:169], v[102:105]
	v_mfma_f32_16x16x32_bf16 v[98:101], v[214:217], v[166:169], v[98:101]
	v_mfma_f32_16x16x32_bf16 v[86:89], v[202:205], v[174:177], v[86:89]
	v_mfma_f32_16x16x32_bf16 v[82:85], v[214:217], v[174:177], v[82:85]
	v_mfma_f32_16x16x32_bf16 v[70:73], v[202:205], v[190:193], v[70:73]
	v_mfma_f32_16x16x32_bf16 v[66:69], v[214:217], v[190:193], v[66:69]
	v_mfma_f32_16x16x32_bf16 v[118:121], v[206:209], v[162:165], v[118:121]
	v_mfma_f32_16x16x32_bf16 v[114:117], v[218:221], v[162:165], v[114:117]
	v_mfma_f32_16x16x32_bf16 v[102:105], v[206:209], v[170:173], v[102:105]
	v_mfma_f32_16x16x32_bf16 v[98:101], v[218:221], v[170:173], v[98:101]
	v_mfma_f32_16x16x32_bf16 v[86:89], v[206:209], v[186:189], v[86:89]
	v_mfma_f32_16x16x32_bf16 v[82:85], v[218:221], v[186:189], v[82:85]
	v_mfma_f32_16x16x32_bf16 v[70:73], v[206:209], v[198:201], v[70:73]
	v_mfma_f32_16x16x32_bf16 v[66:69], v[218:221], v[198:201], v[66:69]
	s_mov_b32 m0, s31
	v_lshl_add_u64 v[184:185], s[18:19], 0, v[0:1]
	s_barrier
	ds_read_b128 v[158:161], v138 offset:16384
	ds_read_b128 v[162:165], v138 offset:17408
	ds_read_b128 v[166:169], v138 offset:18432
	ds_read_b128 v[170:173], v138 offset:19456
	ds_read_b128 v[174:177], v138 offset:20480
	ds_read_b128 v[186:189], v138 offset:21504
	ds_read_b128 v[190:193], v138 offset:22528
	ds_read_b128 v[198:201], v138 offset:23552
	global_load_lds_dwordx4 v[184:185], off
	v_lshl_add_u64 v[222:223], s[18:19], 0, v[130:131]
	s_mov_b32 m0, s34
	s_nop 0
	global_load_lds_dwordx4 v[222:223], off
	s_barrier
	s_waitcnt lgkmcnt(0)
	s_waitcnt lgkmcnt(0)
	v_mfma_f32_16x16x32_bf16 v[62:65], v[140:143], v[158:161], v[62:65]
	v_mfma_f32_16x16x32_bf16 v[58:61], v[150:153], v[158:161], v[58:61]
	v_mfma_f32_16x16x32_bf16 v[46:49], v[140:143], v[166:169], v[46:49]
	v_mfma_f32_16x16x32_bf16 v[42:45], v[150:153], v[166:169], v[42:45]
	v_mfma_f32_16x16x32_bf16 v[30:33], v[140:143], v[174:177], v[30:33]
	v_mfma_f32_16x16x32_bf16 v[26:29], v[150:153], v[174:177], v[26:29]
	v_mfma_f32_16x16x32_bf16 v[14:17], v[140:143], v[190:193], v[14:17]
	v_mfma_f32_16x16x32_bf16 v[10:13], v[150:153], v[190:193], v[10:13]
	v_mfma_f32_16x16x32_bf16 v[62:65], v[144:147], v[162:165], v[62:65]
	v_mfma_f32_16x16x32_bf16 v[58:61], v[154:157], v[162:165], v[58:61]
	v_mfma_f32_16x16x32_bf16 v[46:49], v[144:147], v[170:173], v[46:49]
	v_mfma_f32_16x16x32_bf16 v[42:45], v[154:157], v[170:173], v[42:45]
	v_mfma_f32_16x16x32_bf16 v[30:33], v[144:147], v[186:189], v[30:33]
	v_mfma_f32_16x16x32_bf16 v[26:29], v[154:157], v[186:189], v[26:29]
	v_mfma_f32_16x16x32_bf16 v[14:17], v[144:147], v[198:201], v[14:17]
	v_mfma_f32_16x16x32_bf16 v[10:13], v[154:157], v[198:201], v[10:13]
	s_barrier
; #define PG8_STAGE(bufoff, gbase, voff) do { _Pragma("unroll") for (int _i = 0; _i < 2; ++_i) \
;     __builtin_amdgcn_global_load_lds((const unsigned*)((const char*)(gbase) + (voff)[_i]), (LAS unsigned*)(lds + (bufoff) + ldsw + _i * 8192), 16, 0, 0); } while (0)
; #define PG8_LDA(dst, b, h) do { _Pragma("unroll") for (int m = 0; m < 4; ++m) _Pragma("unroll") for (int k = 0; k < 2; ++k) dst[m][k] = *(const LAS bf16x8*)(lds + PG8_SA(b, h) + aoff + m * 2048 + k * 1024); } while (0)
; #define PG8_LDB(dst, b, h) do { _Pragma("unroll") for (int n = 0; n < 2; ++n) _Pragma("unroll") for (int k = 0; k < 2; ++k) dst[n][k] = *(const LAS bf16x8*)(lds + PG8_SB(b, h) + boff + n * 2048 + k * 1024); } while (0)
; #define PG8_MMA(ai, bj, At, Bt) do { __builtin_amdgcn_s_setprio(1); _Pragma("unroll") for (int m = 0; m < 4; ++m) _Pragma("unroll") for (int n = 0; n < 2; ++n) _Pragma("unroll") for (int k = 0; k < 2; ++k) \
;     acc[ai][bj][m][n] = __builtin_amdgcn_mfma_f32_16x16x32_bf16(Bt[n][k], At[m][k], acc[ai][bj][m][n], 0, 0, 0); __builtin_amdgcn_s_setprio(0); } while (0)
; #define PG8_WAIT_V(n) asm volatile("s_waitcnt vmcnt(" #n ")" ::: "memory")
; #define PG8_WAIT_L(n) asm volatile("s_waitcnt lgkmcnt(" #n ")" ::: "memory")
; #define PG8_BAR __builtin_amdgcn_s_barrier()
; #define PG8_SCHED __builtin_amdgcn_sched_barrier(0)
; template <class Epi, class Sched>
; DI void gemm_phase(LAS unsigned char* lds, const Gemm g, const Sched& S, const Epi& E) {
;     ...
;       PG8_STAGE(PG8_SB(0, 1), b2 + hstepB, voffB);
;       PG8_WAIT_V(6); PG8_BAR; PG8_MMA(1, 1, At, B1); PG8_BAR;
;       PG8_LDB(B0, 1, 0); PG8_SCHED; PG8_LDA(At, 1, 0); PG8_STAGE(PG8_SA(0, 1), a2 + hstep, voffA);
;       PG8_WAIT_L(8); PG8_BAR; PG8_WAIT_L(0); PG8_MMA(0, 0, At, B0); PG8_BAR; PG8_SCHED;
;       PG8_LDB(B1, 1, 1); PG8_STAGE(PG8_SB(1, 0), b3, voffB);
;       PG8_BAR; PG8_WAIT_L(0); PG8_MMA(0, 1, At, B1); PG8_BAR;
	s_add_u32 s20, s20, s2
	s_addc_u32 s21, s21, s3
	s_add_i32 s1, s1, s30
	v_lshl_add_u64 v[224:225], s[20:21], 0, v[0:1]
	s_mov_b32 m0, s1
	v_lshl_add_u64 v[226:227], s[20:21], 0, v[130:131]
	global_load_lds_dwordx4 v[224:225], off
	s_add_i32 m0, s1, 0x2000
	s_nop 0
	global_load_lds_dwordx4 v[226:227], off
	s_waitcnt vmcnt(10)
	s_barrier
	v_mfma_f32_16x16x32_bf16 v[54:57], v[202:205], v[158:161], v[54:57]
	v_mfma_f32_16x16x32_bf16 v[50:53], v[214:217], v[158:161], v[50:53]
	v_mfma_f32_16x16x32_bf16 v[38:41], v[202:205], v[166:169], v[38:41]
	v_mfma_f32_16x16x32_bf16 v[34:37], v[214:217], v[166:169], v[34:37]
	v_mfma_f32_16x16x32_bf16 v[22:25], v[202:205], v[174:177], v[22:25]
	v_mfma_f32_16x16x32_bf16 v[18:21], v[214:217], v[174:177], v[18:21]
	v_mfma_f32_16x16x32_bf16 v[6:9], v[202:205], v[190:193], v[6:9]
	v_mfma_f32_16x16x32_bf16 v[2:5], v[214:217], v[190:193], v[2:5]
	v_mfma_f32_16x16x32_bf16 v[54:57], v[206:209], v[162:165], v[54:57]
	v_mfma_f32_16x16x32_bf16 v[50:53], v[218:221], v[162:165], v[50:53]
	v_mfma_f32_16x16x32_bf16 v[38:41], v[206:209], v[170:173], v[38:41]
	v_mfma_f32_16x16x32_bf16 v[34:37], v[218:221], v[170:173], v[34:37]
	v_mfma_f32_16x16x32_bf16 v[22:25], v[206:209], v[186:189], v[22:25]
	v_mfma_f32_16x16x32_bf16 v[18:21], v[218:221], v[186:189], v[18:21]
	v_mfma_f32_16x16x32_bf16 v[6:9], v[206:209], v[198:201], v[6:9]
	v_mfma_f32_16x16x32_bf16 v[2:5], v[218:221], v[198:201], v[2:5]
	s_add_i32 s1, 16, 0x18000
	v_add_u32_e32 v139, s1, v137
	s_barrier
	ds_read_b128 v[140:143], v139
	ds_read_b128 v[144:147], v139 offset:1024
	ds_read_b128 v[150:153], v139 offset:2048
	ds_read_b128 v[154:157], v139 offset:3072
	s_add_u32 s18, s18, s2
	s_addc_u32 s19, s19, s3
	s_mov_b32 m0, s35
	v_lshl_add_u64 v[202:203], s[18:19], 0, v[0:1]
	ds_read_b128 v[158:161], v138 offset:32768
	ds_read_b128 v[162:165], v138 offset:33792
	ds_read_b128 v[166:169], v138 offset:34816
	ds_read_b128 v[170:173], v138 offset:35840
	ds_read_b128 v[174:177], v138 offset:36864
	ds_read_b128 v[186:189], v138 offset:37888
	ds_read_b128 v[190:193], v138 offset:38912
	ds_read_b128 v[198:201], v138 offset:39936
	global_load_lds_dwordx4 v[202:203], off
	v_lshl_add_u64 v[202:203], s[18:19], 0, v[130:131]
	s_mov_b32 m0, s36
	s_nop 0
	global_load_lds_dwordx4 v[202:203], off
	s_waitcnt lgkmcnt(8)
	s_waitcnt vmcnt(10)
	s_barrier
	s_waitcnt lgkmcnt(0)
	s_waitcnt lgkmcnt(0)
	v_mfma_f32_16x16x32_bf16 v[126:129], v[140:143], v[158:161], v[126:129]
	v_mfma_f32_16x16x32_bf16 v[122:125], v[150:153], v[158:161], v[122:125]
	v_mfma_f32_16x16x32_bf16 v[110:113], v[140:143], v[166:169], v[110:113]
	v_mfma_f32_16x16x32_bf16 v[106:109], v[150:153], v[166:169], v[106:109]
	v_mfma_f32_16x16x32_bf16 v[94:97], v[140:143], v[174:177], v[94:97]
	v_mfma_f32_16x16x32_bf16 v[90:93], v[150:153], v[174:177], v[90:93]
	v_mfma_f32_16x16x32_bf16 v[78:81], v[140:143], v[190:193], v[78:81]
	v_mfma_f32_16x16x32_bf16 v[74:77], v[150:153], v[190:193], v[74:77]
	v_mfma_f32_16x16x32_bf16 v[126:129], v[144:147], v[162:165], v[126:129]
	v_mfma_f32_16x16x32_bf16 v[122:125], v[154:157], v[162:165], v[122:125]
	v_mfma_f32_16x16x32_bf16 v[110:113], v[144:147], v[170:173], v[110:113]
	v_mfma_f32_16x16x32_bf16 v[106:109], v[154:157], v[170:173], v[106:109]
	v_mfma_f32_16x16x32_bf16 v[94:97], v[144:147], v[186:189], v[94:97]
	v_mfma_f32_16x16x32_bf16 v[90:93], v[154:157], v[186:189], v[90:93]
	v_mfma_f32_16x16x32_bf16 v[78:81], v[144:147], v[198:201], v[78:81]
	v_mfma_f32_16x16x32_bf16 v[74:77], v[154:157], v[198:201], v[74:77]
	s_barrier
	s_add_i32 s18, 16, 0x1c000
	s_add_i32 s1, s1, s30
	v_add_u32_e32 v139, s18, v137
	v_lshl_add_u64 v[180:181], v[180:181], 0, s[70:71]
	s_mov_b32 m0, s1
	ds_read_b128 v[202:205], v139
	ds_read_b128 v[206:209], v139 offset:1024
	ds_read_b128 v[214:217], v139 offset:2048
	ds_read_b128 v[218:221], v139 offset:3072
	global_load_lds_dwordx4 v[180:181], off
	v_lshl_add_u64 v[180:181], v[182:183], 0, s[70:71]
	s_add_i32 m0, s1, 0x2000
	s_nop 0
	global_load_lds_dwordx4 v[180:181], off
	s_waitcnt vmcnt(10)
	s_barrier
; #define PG8_STAGE(bufoff, gbase, voff) do { _Pragma("unroll") for (int _i = 0; _i < 2; ++_i) \
;     __builtin_amdgcn_global_load_lds((const unsigned*)((const char*)(gbase) + (voff)[_i]), (LAS unsigned*)(lds + (bufoff) + ldsw + _i * 8192), 16, 0, 0); } while (0)
; #define PG8_LDA(dst, b, h) do { _Pragma("unroll") for (int m = 0; m < 4; ++m) _Pragma("unroll") for (int k = 0; k < 2; ++k) dst[m][k] = *(const LAS bf16x8*)(lds + PG8_SA(b, h) + aoff + m * 2048 + k * 1024); } while (0)
; #define PG8_MMA(ai, bj, At, Bt) do { __builtin_amdgcn_s_setprio(1); _Pragma("unroll") for (int m = 0; m < 4; ++m) _Pragma("unroll") for (int n = 0; n < 2; ++n) _Pragma("unroll") for (int k = 0; k < 2; ++k) \
;     acc[ai][bj][m][n] = __builtin_amdgcn_mfma_f32_16x16x32_bf16(Bt[n][k], At[m][k], acc[ai][bj][m][n], 0, 0, 0); __builtin_amdgcn_s_setprio(0); } while (0)
; #define PG8_WAIT_V(n) asm volatile("s_waitcnt vmcnt(" #n ")" ::: "memory")
; #define PG8_WAIT_L(n) asm volatile("s_waitcnt lgkmcnt(" #n ")" ::: "memory")
; #define PG8_BAR __builtin_amdgcn_s_barrier()
; #define PG8_SCHED __builtin_amdgcn_sched_barrier(0)
; template <class Epi, class Sched>
; DI void gemm_phase(LAS unsigned char* lds, const Gemm g, const Sched& S, const Epi& E) {
;     ...
;       PG8_LDA(At, 1, 1); PG8_STAGE(PG8_SA(1, 0), a3, voffA);
;       PG8_BAR; PG8_WAIT_L(0); PG8_MMA(1, 0, At, B0); PG8_BAR; PG8_SCHED;
;       PG8_STAGE(PG8_SB(1, 1), b3 + hstepB, voffB);
;       PG8_WAIT_V(6); PG8_BAR; PG8_MMA(1, 1, At, B1); PG8_BAR;
;     }
	s_waitcnt lgkmcnt(0)
	s_waitcnt lgkmcnt(0)
	v_mfma_f32_16x16x32_bf16 v[118:121], v[202:205], v[158:161], v[118:121]
	v_mfma_f32_16x16x32_bf16 v[114:117], v[214:217], v[158:161], v[114:117]
	v_mfma_f32_16x16x32_bf16 v[102:105], v[202:205], v[166:169], v[102:105]
	v_mfma_f32_16x16x32_bf16 v[98:101], v[214:217], v[166:169], v[98:101]
	v_mfma_f32_16x16x32_bf16 v[86:89], v[202:205], v[174:177], v[86:89]
	v_mfma_f32_16x16x32_bf16 v[82:85], v[214:217], v[174:177], v[82:85]
	v_mfma_f32_16x16x32_bf16 v[70:73], v[202:205], v[190:193], v[70:73]
	v_mfma_f32_16x16x32_bf16 v[66:69], v[214:217], v[190:193], v[66:69]
	v_mfma_f32_16x16x32_bf16 v[118:121], v[206:209], v[162:165], v[118:121]
	v_mfma_f32_16x16x32_bf16 v[114:117], v[218:221], v[162:165], v[114:117]
	v_mfma_f32_16x16x32_bf16 v[102:105], v[206:209], v[170:173], v[102:105]
	v_mfma_f32_16x16x32_bf16 v[98:101], v[218:221], v[170:173], v[98:101]
	v_mfma_f32_16x16x32_bf16 v[86:89], v[206:209], v[186:189], v[86:89]
	v_mfma_f32_16x16x32_bf16 v[82:85], v[218:221], v[186:189], v[82:85]
	v_mfma_f32_16x16x32_bf16 v[70:73], v[206:209], v[198:201], v[70:73]
	v_mfma_f32_16x16x32_bf16 v[66:69], v[218:221], v[198:201], v[66:69]
	s_mov_b32 m0, s37
	v_lshl_add_u64 v[180:181], v[184:185], 0, s[70:71]
	s_barrier
	ds_read_b128 v[158:161], v138 offset:49152
	ds_read_b128 v[162:165], v138 offset:50176
	ds_read_b128 v[166:169], v138 offset:51200
	ds_read_b128 v[170:173], v138 offset:52224
	ds_read_b128 v[174:177], v138 offset:53248
	ds_read_b128 v[186:189], v138 offset:54272
	ds_read_b128 v[190:193], v138 offset:55296
	ds_read_b128 v[198:201], v138 offset:56320
	global_load_lds_dwordx4 v[180:181], off
	v_lshl_add_u64 v[180:181], v[222:223], 0, s[70:71]
	s_mov_b32 m0, s38
	s_nop 0
	global_load_lds_dwordx4 v[180:181], off
	s_barrier
	s_waitcnt lgkmcnt(0)
	s_waitcnt lgkmcnt(0)
	v_mfma_f32_16x16x32_bf16 v[62:65], v[140:143], v[158:161], v[62:65]
	v_mfma_f32_16x16x32_bf16 v[58:61], v[150:153], v[158:161], v[58:61]
	v_mfma_f32_16x16x32_bf16 v[46:49], v[140:143], v[166:169], v[46:49]
	v_mfma_f32_16x16x32_bf16 v[42:45], v[150:153], v[166:169], v[42:45]
	v_mfma_f32_16x16x32_bf16 v[30:33], v[140:143], v[174:177], v[30:33]
	v_mfma_f32_16x16x32_bf16 v[26:29], v[150:153], v[174:177], v[26:29]
	v_mfma_f32_16x16x32_bf16 v[14:17], v[140:143], v[190:193], v[14:17]
	v_mfma_f32_16x16x32_bf16 v[10:13], v[150:153], v[190:193], v[10:13]
	v_mfma_f32_16x16x32_bf16 v[62:65], v[144:147], v[162:165], v[62:65]
	v_mfma_f32_16x16x32_bf16 v[58:61], v[154:157], v[162:165], v[58:61]
	v_mfma_f32_16x16x32_bf16 v[46:49], v[144:147], v[170:173], v[46:49]
	v_mfma_f32_16x16x32_bf16 v[42:45], v[154:157], v[170:173], v[42:45]
	v_mfma_f32_16x16x32_bf16 v[30:33], v[144:147], v[186:189], v[30:33]
	v_mfma_f32_16x16x32_bf16 v[26:29], v[154:157], v[186:189], v[26:29]
	v_mfma_f32_16x16x32_bf16 v[14:17], v[144:147], v[198:201], v[14:17]
	v_mfma_f32_16x16x32_bf16 v[10:13], v[154:157], v[198:201], v[10:13]
	s_barrier
	s_add_i32 s1, s18, s30
	v_lshl_add_u64 v[140:141], v[224:225], 0, s[70:71]
	s_mov_b32 m0, s1
	s_nop 0
	global_load_lds_dwordx4 v[140:141], off
	v_lshl_add_u64 v[140:141], v[226:227], 0, s[70:71]
	s_add_i32 m0, s1, 0x2000
	s_nop 0
	global_load_lds_dwordx4 v[140:141], off
	s_waitcnt vmcnt(10)
	s_barrier
	v_mfma_f32_16x16x32_bf16 v[54:57], v[202:205], v[158:161], v[54:57]
	v_mfma_f32_16x16x32_bf16 v[50:53], v[214:217], v[158:161], v[50:53]
	v_mfma_f32_16x16x32_bf16 v[38:41], v[202:205], v[166:169], v[38:41]
	v_mfma_f32_16x16x32_bf16 v[34:37], v[214:217], v[166:169], v[34:37]
	v_mfma_f32_16x16x32_bf16 v[22:25], v[202:205], v[174:177], v[22:25]
	v_mfma_f32_16x16x32_bf16 v[18:21], v[214:217], v[174:177], v[18:21]
	v_mfma_f32_16x16x32_bf16 v[6:9], v[202:205], v[190:193], v[6:9]
	v_mfma_f32_16x16x32_bf16 v[2:5], v[214:217], v[190:193], v[2:5]
	v_mfma_f32_16x16x32_bf16 v[54:57], v[206:209], v[162:165], v[54:57]
	v_mfma_f32_16x16x32_bf16 v[50:53], v[218:221], v[162:165], v[50:53]
	v_mfma_f32_16x16x32_bf16 v[38:41], v[206:209], v[170:173], v[38:41]
	v_mfma_f32_16x16x32_bf16 v[34:37], v[218:221], v[170:173], v[34:37]
	v_mfma_f32_16x16x32_bf16 v[22:25], v[206:209], v[186:189], v[22:25]
	v_mfma_f32_16x16x32_bf16 v[18:21], v[218:221], v[186:189], v[18:21]
	v_mfma_f32_16x16x32_bf16 v[6:9], v[206:209], v[198:201], v[6:9]
	v_mfma_f32_16x16x32_bf16 v[2:5], v[218:221], v[198:201], v[2:5]
	s_add_u32 s16, s16, 0x100
	s_addc_u32 s17, s17, 0
	s_cmp_ge_i32 s41, s39
	s_mov_b32 s1, s41
	s_barrier
	s_cbranch_scc0 .LBB0_137

; #define PG8_STAGE(bufoff, gbase, voff) do { _Pragma("unroll") for (int _i = 0; _i < 2; ++_i) \
;     __builtin_amdgcn_global_load_lds((const unsigned*)((const char*)(gbase) + (voff)[_i]), (LAS unsigned*)(lds + (bufoff) + ldsw + _i * 8192), 16, 0, 0); } while (0)
; #define PG8_LDA(dst, b, h) do { _Pragma("unroll") for (int m = 0; m < 4; ++m) _Pragma("unroll") for (int k = 0; k < 2; ++k) dst[m][k] = *(const LAS bf16x8*)(lds + PG8_SA(b, h) + aoff + m * 2048 + k * 1024); } while (0)
; #define PG8_LDB(dst, b, h) do { _Pragma("unroll") for (int n = 0; n < 2; ++n) _Pragma("unroll") for (int k = 0; k < 2; ++k) dst[n][k] = *(const LAS bf16x8*)(lds + PG8_SB(b, h) + boff + n * 2048 + k * 1024); } while (0)
; #define PG8_MMA(ai, bj, At, Bt) do { __builtin_amdgcn_s_setprio(1); _Pragma("unroll") for (int m = 0; m < 4; ++m) _Pragma("unroll") for (int n = 0; n < 2; ++n) _Pragma("unroll") for (int k = 0; k < 2; ++k) \
;     acc[ai][bj][m][n] = __builtin_amdgcn_mfma_f32_16x16x32_bf16(Bt[n][k], At[m][k], acc[ai][bj][m][n], 0, 0, 0); __builtin_amdgcn_s_setprio(0); } while (0)
; #define PG8_WAIT_L(n) asm volatile("s_waitcnt lgkmcnt(" #n ")" ::: "memory")
; #define PG8_BAR __builtin_amdgcn_s_barrier()
; #define PG8_SCHED __builtin_amdgcn_sched_barrier(0)
; template <class Epi, class Sched>
; DI void gemm_phase(LAS unsigned char* lds, const Gemm g, const Sched& S, const Epi& E) {
;     ...
;     for (int t = 0; t < nt; t += 2) {
;       const bool last = (t == nt - 2);
;       const char* a1 = cA + (size_t)(t + 1) * kstep;
;       const char* a2 = last ? nA : cA + (size_t)(t + 2) * kstep; const char* b2 = last ? nB : cB + (size_t)(t + 2) * kstep;
;       const char* a3 = a2 + kstep; const char* b3 = b2 + kstep;
;       PG8_LDB(B0, 0, 0); PG8_SCHED; PG8_LDA(At, 0, 0); PG8_STAGE(PG8_SA(1, 1), a1 + hstep, voffA);
;       PG8_WAIT_L(8); PG8_BAR; PG8_WAIT_L(0); PG8_MMA(0, 0, At, B0); PG8_BAR; PG8_SCHED;
;       PG8_LDB(B1, 0, 1); PG8_STAGE(PG8_SB(0, 0), b2, voffB);
;       PG8_BAR; PG8_WAIT_L(0); PG8_MMA(0, 1, At, B1); PG8_BAR;
;       PG8_LDA(At, 0, 1); PG8_STAGE(PG8_SA(0, 0), a2, voffA);
;       PG8_BAR; PG8_WAIT_L(0); PG8_MMA(1, 0, At, B0); PG8_BAR; PG8_SCHED;
.LBB0_153:
	s_add_i32 s36, s16, 2
	s_add_u32 s17, s14, 0xfa800080
	s_addc_u32 s18, s15, -1
	s_cmp_lg_u32 s35, s16
	s_cselect_b32 s19, s18, 0
	s_cselect_b32 s18, s17, 0
	s_add_u32 s16, s12, s18
	s_addc_u32 s17, s13, s19
	s_add_i32 s37, 16, 0x10000
	v_add_u32_e32 v139, s37, v137
	ds_read_b128 v[140:143], v139
	ds_read_b128 v[144:147], v139 offset:1024
	ds_read_b128 v[150:153], v139 offset:2048
	ds_read_b128 v[154:157], v139 offset:3072
	s_add_u32 s18, s2, s18
	s_addc_u32 s19, s3, s19
	v_lshl_add_u64 v[180:181], v[132:133], 0, s[14:15]
	s_add_i32 m0, s24, 0xc000
	ds_read_b128 v[158:161], v138
	ds_read_b128 v[162:165], v138 offset:1024
	ds_read_b128 v[166:169], v138 offset:2048
	ds_read_b128 v[170:173], v138 offset:3072
	ds_read_b128 v[174:177], v138 offset:4096
	ds_read_b128 v[186:189], v138 offset:5120
	ds_read_b128 v[190:193], v138 offset:6144
	ds_read_b128 v[198:201], v138 offset:7168
	global_load_lds_dwordx4 v[180:181], off
	v_lshl_add_u64 v[180:181], v[134:135], 0, s[14:15]
	s_add_i32 m0, s24, 0xe000
	s_nop 0
	global_load_lds_dwordx4 v[180:181], off
	s_waitcnt lgkmcnt(8)
	s_waitcnt vmcnt(10)
	s_barrier
	s_waitcnt lgkmcnt(0)
	s_waitcnt lgkmcnt(0)
	v_mfma_f32_16x16x32_bf16 v[126:129], v[140:143], v[158:161], v[126:129]
	v_mfma_f32_16x16x32_bf16 v[122:125], v[150:153], v[158:161], v[122:125]
	v_mfma_f32_16x16x32_bf16 v[110:113], v[140:143], v[166:169], v[110:113]
	v_mfma_f32_16x16x32_bf16 v[106:109], v[150:153], v[166:169], v[106:109]
	v_mfma_f32_16x16x32_bf16 v[94:97], v[140:143], v[174:177], v[94:97]
	v_mfma_f32_16x16x32_bf16 v[90:93], v[150:153], v[174:177], v[90:93]
	v_mfma_f32_16x16x32_bf16 v[78:81], v[140:143], v[190:193], v[78:81]
	v_mfma_f32_16x16x32_bf16 v[74:77], v[150:153], v[190:193], v[74:77]
	v_mfma_f32_16x16x32_bf16 v[126:129], v[144:147], v[162:165], v[126:129]
	v_mfma_f32_16x16x32_bf16 v[122:125], v[154:157], v[162:165], v[122:125]
	v_mfma_f32_16x16x32_bf16 v[110:113], v[144:147], v[170:173], v[110:113]
	v_mfma_f32_16x16x32_bf16 v[106:109], v[154:157], v[170:173], v[106:109]
	v_mfma_f32_16x16x32_bf16 v[94:97], v[144:147], v[186:189], v[94:97]
	v_mfma_f32_16x16x32_bf16 v[90:93], v[154:157], v[186:189], v[90:93]
	v_mfma_f32_16x16x32_bf16 v[78:81], v[144:147], v[198:201], v[78:81]
	v_mfma_f32_16x16x32_bf16 v[74:77], v[154:157], v[198:201], v[74:77]
	s_barrier
	s_add_i32 s38, 16, 0x14000
	s_add_i32 s37, s37, s23
	v_add_u32_e32 v139, s38, v137
	v_lshl_add_u64 v[180:181], s[18:19], 0, v[0:1]
	s_mov_b32 m0, s37
	ds_read_b128 v[202:205], v139
	ds_read_b128 v[206:209], v139 offset:1024
	ds_read_b128 v[214:217], v139 offset:2048
	ds_read_b128 v[218:221], v139 offset:3072
	global_load_lds_dwordx4 v[180:181], off
	v_lshl_add_u64 v[182:183], s[18:19], 0, v[130:131]
	s_add_i32 m0, s37, 0x2000
	s_nop 0
	global_load_lds_dwordx4 v[182:183], off
	s_waitcnt vmcnt(10)
	s_barrier
	s_waitcnt lgkmcnt(0)
	s_waitcnt lgkmcnt(0)
	v_mfma_f32_16x16x32_bf16 v[118:121], v[202:205], v[158:161], v[118:121]
	v_mfma_f32_16x16x32_bf16 v[114:117], v[214:217], v[158:161], v[114:117]
	v_mfma_f32_16x16x32_bf16 v[102:105], v[202:205], v[166:169], v[102:105]
	v_mfma_f32_16x16x32_bf16 v[98:101], v[214:217], v[166:169], v[98:101]
	v_mfma_f32_16x16x32_bf16 v[86:89], v[202:205], v[174:177], v[86:89]
	v_mfma_f32_16x16x32_bf16 v[82:85], v[214:217], v[174:177], v[82:85]
	v_mfma_f32_16x16x32_bf16 v[70:73], v[202:205], v[190:193], v[70:73]
	v_mfma_f32_16x16x32_bf16 v[66:69], v[214:217], v[190:193], v[66:69]
	v_mfma_f32_16x16x32_bf16 v[118:121], v[206:209], v[162:165], v[118:121]
	v_mfma_f32_16x16x32_bf16 v[114:117], v[218:221], v[162:165], v[114:117]
	v_mfma_f32_16x16x32_bf16 v[102:105], v[206:209], v[170:173], v[102:105]
	v_mfma_f32_16x16x32_bf16 v[98:101], v[218:221], v[170:173], v[98:101]
	v_mfma_f32_16x16x32_bf16 v[86:89], v[206:209], v[186:189], v[86:89]
	v_mfma_f32_16x16x32_bf16 v[82:85], v[218:221], v[186:189], v[82:85]
	v_mfma_f32_16x16x32_bf16 v[70:73], v[206:209], v[198:201], v[70:73]
	v_mfma_f32_16x16x32_bf16 v[66:69], v[218:221], v[198:201], v[66:69]
	s_mov_b32 m0, s24
	v_lshl_add_u64 v[184:185], s[16:17], 0, v[0:1]
	s_barrier
	ds_read_b128 v[158:161], v138 offset:16384
	ds_read_b128 v[162:165], v138 offset:17408
	ds_read_b128 v[166:169], v138 offset:18432
	ds_read_b128 v[170:173], v138 offset:19456
	ds_read_b128 v[174:177], v138 offset:20480
	ds_read_b128 v[186:189], v138 offset:21504
	ds_read_b128 v[190:193], v138 offset:22528
	ds_read_b128 v[198:201], v138 offset:23552
	global_load_lds_dwordx4 v[184:185], off
	v_lshl_add_u64 v[222:223], s[16:17], 0, v[130:131]
	s_mov_b32 m0, s25
	s_nop 0
	global_load_lds_dwordx4 v[222:223], off
	s_barrier
	s_waitcnt lgkmcnt(0)
	s_waitcnt lgkmcnt(0)
	v_mfma_f32_16x16x32_bf16 v[62:65], v[140:143], v[158:161], v[62:65]
	v_mfma_f32_16x16x32_bf16 v[58:61], v[150:153], v[158:161], v[58:61]
	v_mfma_f32_16x16x32_bf16 v[46:49], v[140:143], v[166:169], v[46:49]
	v_mfma_f32_16x16x32_bf16 v[42:45], v[150:153], v[166:169], v[42:45]
	v_mfma_f32_16x16x32_bf16 v[30:33], v[140:143], v[174:177], v[30:33]
	v_mfma_f32_16x16x32_bf16 v[26:29], v[150:153], v[174:177], v[26:29]
	v_mfma_f32_16x16x32_bf16 v[14:17], v[140:143], v[190:193], v[14:17]
	v_mfma_f32_16x16x32_bf16 v[10:13], v[150:153], v[190:193], v[10:13]
	v_mfma_f32_16x16x32_bf16 v[62:65], v[144:147], v[162:165], v[62:65]
	v_mfma_f32_16x16x32_bf16 v[58:61], v[154:157], v[162:165], v[58:61]
	v_mfma_f32_16x16x32_bf16 v[46:49], v[144:147], v[170:173], v[46:49]
	v_mfma_f32_16x16x32_bf16 v[42:45], v[154:157], v[170:173], v[42:45]
	v_mfma_f32_16x16x32_bf16 v[30:33], v[144:147], v[186:189], v[30:33]
	v_mfma_f32_16x16x32_bf16 v[26:29], v[154:157], v[186:189], v[26:29]
	v_mfma_f32_16x16x32_bf16 v[14:17], v[144:147], v[198:201], v[14:17]
	v_mfma_f32_16x16x32_bf16 v[10:13], v[154:157], v[198:201], v[10:13]
	s_barrier
; #define PG8_STAGE(bufoff, gbase, voff) do { _Pragma("unroll") for (int _i = 0; _i < 2; ++_i) \
;     __builtin_amdgcn_global_load_lds((const unsigned*)((const char*)(gbase) + (voff)[_i]), (LAS unsigned*)(lds + (bufoff) + ldsw + _i * 8192), 16, 0, 0); } while (0)
; #define PG8_LDA(dst, b, h) do { _Pragma("unroll") for (int m = 0; m < 4; ++m) _Pragma("unroll") for (int k = 0; k < 2; ++k) dst[m][k] = *(const LAS bf16x8*)(lds + PG8_SA(b, h) + aoff + m * 2048 + k * 1024); } while (0)
; #define PG8_LDB(dst, b, h) do { _Pragma("unroll") for (int n = 0; n < 2; ++n) _Pragma("unroll") for (int k = 0; k < 2; ++k) dst[n][k] = *(const LAS bf16x8*)(lds + PG8_SB(b, h) + boff + n * 2048 + k * 1024); } while (0)
; #define PG8_MMA(ai, bj, At, Bt) do { __builtin_amdgcn_s_setprio(1); _Pragma("unroll") for (int m = 0; m < 4; ++m) _Pragma("unroll") for (int n = 0; n < 2; ++n) _Pragma("unroll") for (int k = 0; k < 2; ++k) \
;     acc[ai][bj][m][n] = __builtin_amdgcn_mfma_f32_16x16x32_bf16(Bt[n][k], At[m][k], acc[ai][bj][m][n], 0, 0, 0); __builtin_amdgcn_s_setprio(0); } while (0)
; #define PG8_WAIT_V(n) asm volatile("s_waitcnt vmcnt(" #n ")" ::: "memory")
; #define PG8_WAIT_L(n) asm volatile("s_waitcnt lgkmcnt(" #n ")" ::: "memory")
; #define PG8_BAR __builtin_amdgcn_s_barrier()
; #define PG8_SCHED __builtin_amdgcn_sched_barrier(0)
; template <class Epi, class Sched>
; DI void gemm_phase(LAS unsigned char* lds, const Gemm g, const Sched& S, const Epi& E) {
;     ...
;       PG8_STAGE(PG8_SB(0, 1), b2 + hstepB, voffB);
;       PG8_WAIT_V(6); PG8_BAR; PG8_MMA(1, 1, At, B1); PG8_BAR;
;       PG8_LDB(B0, 1, 0); PG8_SCHED; PG8_LDA(At, 1, 0); PG8_STAGE(PG8_SA(0, 1), a2 + hstep, voffA);
;       PG8_WAIT_L(8); PG8_BAR; PG8_WAIT_L(0); PG8_MMA(0, 0, At, B0); PG8_BAR; PG8_SCHED;
;       PG8_LDB(B1, 1, 1); PG8_STAGE(PG8_SB(1, 0), b3, voffB);
;       PG8_BAR; PG8_WAIT_L(0); PG8_MMA(0, 1, At, B1); PG8_BAR;
	s_add_u32 s18, s18, s0
	s_addc_u32 s19, s19, s1
	s_add_i32 s37, s38, s23
	v_lshl_add_u64 v[224:225], s[18:19], 0, v[0:1]
	s_mov_b32 m0, s37
	v_lshl_add_u64 v[226:227], s[18:19], 0, v[130:131]
	global_load_lds_dwordx4 v[224:225], off
	s_add_i32 m0, s37, 0x2000
	s_nop 0
	global_load_lds_dwordx4 v[226:227], off
	s_waitcnt vmcnt(10)
	s_barrier
	v_mfma_f32_16x16x32_bf16 v[54:57], v[202:205], v[158:161], v[54:57]
	v_mfma_f32_16x16x32_bf16 v[50:53], v[214:217], v[158:161], v[50:53]
	v_mfma_f32_16x16x32_bf16 v[38:41], v[202:205], v[166:169], v[38:41]
	v_mfma_f32_16x16x32_bf16 v[34:37], v[214:217], v[166:169], v[34:37]
	v_mfma_f32_16x16x32_bf16 v[22:25], v[202:205], v[174:177], v[22:25]
	v_mfma_f32_16x16x32_bf16 v[18:21], v[214:217], v[174:177], v[18:21]
	v_mfma_f32_16x16x32_bf16 v[6:9], v[202:205], v[190:193], v[6:9]
	v_mfma_f32_16x16x32_bf16 v[2:5], v[214:217], v[190:193], v[2:5]
	v_mfma_f32_16x16x32_bf16 v[54:57], v[206:209], v[162:165], v[54:57]
	v_mfma_f32_16x16x32_bf16 v[50:53], v[218:221], v[162:165], v[50:53]
	v_mfma_f32_16x16x32_bf16 v[38:41], v[206:209], v[170:173], v[38:41]
	v_mfma_f32_16x16x32_bf16 v[34:37], v[218:221], v[170:173], v[34:37]
	v_mfma_f32_16x16x32_bf16 v[22:25], v[206:209], v[186:189], v[22:25]
	v_mfma_f32_16x16x32_bf16 v[18:21], v[218:221], v[186:189], v[18:21]
	v_mfma_f32_16x16x32_bf16 v[6:9], v[206:209], v[198:201], v[6:9]
	v_mfma_f32_16x16x32_bf16 v[2:5], v[218:221], v[198:201], v[2:5]
	s_add_i32 s18, 16, 0x18000
	v_add_u32_e32 v139, s18, v137
	s_barrier
	ds_read_b128 v[140:143], v139
	ds_read_b128 v[144:147], v139 offset:1024
	ds_read_b128 v[150:153], v139 offset:2048
	ds_read_b128 v[154:157], v139 offset:3072
	s_add_u32 s16, s16, s0
	s_addc_u32 s17, s17, s1
	s_mov_b32 m0, s26
	v_lshl_add_u64 v[202:203], s[16:17], 0, v[0:1]
	ds_read_b128 v[158:161], v138 offset:32768
	ds_read_b128 v[162:165], v138 offset:33792
	ds_read_b128 v[166:169], v138 offset:34816
	ds_read_b128 v[170:173], v138 offset:35840
	ds_read_b128 v[174:177], v138 offset:36864
	ds_read_b128 v[186:189], v138 offset:37888
	ds_read_b128 v[190:193], v138 offset:38912
	ds_read_b128 v[198:201], v138 offset:39936
	global_load_lds_dwordx4 v[202:203], off
	v_lshl_add_u64 v[202:203], s[16:17], 0, v[130:131]
	s_mov_b32 m0, s27
	s_nop 0
	global_load_lds_dwordx4 v[202:203], off
	s_waitcnt lgkmcnt(8)
	s_waitcnt vmcnt(10)
	s_barrier
	s_waitcnt lgkmcnt(0)
	s_waitcnt lgkmcnt(0)
	v_mfma_f32_16x16x32_bf16 v[126:129], v[140:143], v[158:161], v[126:129]
	v_mfma_f32_16x16x32_bf16 v[122:125], v[150:153], v[158:161], v[122:125]
	v_mfma_f32_16x16x32_bf16 v[110:113], v[140:143], v[166:169], v[110:113]
	v_mfma_f32_16x16x32_bf16 v[106:109], v[150:153], v[166:169], v[106:109]
	v_mfma_f32_16x16x32_bf16 v[94:97], v[140:143], v[174:177], v[94:97]
	v_mfma_f32_16x16x32_bf16 v[90:93], v[150:153], v[174:177], v[90:93]
	v_mfma_f32_16x16x32_bf16 v[78:81], v[140:143], v[190:193], v[78:81]
	v_mfma_f32_16x16x32_bf16 v[74:77], v[150:153], v[190:193], v[74:77]
	v_mfma_f32_16x16x32_bf16 v[126:129], v[144:147], v[162:165], v[126:129]
	v_mfma_f32_16x16x32_bf16 v[122:125], v[154:157], v[162:165], v[122:125]
	v_mfma_f32_16x16x32_bf16 v[110:113], v[144:147], v[170:173], v[110:113]
	v_mfma_f32_16x16x32_bf16 v[106:109], v[154:157], v[170:173], v[106:109]
	v_mfma_f32_16x16x32_bf16 v[94:97], v[144:147], v[186:189], v[94:97]
	v_mfma_f32_16x16x32_bf16 v[90:93], v[154:157], v[186:189], v[90:93]
	v_mfma_f32_16x16x32_bf16 v[78:81], v[144:147], v[198:201], v[78:81]
	v_mfma_f32_16x16x32_bf16 v[74:77], v[154:157], v[198:201], v[74:77]
	s_barrier
	s_add_i32 s16, 16, 0x1c000
	s_add_i32 s17, s18, s23
	v_add_u32_e32 v139, s16, v137
	v_lshl_add_u64 v[180:181], v[180:181], 0, s[70:71]
	s_mov_b32 m0, s17
	ds_read_b128 v[202:205], v139
	ds_read_b128 v[206:209], v139 offset:1024
	ds_read_b128 v[214:217], v139 offset:2048
	ds_read_b128 v[218:221], v139 offset:3072
	global_load_lds_dwordx4 v[180:181], off
	v_lshl_add_u64 v[180:181], v[182:183], 0, s[70:71]
	s_add_i32 m0, s17, 0x2000
	s_nop 0
	global_load_lds_dwordx4 v[180:181], off
	s_waitcnt vmcnt(10)
	s_barrier
; #define PG8_STAGE(bufoff, gbase, voff) do { _Pragma("unroll") for (int _i = 0; _i < 2; ++_i) \
;     __builtin_amdgcn_global_load_lds((const unsigned*)((const char*)(gbase) + (voff)[_i]), (LAS unsigned*)(lds + (bufoff) + ldsw + _i * 8192), 16, 0, 0); } while (0)
; #define PG8_LDA(dst, b, h) do { _Pragma("unroll") for (int m = 0; m < 4; ++m) _Pragma("unroll") for (int k = 0; k < 2; ++k) dst[m][k] = *(const LAS bf16x8*)(lds + PG8_SA(b, h) + aoff + m * 2048 + k * 1024); } while (0)
; #define PG8_MMA(ai, bj, At, Bt) do { __builtin_amdgcn_s_setprio(1); _Pragma("unroll") for (int m = 0; m < 4; ++m) _Pragma("unroll") for (int n = 0; n < 2; ++n) _Pragma("unroll") for (int k = 0; k < 2; ++k) \
;     acc[ai][bj][m][n] = __builtin_amdgcn_mfma_f32_16x16x32_bf16(Bt[n][k], At[m][k], acc[ai][bj][m][n], 0, 0, 0); __builtin_amdgcn_s_setprio(0); } while (0)
; #define PG8_WAIT_V(n) asm volatile("s_waitcnt vmcnt(" #n ")" ::: "memory")
; #define PG8_WAIT_L(n) asm volatile("s_waitcnt lgkmcnt(" #n ")" ::: "memory")
; #define PG8_BAR __builtin_amdgcn_s_barrier()
; #define PG8_SCHED __builtin_amdgcn_sched_barrier(0)
; template <class Epi, class Sched>
; DI void gemm_phase(LAS unsigned char* lds, const Gemm g, const Sched& S, const Epi& E) {
;     ...
;       PG8_LDA(At, 1, 1); PG8_STAGE(PG8_SA(1, 0), a3, voffA);
;       PG8_BAR; PG8_WAIT_L(0); PG8_MMA(1, 0, At, B0); PG8_BAR; PG8_SCHED;
;       PG8_STAGE(PG8_SB(1, 1), b3 + hstepB, voffB);
;       PG8_WAIT_V(6); PG8_BAR; PG8_MMA(1, 1, At, B1); PG8_BAR;
;     }
	s_waitcnt lgkmcnt(0)
	s_waitcnt lgkmcnt(0)
	v_mfma_f32_16x16x32_bf16 v[118:121], v[202:205], v[158:161], v[118:121]
	v_mfma_f32_16x16x32_bf16 v[114:117], v[214:217], v[158:161], v[114:117]
	v_mfma_f32_16x16x32_bf16 v[102:105], v[202:205], v[166:169], v[102:105]
	v_mfma_f32_16x16x32_bf16 v[98:101], v[214:217], v[166:169], v[98:101]
	v_mfma_f32_16x16x32_bf16 v[86:89], v[202:205], v[174:177], v[86:89]
	v_mfma_f32_16x16x32_bf16 v[82:85], v[214:217], v[174:177], v[82:85]
	v_mfma_f32_16x16x32_bf16 v[70:73], v[202:205], v[190:193], v[70:73]
	v_mfma_f32_16x16x32_bf16 v[66:69], v[214:217], v[190:193], v[66:69]
	v_mfma_f32_16x16x32_bf16 v[118:121], v[206:209], v[162:165], v[118:121]
	v_mfma_f32_16x16x32_bf16 v[114:117], v[218:221], v[162:165], v[114:117]
	v_mfma_f32_16x16x32_bf16 v[102:105], v[206:209], v[170:173], v[102:105]
	v_mfma_f32_16x16x32_bf16 v[98:101], v[218:221], v[170:173], v[98:101]
	v_mfma_f32_16x16x32_bf16 v[86:89], v[206:209], v[186:189], v[86:89]
	v_mfma_f32_16x16x32_bf16 v[82:85], v[218:221], v[186:189], v[82:85]
	v_mfma_f32_16x16x32_bf16 v[70:73], v[206:209], v[198:201], v[70:73]
	v_mfma_f32_16x16x32_bf16 v[66:69], v[218:221], v[198:201], v[66:69]
	s_mov_b32 m0, s30
	v_lshl_add_u64 v[180:181], v[184:185], 0, s[70:71]
	s_barrier
	ds_read_b128 v[158:161], v138 offset:49152
	ds_read_b128 v[162:165], v138 offset:50176
	ds_read_b128 v[166:169], v138 offset:51200
	ds_read_b128 v[170:173], v138 offset:52224
	ds_read_b128 v[174:177], v138 offset:53248
	ds_read_b128 v[186:189], v138 offset:54272
	ds_read_b128 v[190:193], v138 offset:55296
	ds_read_b128 v[198:201], v138 offset:56320
	global_load_lds_dwordx4 v[180:181], off
	v_lshl_add_u64 v[180:181], v[222:223], 0, s[70:71]
	s_mov_b32 m0, s31
	s_nop 0
	global_load_lds_dwordx4 v[180:181], off
	s_barrier
	s_waitcnt lgkmcnt(0)
	s_waitcnt lgkmcnt(0)
	v_mfma_f32_16x16x32_bf16 v[62:65], v[140:143], v[158:161], v[62:65]
	v_mfma_f32_16x16x32_bf16 v[58:61], v[150:153], v[158:161], v[58:61]
	v_mfma_f32_16x16x32_bf16 v[46:49], v[140:143], v[166:169], v[46:49]
	v_mfma_f32_16x16x32_bf16 v[42:45], v[150:153], v[166:169], v[42:45]
	v_mfma_f32_16x16x32_bf16 v[30:33], v[140:143], v[174:177], v[30:33]
	v_mfma_f32_16x16x32_bf16 v[26:29], v[150:153], v[174:177], v[26:29]
	v_mfma_f32_16x16x32_bf16 v[14:17], v[140:143], v[190:193], v[14:17]
	v_mfma_f32_16x16x32_bf16 v[10:13], v[150:153], v[190:193], v[10:13]
	v_mfma_f32_16x16x32_bf16 v[62:65], v[144:147], v[162:165], v[62:65]
	v_mfma_f32_16x16x32_bf16 v[58:61], v[154:157], v[162:165], v[58:61]
	v_mfma_f32_16x16x32_bf16 v[46:49], v[144:147], v[170:173], v[46:49]
	v_mfma_f32_16x16x32_bf16 v[42:45], v[154:157], v[170:173], v[42:45]
	v_mfma_f32_16x16x32_bf16 v[30:33], v[144:147], v[186:189], v[30:33]
	v_mfma_f32_16x16x32_bf16 v[26:29], v[154:157], v[186:189], v[26:29]
	v_mfma_f32_16x16x32_bf16 v[14:17], v[144:147], v[198:201], v[14:17]
	v_mfma_f32_16x16x32_bf16 v[10:13], v[154:157], v[198:201], v[10:13]
	s_barrier
	s_add_i32 s16, s16, s23
	v_lshl_add_u64 v[140:141], v[224:225], 0, s[70:71]
	s_mov_b32 m0, s16
	s_nop 0
	global_load_lds_dwordx4 v[140:141], off
	v_lshl_add_u64 v[140:141], v[226:227], 0, s[70:71]
	s_add_i32 m0, s16, 0x2000
	s_nop 0
	global_load_lds_dwordx4 v[140:141], off
	s_waitcnt vmcnt(10)
	s_barrier
	v_mfma_f32_16x16x32_bf16 v[54:57], v[202:205], v[158:161], v[54:57]
	v_mfma_f32_16x16x32_bf16 v[50:53], v[214:217], v[158:161], v[50:53]
	v_mfma_f32_16x16x32_bf16 v[38:41], v[202:205], v[166:169], v[38:41]
	v_mfma_f32_16x16x32_bf16 v[34:37], v[214:217], v[166:169], v[34:37]
	v_mfma_f32_16x16x32_bf16 v[22:25], v[202:205], v[174:177], v[22:25]
	v_mfma_f32_16x16x32_bf16 v[18:21], v[214:217], v[174:177], v[18:21]
	v_mfma_f32_16x16x32_bf16 v[6:9], v[202:205], v[190:193], v[6:9]
	v_mfma_f32_16x16x32_bf16 v[2:5], v[214:217], v[190:193], v[2:5]
	v_mfma_f32_16x16x32_bf16 v[54:57], v[206:209], v[162:165], v[54:57]
	v_mfma_f32_16x16x32_bf16 v[50:53], v[218:221], v[162:165], v[50:53]
	v_mfma_f32_16x16x32_bf16 v[38:41], v[206:209], v[170:173], v[38:41]
	v_mfma_f32_16x16x32_bf16 v[34:37], v[218:221], v[170:173], v[34:37]
	v_mfma_f32_16x16x32_bf16 v[22:25], v[206:209], v[186:189], v[22:25]
	v_mfma_f32_16x16x32_bf16 v[18:21], v[218:221], v[186:189], v[18:21]
	v_mfma_f32_16x16x32_bf16 v[6:9], v[206:209], v[198:201], v[6:9]
	v_mfma_f32_16x16x32_bf16 v[2:5], v[218:221], v[198:201], v[2:5]
	s_add_u32 s14, s14, 0x100
	s_addc_u32 s15, s15, 0
	s_cmp_ge_i32 s36, s34
	s_mov_b32 s16, s36
	s_barrier
	s_cbranch_scc0 .LBB0_153

; #define PG8_STAGE(bufoff, gbase, voff) do { _Pragma("unroll") for (int _i = 0; _i < 2; ++_i) \
;     __builtin_amdgcn_global_load_lds((const unsigned*)((const char*)(gbase) + (voff)[_i]), (LAS unsigned*)(lds + (bufoff) + ldsw + _i * 8192), 16, 0, 0); } while (0)
; #define PG8_LDA(dst, b, h) do { _Pragma("unroll") for (int m = 0; m < 4; ++m) _Pragma("unroll") for (int k = 0; k < 2; ++k) dst[m][k] = *(const LAS bf16x8*)(lds + PG8_SA(b, h) + aoff + m * 2048 + k * 1024); } while (0)
; #define PG8_LDB(dst, b, h) do { _Pragma("unroll") for (int n = 0; n < 2; ++n) _Pragma("unroll") for (int k = 0; k < 2; ++k) dst[n][k] = *(const LAS bf16x8*)(lds + PG8_SB(b, h) + boff + n * 2048 + k * 1024); } while (0)
; #define PG8_MMA(ai, bj, At, Bt) do { __builtin_amdgcn_s_setprio(1); _Pragma("unroll") for (int m = 0; m < 4; ++m) _Pragma("unroll") for (int n = 0; n < 2; ++n) _Pragma("unroll") for (int k = 0; k < 2; ++k) \
;     acc[ai][bj][m][n] = __builtin_amdgcn_mfma_f32_16x16x32_bf16(Bt[n][k], At[m][k], acc[ai][bj][m][n], 0, 0, 0); __builtin_amdgcn_s_setprio(0); } while (0)
; #define PG8_WAIT_L(n) asm volatile("s_waitcnt lgkmcnt(" #n ")" ::: "memory")
; #define PG8_BAR __builtin_amdgcn_s_barrier()
; #define PG8_SCHED __builtin_amdgcn_sched_barrier(0)
; template <class Epi, class Sched>
; DI void gemm_phase(LAS unsigned char* lds, const Gemm g, const Sched& S, const Epi& E) {
;     ...
;     for (int t = 0; t < nt; t += 2) {
;       const bool last = (t == nt - 2);
;       const char* a1 = cA + (size_t)(t + 1) * kstep;
;       const char* a2 = last ? nA : cA + (size_t)(t + 2) * kstep; const char* b2 = last ? nB : cB + (size_t)(t + 2) * kstep;
;       const char* a3 = a2 + kstep; const char* b3 = b2 + kstep;
;       PG8_LDB(B0, 0, 0); PG8_SCHED; PG8_LDA(At, 0, 0); PG8_STAGE(PG8_SA(1, 1), a1 + hstep, voffA);
;       PG8_WAIT_L(8); PG8_BAR; PG8_WAIT_L(0); PG8_MMA(0, 0, At, B0); PG8_BAR; PG8_SCHED;
;       PG8_LDB(B1, 0, 1); PG8_STAGE(PG8_SB(0, 0), b2, voffB);
;       PG8_BAR; PG8_WAIT_L(0); PG8_MMA(0, 1, At, B1); PG8_BAR;
;       PG8_LDA(At, 0, 1); PG8_STAGE(PG8_SA(0, 0), a2, voffA);
;       PG8_BAR; PG8_WAIT_L(0); PG8_MMA(1, 0, At, B0); PG8_BAR; PG8_SCHED;
.LBB0_178:
	s_add_i32 s51, s24, 2
	s_add_u32 s26, s22, 0x80
	s_addc_u32 s25, s23, 0
	s_add_i32 s52, 16, 0x10000
	v_add_u32_e32 v156, s52, v141
	ds_read_b128 v[144:147], v156
	ds_read_b128 v[148:151], v156 offset:1024
	ds_read_b128 v[152:155], v156 offset:2048
	ds_read_b128 v[156:159], v156 offset:3072
	s_cmp_eq_u32 s43, s24
	s_cselect_b32 s24, s18, s26
	s_cselect_b32 s25, s19, s25
	s_cselect_b32 s27, s21, s50
	s_cselect_b32 s26, s20, s49
	v_lshl_add_u64 v[176:177], s[22:23], 0, v[136:137]
	s_add_i32 m0, s36, 0xc000
	ds_read_b128 v[160:163], v143
	ds_read_b128 v[164:167], v143 offset:1024
	ds_read_b128 v[168:171], v143 offset:2048
	ds_read_b128 v[172:175], v143 offset:3072
	ds_read_b128 v[186:189], v143 offset:4096
	ds_read_b128 v[190:193], v143 offset:5120
	ds_read_b128 v[198:201], v143 offset:6144
	ds_read_b128 v[202:205], v143 offset:7168
	global_load_lds_dwordx4 v[176:177], off
	v_lshl_add_u64 v[176:177], s[22:23], 0, v[138:139]
	s_add_i32 m0, s36, 0xe000
	s_nop 0
	global_load_lds_dwordx4 v[176:177], off
	s_waitcnt lgkmcnt(8)
	s_waitcnt vmcnt(10)
	s_barrier
	s_waitcnt lgkmcnt(0)
	s_waitcnt lgkmcnt(0)
	v_mfma_f32_16x16x32_bf16 v[122:125], v[144:147], v[160:163], v[122:125]
	v_mfma_f32_16x16x32_bf16 v[118:121], v[152:155], v[160:163], v[118:121]
	v_mfma_f32_16x16x32_bf16 v[110:113], v[144:147], v[168:171], v[110:113]
	v_mfma_f32_16x16x32_bf16 v[102:105], v[152:155], v[168:171], v[102:105]
	v_mfma_f32_16x16x32_bf16 v[94:97], v[144:147], v[186:189], v[94:97]
	v_mfma_f32_16x16x32_bf16 v[86:89], v[152:155], v[186:189], v[86:89]
	v_mfma_f32_16x16x32_bf16 v[78:81], v[144:147], v[198:201], v[78:81]
	v_mfma_f32_16x16x32_bf16 v[70:73], v[152:155], v[198:201], v[70:73]
	v_mfma_f32_16x16x32_bf16 v[122:125], v[148:151], v[164:167], v[122:125]
	v_mfma_f32_16x16x32_bf16 v[118:121], v[156:159], v[164:167], v[118:121]
	v_mfma_f32_16x16x32_bf16 v[110:113], v[148:151], v[172:175], v[110:113]
	v_mfma_f32_16x16x32_bf16 v[102:105], v[156:159], v[172:175], v[102:105]
	v_mfma_f32_16x16x32_bf16 v[94:97], v[148:151], v[190:193], v[94:97]
	v_mfma_f32_16x16x32_bf16 v[86:89], v[156:159], v[190:193], v[86:89]
	v_mfma_f32_16x16x32_bf16 v[78:81], v[148:151], v[202:205], v[78:81]
	v_mfma_f32_16x16x32_bf16 v[70:73], v[156:159], v[202:205], v[70:73]
	s_barrier
	s_add_i32 s53, 16, 0x14000
	v_add_u32_e32 v176, s53, v141
	s_add_i32 s52, s52, s35
	ds_read_b128 v[206:209], v176
	ds_read_b128 v[214:217], v176 offset:1024
	ds_read_b128 v[218:221], v176 offset:2048
	ds_read_b128 v[222:225], v176 offset:3072
	v_lshl_add_u64 v[176:177], s[26:27], 0, v[0:1]
	s_mov_b32 m0, s52
	v_lshl_add_u64 v[180:181], s[26:27], 0, v[130:131]
	global_load_lds_dwordx4 v[176:177], off
	s_add_i32 m0, s52, 0x2000
	s_nop 0
	global_load_lds_dwordx4 v[180:181], off
	s_waitcnt vmcnt(10)
	s_barrier
	s_waitcnt lgkmcnt(0)
	s_waitcnt lgkmcnt(0)
	v_mfma_f32_16x16x32_bf16 v[126:129], v[206:209], v[160:163], v[126:129]
	v_mfma_f32_16x16x32_bf16 v[114:117], v[218:221], v[160:163], v[114:117]
	v_mfma_f32_16x16x32_bf16 v[106:109], v[206:209], v[168:171], v[106:109]
	v_mfma_f32_16x16x32_bf16 v[98:101], v[218:221], v[168:171], v[98:101]
	v_mfma_f32_16x16x32_bf16 v[90:93], v[206:209], v[186:189], v[90:93]
	v_mfma_f32_16x16x32_bf16 v[82:85], v[218:221], v[186:189], v[82:85]
	v_mfma_f32_16x16x32_bf16 v[74:77], v[206:209], v[198:201], v[74:77]
	v_mfma_f32_16x16x32_bf16 v[66:69], v[218:221], v[198:201], v[66:69]
	v_mfma_f32_16x16x32_bf16 v[126:129], v[214:217], v[164:167], v[126:129]
	v_mfma_f32_16x16x32_bf16 v[114:117], v[222:225], v[164:167], v[114:117]
	v_mfma_f32_16x16x32_bf16 v[106:109], v[214:217], v[172:175], v[106:109]
	v_mfma_f32_16x16x32_bf16 v[98:101], v[222:225], v[172:175], v[98:101]
	v_mfma_f32_16x16x32_bf16 v[90:93], v[214:217], v[190:193], v[90:93]
	v_mfma_f32_16x16x32_bf16 v[82:85], v[222:225], v[190:193], v[82:85]
	v_mfma_f32_16x16x32_bf16 v[74:77], v[214:217], v[202:205], v[74:77]
	v_mfma_f32_16x16x32_bf16 v[66:69], v[222:225], v[202:205], v[66:69]
	s_mov_b32 m0, s36
	v_lshl_add_u64 v[182:183], s[24:25], 0, v[134:135]
	s_barrier
	ds_read_b128 v[160:163], v143 offset:16384
	ds_read_b128 v[164:167], v143 offset:17408
	ds_read_b128 v[168:171], v143 offset:18432
	ds_read_b128 v[172:175], v143 offset:19456
	ds_read_b128 v[186:189], v143 offset:20480
	ds_read_b128 v[190:193], v143 offset:21504
	ds_read_b128 v[198:201], v143 offset:22528
	ds_read_b128 v[202:205], v143 offset:23552
	global_load_lds_dwordx4 v[182:183], off
	v_lshl_add_u64 v[184:185], s[24:25], 0, v[132:133]
	s_mov_b32 m0, s37
	s_nop 0
	global_load_lds_dwordx4 v[184:185], off
	s_barrier
	s_waitcnt lgkmcnt(0)
	s_waitcnt lgkmcnt(0)
	v_mfma_f32_16x16x32_bf16 v[62:65], v[144:147], v[160:163], v[62:65]
	v_mfma_f32_16x16x32_bf16 v[54:57], v[152:155], v[160:163], v[54:57]
	v_mfma_f32_16x16x32_bf16 v[46:49], v[144:147], v[168:171], v[46:49]
	v_mfma_f32_16x16x32_bf16 v[38:41], v[152:155], v[168:171], v[38:41]
	v_mfma_f32_16x16x32_bf16 v[30:33], v[144:147], v[186:189], v[30:33]
	v_mfma_f32_16x16x32_bf16 v[22:25], v[152:155], v[186:189], v[22:25]
	v_mfma_f32_16x16x32_bf16 v[14:17], v[144:147], v[198:201], v[14:17]
	v_mfma_f32_16x16x32_bf16 v[6:9], v[152:155], v[198:201], v[6:9]
	v_mfma_f32_16x16x32_bf16 v[62:65], v[148:151], v[164:167], v[62:65]
	v_mfma_f32_16x16x32_bf16 v[54:57], v[156:159], v[164:167], v[54:57]
	v_mfma_f32_16x16x32_bf16 v[46:49], v[148:151], v[172:175], v[46:49]
	v_mfma_f32_16x16x32_bf16 v[38:41], v[156:159], v[172:175], v[38:41]
	v_mfma_f32_16x16x32_bf16 v[30:33], v[148:151], v[190:193], v[30:33]
	v_mfma_f32_16x16x32_bf16 v[22:25], v[156:159], v[190:193], v[22:25]
	v_mfma_f32_16x16x32_bf16 v[14:17], v[148:151], v[202:205], v[14:17]
	v_mfma_f32_16x16x32_bf16 v[6:9], v[156:159], v[202:205], v[6:9]
	s_barrier
; #define PG8_STAGE(bufoff, gbase, voff) do { _Pragma("unroll") for (int _i = 0; _i < 2; ++_i) \
;     __builtin_amdgcn_global_load_lds((const unsigned*)((const char*)(gbase) + (voff)[_i]), (LAS unsigned*)(lds + (bufoff) + ldsw + _i * 8192), 16, 0, 0); } while (0)
; #define PG8_LDA(dst, b, h) do { _Pragma("unroll") for (int m = 0; m < 4; ++m) _Pragma("unroll") for (int k = 0; k < 2; ++k) dst[m][k] = *(const LAS bf16x8*)(lds + PG8_SA(b, h) + aoff + m * 2048 + k * 1024); } while (0)
; #define PG8_LDB(dst, b, h) do { _Pragma("unroll") for (int n = 0; n < 2; ++n) _Pragma("unroll") for (int k = 0; k < 2; ++k) dst[n][k] = *(const LAS bf16x8*)(lds + PG8_SB(b, h) + boff + n * 2048 + k * 1024); } while (0)
; #define PG8_MMA(ai, bj, At, Bt) do { __builtin_amdgcn_s_setprio(1); _Pragma("unroll") for (int m = 0; m < 4; ++m) _Pragma("unroll") for (int n = 0; n < 2; ++n) _Pragma("unroll") for (int k = 0; k < 2; ++k) \
;     acc[ai][bj][m][n] = __builtin_amdgcn_mfma_f32_16x16x32_bf16(Bt[n][k], At[m][k], acc[ai][bj][m][n], 0, 0, 0); __builtin_amdgcn_s_setprio(0); } while (0)
; #define PG8_WAIT_V(n) asm volatile("s_waitcnt vmcnt(" #n ")" ::: "memory")
; #define PG8_WAIT_L(n) asm volatile("s_waitcnt lgkmcnt(" #n ")" ::: "memory")
; #define PG8_BAR __builtin_amdgcn_s_barrier()
; #define PG8_SCHED __builtin_amdgcn_sched_barrier(0)
; template <class Epi, class Sched>
; DI void gemm_phase(LAS unsigned char* lds, const Gemm g, const Sched& S, const Epi& E) {
;     ...
;       PG8_STAGE(PG8_SB(0, 1), b2 + hstepB, voffB);
;       PG8_WAIT_V(6); PG8_BAR; PG8_MMA(1, 1, At, B1); PG8_BAR;
;       PG8_LDB(B0, 1, 0); PG8_SCHED; PG8_LDA(At, 1, 0); PG8_STAGE(PG8_SA(0, 1), a2 + hstep, voffA);
;       PG8_WAIT_L(8); PG8_BAR; PG8_WAIT_L(0); PG8_MMA(0, 0, At, B0); PG8_BAR; PG8_SCHED;
;       PG8_LDB(B1, 1, 1); PG8_STAGE(PG8_SB(1, 0), b3, voffB);
;       PG8_BAR; PG8_WAIT_L(0); PG8_MMA(0, 1, At, B1); PG8_BAR;
	s_add_u32 s26, s26, s0
	s_addc_u32 s27, s27, s1
	s_add_i32 s52, s53, s35
	v_lshl_add_u64 v[226:227], s[26:27], 0, v[0:1]
	s_mov_b32 m0, s52
	v_lshl_add_u64 v[228:229], s[26:27], 0, v[130:131]
	global_load_lds_dwordx4 v[226:227], off
	s_add_i32 m0, s52, 0x2000
	s_nop 0
	global_load_lds_dwordx4 v[228:229], off
	s_waitcnt vmcnt(10)
	s_barrier
	v_mfma_f32_16x16x32_bf16 v[58:61], v[206:209], v[160:163], v[58:61]
	v_mfma_f32_16x16x32_bf16 v[50:53], v[218:221], v[160:163], v[50:53]
	v_mfma_f32_16x16x32_bf16 v[42:45], v[206:209], v[168:171], v[42:45]
	v_mfma_f32_16x16x32_bf16 v[34:37], v[218:221], v[168:171], v[34:37]
	v_mfma_f32_16x16x32_bf16 v[26:29], v[206:209], v[186:189], v[26:29]
	v_mfma_f32_16x16x32_bf16 v[18:21], v[218:221], v[186:189], v[18:21]
	v_mfma_f32_16x16x32_bf16 v[10:13], v[206:209], v[198:201], v[10:13]
	v_mfma_f32_16x16x32_bf16 v[2:5], v[218:221], v[198:201], v[2:5]
	v_mfma_f32_16x16x32_bf16 v[58:61], v[214:217], v[164:167], v[58:61]
	v_mfma_f32_16x16x32_bf16 v[50:53], v[222:225], v[164:167], v[50:53]
	v_mfma_f32_16x16x32_bf16 v[42:45], v[214:217], v[172:175], v[42:45]
	v_mfma_f32_16x16x32_bf16 v[34:37], v[222:225], v[172:175], v[34:37]
	v_mfma_f32_16x16x32_bf16 v[26:29], v[214:217], v[190:193], v[26:29]
	v_mfma_f32_16x16x32_bf16 v[18:21], v[222:225], v[190:193], v[18:21]
	v_mfma_f32_16x16x32_bf16 v[10:13], v[214:217], v[202:205], v[10:13]
	v_mfma_f32_16x16x32_bf16 v[2:5], v[222:225], v[202:205], v[2:5]
	s_add_i32 s26, 16, 0x18000
	v_add_u32_e32 v156, s26, v141
	s_barrier
	ds_read_b128 v[144:147], v156
	ds_read_b128 v[148:151], v156 offset:1024
	ds_read_b128 v[152:155], v156 offset:2048
	ds_read_b128 v[156:159], v156 offset:3072
	s_add_u32 s24, s24, s0
	s_addc_u32 s25, s25, s1
	s_mov_b32 m0, s38
	v_lshl_add_u64 v[206:207], s[24:25], 0, v[134:135]
	ds_read_b128 v[160:163], v143 offset:32768
	ds_read_b128 v[164:167], v143 offset:33792
	ds_read_b128 v[168:171], v143 offset:34816
	ds_read_b128 v[172:175], v143 offset:35840
	ds_read_b128 v[186:189], v143 offset:36864
	ds_read_b128 v[190:193], v143 offset:37888
	ds_read_b128 v[198:201], v143 offset:38912
	ds_read_b128 v[202:205], v143 offset:39936
	global_load_lds_dwordx4 v[206:207], off
	v_lshl_add_u64 v[206:207], s[24:25], 0, v[132:133]
	s_mov_b32 m0, s39
	s_nop 0
	global_load_lds_dwordx4 v[206:207], off
	s_waitcnt lgkmcnt(8)
	s_waitcnt vmcnt(10)
	s_barrier
	s_waitcnt lgkmcnt(0)
	s_waitcnt lgkmcnt(0)
	v_mfma_f32_16x16x32_bf16 v[122:125], v[144:147], v[160:163], v[122:125]
	v_mfma_f32_16x16x32_bf16 v[118:121], v[152:155], v[160:163], v[118:121]
	v_mfma_f32_16x16x32_bf16 v[110:113], v[144:147], v[168:171], v[110:113]
	v_mfma_f32_16x16x32_bf16 v[102:105], v[152:155], v[168:171], v[102:105]
	v_mfma_f32_16x16x32_bf16 v[94:97], v[144:147], v[186:189], v[94:97]
	v_mfma_f32_16x16x32_bf16 v[86:89], v[152:155], v[186:189], v[86:89]
	v_mfma_f32_16x16x32_bf16 v[78:81], v[144:147], v[198:201], v[78:81]
	v_mfma_f32_16x16x32_bf16 v[70:73], v[152:155], v[198:201], v[70:73]
	v_mfma_f32_16x16x32_bf16 v[122:125], v[148:151], v[164:167], v[122:125]
	v_mfma_f32_16x16x32_bf16 v[118:121], v[156:159], v[164:167], v[118:121]
	v_mfma_f32_16x16x32_bf16 v[110:113], v[148:151], v[172:175], v[110:113]
	v_mfma_f32_16x16x32_bf16 v[102:105], v[156:159], v[172:175], v[102:105]
	v_mfma_f32_16x16x32_bf16 v[94:97], v[148:151], v[190:193], v[94:97]
	v_mfma_f32_16x16x32_bf16 v[86:89], v[156:159], v[190:193], v[86:89]
	v_mfma_f32_16x16x32_bf16 v[78:81], v[148:151], v[202:205], v[78:81]
	v_mfma_f32_16x16x32_bf16 v[70:73], v[156:159], v[202:205], v[70:73]
	s_barrier
	s_add_i32 s24, 16, 0x1c000
	s_add_i32 s25, s26, s35
	v_add_u32_e32 v194, s24, v141
	v_lshl_add_u64 v[176:177], v[176:177], 0, s[70:71]
	s_mov_b32 m0, s25
	ds_read_b128 v[206:209], v194
	ds_read_b128 v[214:217], v194 offset:1024
	ds_read_b128 v[218:221], v194 offset:2048
	ds_read_b128 v[222:225], v194 offset:3072
	global_load_lds_dwordx4 v[176:177], off
	v_lshl_add_u64 v[176:177], v[180:181], 0, s[70:71]
	s_add_i32 m0, s25, 0x2000
	s_nop 0
	global_load_lds_dwordx4 v[176:177], off
	s_waitcnt vmcnt(10)
	s_barrier
; #define PG8_STAGE(bufoff, gbase, voff) do { _Pragma("unroll") for (int _i = 0; _i < 2; ++_i) \
;     __builtin_amdgcn_global_load_lds((const unsigned*)((const char*)(gbase) + (voff)[_i]), (LAS unsigned*)(lds + (bufoff) + ldsw + _i * 8192), 16, 0, 0); } while (0)
; #define PG8_LDA(dst, b, h) do { _Pragma("unroll") for (int m = 0; m < 4; ++m) _Pragma("unroll") for (int k = 0; k < 2; ++k) dst[m][k] = *(const LAS bf16x8*)(lds + PG8_SA(b, h) + aoff + m * 2048 + k * 1024); } while (0)
; #define PG8_MMA(ai, bj, At, Bt) do { __builtin_amdgcn_s_setprio(1); _Pragma("unroll") for (int m = 0; m < 4; ++m) _Pragma("unroll") for (int n = 0; n < 2; ++n) _Pragma("unroll") for (int k = 0; k < 2; ++k) \
;     acc[ai][bj][m][n] = __builtin_amdgcn_mfma_f32_16x16x32_bf16(Bt[n][k], At[m][k], acc[ai][bj][m][n], 0, 0, 0); __builtin_amdgcn_s_setprio(0); } while (0)
; #define PG8_WAIT_V(n) asm volatile("s_waitcnt vmcnt(" #n ")" ::: "memory")
; #define PG8_WAIT_L(n) asm volatile("s_waitcnt lgkmcnt(" #n ")" ::: "memory")
; #define PG8_BAR __builtin_amdgcn_s_barrier()
; #define PG8_SCHED __builtin_amdgcn_sched_barrier(0)
; template <class Epi, class Sched>
; DI void gemm_phase(LAS unsigned char* lds, const Gemm g, const Sched& S, const Epi& E) {
;     ...
;       PG8_LDA(At, 1, 1); PG8_STAGE(PG8_SA(1, 0), a3, voffA);
;       PG8_BAR; PG8_WAIT_L(0); PG8_MMA(1, 0, At, B0); PG8_BAR; PG8_SCHED;
;       PG8_STAGE(PG8_SB(1, 1), b3 + hstepB, voffB);
;       PG8_WAIT_V(6); PG8_BAR; PG8_MMA(1, 1, At, B1); PG8_BAR;
;     }
	s_waitcnt lgkmcnt(0)
	s_waitcnt lgkmcnt(0)
	v_mfma_f32_16x16x32_bf16 v[126:129], v[206:209], v[160:163], v[126:129]
	v_mfma_f32_16x16x32_bf16 v[114:117], v[218:221], v[160:163], v[114:117]
	v_mfma_f32_16x16x32_bf16 v[106:109], v[206:209], v[168:171], v[106:109]
	v_mfma_f32_16x16x32_bf16 v[98:101], v[218:221], v[168:171], v[98:101]
	v_mfma_f32_16x16x32_bf16 v[90:93], v[206:209], v[186:189], v[90:93]
	v_mfma_f32_16x16x32_bf16 v[82:85], v[218:221], v[186:189], v[82:85]
	v_mfma_f32_16x16x32_bf16 v[74:77], v[206:209], v[198:201], v[74:77]
	v_mfma_f32_16x16x32_bf16 v[66:69], v[218:221], v[198:201], v[66:69]
	v_mfma_f32_16x16x32_bf16 v[126:129], v[214:217], v[164:167], v[126:129]
	v_mfma_f32_16x16x32_bf16 v[114:117], v[222:225], v[164:167], v[114:117]
	v_mfma_f32_16x16x32_bf16 v[106:109], v[214:217], v[172:175], v[106:109]
	v_mfma_f32_16x16x32_bf16 v[98:101], v[222:225], v[172:175], v[98:101]
	v_mfma_f32_16x16x32_bf16 v[90:93], v[214:217], v[190:193], v[90:93]
	v_mfma_f32_16x16x32_bf16 v[82:85], v[222:225], v[190:193], v[82:85]
	v_mfma_f32_16x16x32_bf16 v[74:77], v[214:217], v[202:205], v[74:77]
	v_mfma_f32_16x16x32_bf16 v[66:69], v[222:225], v[202:205], v[66:69]
	s_mov_b32 m0, s41
	v_lshl_add_u64 v[176:177], v[182:183], 0, s[70:71]
	s_barrier
	ds_read_b128 v[160:163], v143 offset:49152
	ds_read_b128 v[164:167], v143 offset:50176
	ds_read_b128 v[168:171], v143 offset:51200
	ds_read_b128 v[172:175], v143 offset:52224
	ds_read_b128 v[186:189], v143 offset:53248
	ds_read_b128 v[190:193], v143 offset:54272
	ds_read_b128 v[198:201], v143 offset:55296
	ds_read_b128 v[202:205], v143 offset:56320
	global_load_lds_dwordx4 v[176:177], off
	v_lshl_add_u64 v[176:177], v[184:185], 0, s[70:71]
	s_mov_b32 m0, s42
	s_nop 0
	global_load_lds_dwordx4 v[176:177], off
	s_barrier
	s_waitcnt lgkmcnt(0)
	s_waitcnt lgkmcnt(0)
	v_mfma_f32_16x16x32_bf16 v[62:65], v[144:147], v[160:163], v[62:65]
	v_mfma_f32_16x16x32_bf16 v[54:57], v[152:155], v[160:163], v[54:57]
	v_mfma_f32_16x16x32_bf16 v[46:49], v[144:147], v[168:171], v[46:49]
	v_mfma_f32_16x16x32_bf16 v[38:41], v[152:155], v[168:171], v[38:41]
	v_mfma_f32_16x16x32_bf16 v[30:33], v[144:147], v[186:189], v[30:33]
	v_mfma_f32_16x16x32_bf16 v[22:25], v[152:155], v[186:189], v[22:25]
	v_mfma_f32_16x16x32_bf16 v[14:17], v[144:147], v[198:201], v[14:17]
	v_mfma_f32_16x16x32_bf16 v[6:9], v[152:155], v[198:201], v[6:9]
	v_mfma_f32_16x16x32_bf16 v[62:65], v[148:151], v[164:167], v[62:65]
	v_mfma_f32_16x16x32_bf16 v[54:57], v[156:159], v[164:167], v[54:57]
	v_mfma_f32_16x16x32_bf16 v[46:49], v[148:151], v[172:175], v[46:49]
	v_mfma_f32_16x16x32_bf16 v[38:41], v[156:159], v[172:175], v[38:41]
	v_mfma_f32_16x16x32_bf16 v[30:33], v[148:151], v[190:193], v[30:33]
	v_mfma_f32_16x16x32_bf16 v[22:25], v[156:159], v[190:193], v[22:25]
	v_mfma_f32_16x16x32_bf16 v[14:17], v[148:151], v[202:205], v[14:17]
	v_mfma_f32_16x16x32_bf16 v[6:9], v[156:159], v[202:205], v[6:9]
	s_barrier
	s_add_i32 s24, s24, s35
	v_lshl_add_u64 v[144:145], v[226:227], 0, s[70:71]
	s_mov_b32 m0, s24
	s_nop 0
	global_load_lds_dwordx4 v[144:145], off
	v_lshl_add_u64 v[144:145], v[228:229], 0, s[70:71]
	s_add_i32 m0, s24, 0x2000
	s_nop 0
	global_load_lds_dwordx4 v[144:145], off
	s_waitcnt vmcnt(10)
	s_barrier
	v_mfma_f32_16x16x32_bf16 v[58:61], v[206:209], v[160:163], v[58:61]
	v_mfma_f32_16x16x32_bf16 v[50:53], v[218:221], v[160:163], v[50:53]
	v_mfma_f32_16x16x32_bf16 v[42:45], v[206:209], v[168:171], v[42:45]
	v_mfma_f32_16x16x32_bf16 v[34:37], v[218:221], v[168:171], v[34:37]
	v_mfma_f32_16x16x32_bf16 v[26:29], v[206:209], v[186:189], v[26:29]
	v_mfma_f32_16x16x32_bf16 v[18:21], v[218:221], v[186:189], v[18:21]
	v_mfma_f32_16x16x32_bf16 v[10:13], v[206:209], v[198:201], v[10:13]
	v_mfma_f32_16x16x32_bf16 v[2:5], v[218:221], v[198:201], v[2:5]
	v_mfma_f32_16x16x32_bf16 v[58:61], v[214:217], v[164:167], v[58:61]
	v_mfma_f32_16x16x32_bf16 v[50:53], v[222:225], v[164:167], v[50:53]
	v_mfma_f32_16x16x32_bf16 v[42:45], v[214:217], v[172:175], v[42:45]
	v_mfma_f32_16x16x32_bf16 v[34:37], v[222:225], v[172:175], v[34:37]
	v_mfma_f32_16x16x32_bf16 v[26:29], v[214:217], v[190:193], v[26:29]
	v_mfma_f32_16x16x32_bf16 v[18:21], v[222:225], v[190:193], v[18:21]
	v_mfma_f32_16x16x32_bf16 v[10:13], v[214:217], v[202:205], v[10:13]
	v_mfma_f32_16x16x32_bf16 v[2:5], v[222:225], v[202:205], v[2:5]
	s_add_u32 s22, s22, 0x100
	s_addc_u32 s23, s23, 0
	s_add_u32 s49, s49, 0x100
	s_addc_u32 s50, s50, 0
	s_cmp_ge_i32 s51, s40
	s_mov_b32 s24, s51
	s_barrier
	s_cbranch_scc0 .LBB0_178
	s_branch .LBB0_161

; #define PG8_STAGE(bufoff, gbase, voff) do { _Pragma("unroll") for (int _i = 0; _i < 2; ++_i) \
;     __builtin_amdgcn_global_load_lds((const unsigned*)((const char*)(gbase) + (voff)[_i]), (LAS unsigned*)(lds + (bufoff) + ldsw + _i * 8192), 16, 0, 0); } while (0)
; #define PG8_LDA(dst, b, h) do { _Pragma("unroll") for (int m = 0; m < 4; ++m) _Pragma("unroll") for (int k = 0; k < 2; ++k) dst[m][k] = *(const LAS bf16x8*)(lds + PG8_SA(b, h) + aoff + m * 2048 + k * 1024); } while (0)
; #define PG8_LDB(dst, b, h) do { _Pragma("unroll") for (int n = 0; n < 2; ++n) _Pragma("unroll") for (int k = 0; k < 2; ++k) dst[n][k] = *(const LAS bf16x8*)(lds + PG8_SB(b, h) + boff + n * 2048 + k * 1024); } while (0)
; #define PG8_MMA(ai, bj, At, Bt) do { __builtin_amdgcn_s_setprio(1); _Pragma("unroll") for (int m = 0; m < 4; ++m) _Pragma("unroll") for (int n = 0; n < 2; ++n) _Pragma("unroll") for (int k = 0; k < 2; ++k) \
;     acc[ai][bj][m][n] = __builtin_amdgcn_mfma_f32_16x16x32_bf16(Bt[n][k], At[m][k], acc[ai][bj][m][n], 0, 0, 0); __builtin_amdgcn_s_setprio(0); } while (0)
; #define PG8_WAIT_L(n) asm volatile("s_waitcnt lgkmcnt(" #n ")" ::: "memory")
; #define PG8_BAR __builtin_amdgcn_s_barrier()
; #define PG8_SCHED __builtin_amdgcn_sched_barrier(0)
; template <class Epi, class Sched>
; DI void gemm_phase(LAS unsigned char* lds, const Gemm g, const Sched& S, const Epi& E) {
;     ...
;     for (int t = 0; t < nt; t += 2) {
;       const bool last = (t == nt - 2);
;       const char* a1 = cA + (size_t)(t + 1) * kstep;
;       const char* a2 = last ? nA : cA + (size_t)(t + 2) * kstep; const char* b2 = last ? nB : cB + (size_t)(t + 2) * kstep;
;       const char* a3 = a2 + kstep; const char* b3 = b2 + kstep;
;       PG8_LDB(B0, 0, 0); PG8_SCHED; PG8_LDA(At, 0, 0); PG8_STAGE(PG8_SA(1, 1), a1 + hstep, voffA);
;       PG8_WAIT_L(8); PG8_BAR; PG8_WAIT_L(0); PG8_MMA(0, 0, At, B0); PG8_BAR; PG8_SCHED;
;       PG8_LDB(B1, 0, 1); PG8_STAGE(PG8_SB(0, 0), b2, voffB);
;       PG8_BAR; PG8_WAIT_L(0); PG8_MMA(0, 1, At, B1); PG8_BAR;
;       PG8_LDA(At, 0, 1); PG8_STAGE(PG8_SA(0, 0), a2, voffA);
;       PG8_BAR; PG8_WAIT_L(0); PG8_MMA(1, 0, At, B0); PG8_BAR; PG8_SCHED;
.LBB0_191:
	s_add_i32 s34, s16, 2
	s_add_u32 s17, s14, 0xfe000080
	s_addc_u32 s18, s15, -1
	s_cmp_lg_u32 s31, s16
	s_cselect_b32 s19, s18, 0
	s_cselect_b32 s18, s17, 0
	s_add_u32 s16, s12, s18
	s_addc_u32 s17, s13, s19
	s_add_i32 s35, 16, 0x10000
	v_add_u32_e32 v156, s35, v142
	ds_read_b128 v[144:147], v156
	ds_read_b128 v[148:151], v156 offset:1024
	ds_read_b128 v[152:155], v156 offset:2048
	ds_read_b128 v[156:159], v156 offset:3072
	s_add_u32 s18, s2, s18
	s_addc_u32 s19, s3, s19
	v_lshl_add_u64 v[176:177], v[136:137], 0, s[14:15]
	s_add_i32 m0, s23, 0xc000
	ds_read_b128 v[160:163], v143
	ds_read_b128 v[164:167], v143 offset:1024
	ds_read_b128 v[168:171], v143 offset:2048
	ds_read_b128 v[172:175], v143 offset:3072
	ds_read_b128 v[186:189], v143 offset:4096
	ds_read_b128 v[190:193], v143 offset:5120
	ds_read_b128 v[198:201], v143 offset:6144
	ds_read_b128 v[202:205], v143 offset:7168
	global_load_lds_dwordx4 v[176:177], off
	v_lshl_add_u64 v[176:177], v[138:139], 0, s[14:15]
	s_add_i32 m0, s23, 0xe000
	s_nop 0
	global_load_lds_dwordx4 v[176:177], off
	s_waitcnt lgkmcnt(8)
	s_waitcnt vmcnt(10)
	s_barrier
	s_waitcnt lgkmcnt(0)
	s_waitcnt lgkmcnt(0)
	v_mfma_f32_16x16x32_bf16 v[126:129], v[144:147], v[160:163], v[126:129]
	v_mfma_f32_16x16x32_bf16 v[118:121], v[152:155], v[160:163], v[118:121]
	v_mfma_f32_16x16x32_bf16 v[110:113], v[144:147], v[168:171], v[110:113]
	v_mfma_f32_16x16x32_bf16 v[102:105], v[152:155], v[168:171], v[102:105]
	v_mfma_f32_16x16x32_bf16 v[94:97], v[144:147], v[186:189], v[94:97]
	v_mfma_f32_16x16x32_bf16 v[86:89], v[152:155], v[186:189], v[86:89]
	v_mfma_f32_16x16x32_bf16 v[78:81], v[144:147], v[198:201], v[78:81]
	v_mfma_f32_16x16x32_bf16 v[70:73], v[152:155], v[198:201], v[70:73]
	v_mfma_f32_16x16x32_bf16 v[126:129], v[148:151], v[164:167], v[126:129]
	v_mfma_f32_16x16x32_bf16 v[118:121], v[156:159], v[164:167], v[118:121]
	v_mfma_f32_16x16x32_bf16 v[110:113], v[148:151], v[172:175], v[110:113]
	v_mfma_f32_16x16x32_bf16 v[102:105], v[156:159], v[172:175], v[102:105]
	v_mfma_f32_16x16x32_bf16 v[94:97], v[148:151], v[190:193], v[94:97]
	v_mfma_f32_16x16x32_bf16 v[86:89], v[156:159], v[190:193], v[86:89]
	v_mfma_f32_16x16x32_bf16 v[78:81], v[148:151], v[202:205], v[78:81]
	v_mfma_f32_16x16x32_bf16 v[70:73], v[156:159], v[202:205], v[70:73]
	s_barrier
	s_add_i32 s36, 16, 0x14000
	v_add_u32_e32 v176, s36, v142
	s_add_i32 s35, s35, s22
	ds_read_b128 v[206:209], v176
	ds_read_b128 v[214:217], v176 offset:1024
	ds_read_b128 v[218:221], v176 offset:2048
	ds_read_b128 v[222:225], v176 offset:3072
	v_lshl_add_u64 v[176:177], s[18:19], 0, v[0:1]
	s_mov_b32 m0, s35
	v_lshl_add_u64 v[180:181], s[18:19], 0, v[130:131]
	global_load_lds_dwordx4 v[176:177], off
	s_add_i32 m0, s35, 0x2000
	s_nop 0
	global_load_lds_dwordx4 v[180:181], off
	s_waitcnt vmcnt(10)
	s_barrier
	s_waitcnt lgkmcnt(0)
	s_waitcnt lgkmcnt(0)
	v_mfma_f32_16x16x32_bf16 v[122:125], v[206:209], v[160:163], v[122:125]
	v_mfma_f32_16x16x32_bf16 v[114:117], v[218:221], v[160:163], v[114:117]
	v_mfma_f32_16x16x32_bf16 v[106:109], v[206:209], v[168:171], v[106:109]
	v_mfma_f32_16x16x32_bf16 v[98:101], v[218:221], v[168:171], v[98:101]
	v_mfma_f32_16x16x32_bf16 v[90:93], v[206:209], v[186:189], v[90:93]
	v_mfma_f32_16x16x32_bf16 v[82:85], v[218:221], v[186:189], v[82:85]
	v_mfma_f32_16x16x32_bf16 v[74:77], v[206:209], v[198:201], v[74:77]
	v_mfma_f32_16x16x32_bf16 v[66:69], v[218:221], v[198:201], v[66:69]
	v_mfma_f32_16x16x32_bf16 v[122:125], v[214:217], v[164:167], v[122:125]
	v_mfma_f32_16x16x32_bf16 v[114:117], v[222:225], v[164:167], v[114:117]
	v_mfma_f32_16x16x32_bf16 v[106:109], v[214:217], v[172:175], v[106:109]
	v_mfma_f32_16x16x32_bf16 v[98:101], v[222:225], v[172:175], v[98:101]
	v_mfma_f32_16x16x32_bf16 v[90:93], v[214:217], v[190:193], v[90:93]
	v_mfma_f32_16x16x32_bf16 v[82:85], v[222:225], v[190:193], v[82:85]
	v_mfma_f32_16x16x32_bf16 v[74:77], v[214:217], v[202:205], v[74:77]
	v_mfma_f32_16x16x32_bf16 v[66:69], v[222:225], v[202:205], v[66:69]
	s_mov_b32 m0, s23
	v_lshl_add_u64 v[182:183], s[16:17], 0, v[134:135]
	s_barrier
	ds_read_b128 v[160:163], v143 offset:16384
	ds_read_b128 v[164:167], v143 offset:17408
	ds_read_b128 v[168:171], v143 offset:18432
	ds_read_b128 v[172:175], v143 offset:19456
	ds_read_b128 v[186:189], v143 offset:20480
	ds_read_b128 v[190:193], v143 offset:21504
	ds_read_b128 v[198:201], v143 offset:22528
	ds_read_b128 v[202:205], v143 offset:23552
	global_load_lds_dwordx4 v[182:183], off
	v_lshl_add_u64 v[184:185], s[16:17], 0, v[132:133]
	s_mov_b32 m0, s24
	s_nop 0
	global_load_lds_dwordx4 v[184:185], off
	s_barrier
	s_waitcnt lgkmcnt(0)
	s_waitcnt lgkmcnt(0)
	v_mfma_f32_16x16x32_bf16 v[62:65], v[144:147], v[160:163], v[62:65]
	v_mfma_f32_16x16x32_bf16 v[54:57], v[152:155], v[160:163], v[54:57]
	v_mfma_f32_16x16x32_bf16 v[46:49], v[144:147], v[168:171], v[46:49]
	v_mfma_f32_16x16x32_bf16 v[38:41], v[152:155], v[168:171], v[38:41]
	v_mfma_f32_16x16x32_bf16 v[30:33], v[144:147], v[186:189], v[30:33]
	v_mfma_f32_16x16x32_bf16 v[22:25], v[152:155], v[186:189], v[22:25]
	v_mfma_f32_16x16x32_bf16 v[14:17], v[144:147], v[198:201], v[14:17]
	v_mfma_f32_16x16x32_bf16 v[6:9], v[152:155], v[198:201], v[6:9]
	v_mfma_f32_16x16x32_bf16 v[62:65], v[148:151], v[164:167], v[62:65]
	v_mfma_f32_16x16x32_bf16 v[54:57], v[156:159], v[164:167], v[54:57]
	v_mfma_f32_16x16x32_bf16 v[46:49], v[148:151], v[172:175], v[46:49]
	v_mfma_f32_16x16x32_bf16 v[38:41], v[156:159], v[172:175], v[38:41]
	v_mfma_f32_16x16x32_bf16 v[30:33], v[148:151], v[190:193], v[30:33]
	v_mfma_f32_16x16x32_bf16 v[22:25], v[156:159], v[190:193], v[22:25]
	v_mfma_f32_16x16x32_bf16 v[14:17], v[148:151], v[202:205], v[14:17]
	v_mfma_f32_16x16x32_bf16 v[6:9], v[156:159], v[202:205], v[6:9]
	s_barrier
; #define PG8_STAGE(bufoff, gbase, voff) do { _Pragma("unroll") for (int _i = 0; _i < 2; ++_i) \
;     __builtin_amdgcn_global_load_lds((const unsigned*)((const char*)(gbase) + (voff)[_i]), (LAS unsigned*)(lds + (bufoff) + ldsw + _i * 8192), 16, 0, 0); } while (0)
; #define PG8_LDA(dst, b, h) do { _Pragma("unroll") for (int m = 0; m < 4; ++m) _Pragma("unroll") for (int k = 0; k < 2; ++k) dst[m][k] = *(const LAS bf16x8*)(lds + PG8_SA(b, h) + aoff + m * 2048 + k * 1024); } while (0)
; #define PG8_LDB(dst, b, h) do { _Pragma("unroll") for (int n = 0; n < 2; ++n) _Pragma("unroll") for (int k = 0; k < 2; ++k) dst[n][k] = *(const LAS bf16x8*)(lds + PG8_SB(b, h) + boff + n * 2048 + k * 1024); } while (0)
; #define PG8_MMA(ai, bj, At, Bt) do { __builtin_amdgcn_s_setprio(1); _Pragma("unroll") for (int m = 0; m < 4; ++m) _Pragma("unroll") for (int n = 0; n < 2; ++n) _Pragma("unroll") for (int k = 0; k < 2; ++k) \
;     acc[ai][bj][m][n] = __builtin_amdgcn_mfma_f32_16x16x32_bf16(Bt[n][k], At[m][k], acc[ai][bj][m][n], 0, 0, 0); __builtin_amdgcn_s_setprio(0); } while (0)
; #define PG8_WAIT_V(n) asm volatile("s_waitcnt vmcnt(" #n ")" ::: "memory")
; #define PG8_WAIT_L(n) asm volatile("s_waitcnt lgkmcnt(" #n ")" ::: "memory")
; #define PG8_BAR __builtin_amdgcn_s_barrier()
; #define PG8_SCHED __builtin_amdgcn_sched_barrier(0)
; template <class Epi, class Sched>
; DI void gemm_phase(LAS unsigned char* lds, const Gemm g, const Sched& S, const Epi& E) {
;     ...
;       PG8_STAGE(PG8_SB(0, 1), b2 + hstepB, voffB);
;       PG8_WAIT_V(6); PG8_BAR; PG8_MMA(1, 1, At, B1); PG8_BAR;
;       PG8_LDB(B0, 1, 0); PG8_SCHED; PG8_LDA(At, 1, 0); PG8_STAGE(PG8_SA(0, 1), a2 + hstep, voffA);
;       PG8_WAIT_L(8); PG8_BAR; PG8_WAIT_L(0); PG8_MMA(0, 0, At, B0); PG8_BAR; PG8_SCHED;
;       PG8_LDB(B1, 1, 1); PG8_STAGE(PG8_SB(1, 0), b3, voffB);
;       PG8_BAR; PG8_WAIT_L(0); PG8_MMA(0, 1, At, B1); PG8_BAR;
	s_add_u32 s18, s18, s0
	s_addc_u32 s19, s19, s1
	s_add_i32 s35, s36, s22
	v_lshl_add_u64 v[226:227], s[18:19], 0, v[0:1]
	s_mov_b32 m0, s35
	v_lshl_add_u64 v[228:229], s[18:19], 0, v[130:131]
	global_load_lds_dwordx4 v[226:227], off
	s_add_i32 m0, s35, 0x2000
	s_nop 0
	global_load_lds_dwordx4 v[228:229], off
	s_waitcnt vmcnt(10)
	s_barrier
	v_mfma_f32_16x16x32_bf16 v[58:61], v[206:209], v[160:163], v[58:61]
	v_mfma_f32_16x16x32_bf16 v[50:53], v[218:221], v[160:163], v[50:53]
	v_mfma_f32_16x16x32_bf16 v[42:45], v[206:209], v[168:171], v[42:45]
	v_mfma_f32_16x16x32_bf16 v[34:37], v[218:221], v[168:171], v[34:37]
	v_mfma_f32_16x16x32_bf16 v[26:29], v[206:209], v[186:189], v[26:29]
	v_mfma_f32_16x16x32_bf16 v[18:21], v[218:221], v[186:189], v[18:21]
	v_mfma_f32_16x16x32_bf16 v[10:13], v[206:209], v[198:201], v[10:13]
	v_mfma_f32_16x16x32_bf16 v[2:5], v[218:221], v[198:201], v[2:5]
	v_mfma_f32_16x16x32_bf16 v[58:61], v[214:217], v[164:167], v[58:61]
	v_mfma_f32_16x16x32_bf16 v[50:53], v[222:225], v[164:167], v[50:53]
	v_mfma_f32_16x16x32_bf16 v[42:45], v[214:217], v[172:175], v[42:45]
	v_mfma_f32_16x16x32_bf16 v[34:37], v[222:225], v[172:175], v[34:37]
	v_mfma_f32_16x16x32_bf16 v[26:29], v[214:217], v[190:193], v[26:29]
	v_mfma_f32_16x16x32_bf16 v[18:21], v[222:225], v[190:193], v[18:21]
	v_mfma_f32_16x16x32_bf16 v[10:13], v[214:217], v[202:205], v[10:13]
	v_mfma_f32_16x16x32_bf16 v[2:5], v[222:225], v[202:205], v[2:5]
	s_add_i32 s18, 16, 0x18000
	v_add_u32_e32 v156, s18, v142
	s_barrier
	ds_read_b128 v[144:147], v156
	ds_read_b128 v[148:151], v156 offset:1024
	ds_read_b128 v[152:155], v156 offset:2048
	ds_read_b128 v[156:159], v156 offset:3072
	s_add_u32 s16, s16, s0
	s_addc_u32 s17, s17, s1
	s_mov_b32 m0, s25
	v_lshl_add_u64 v[206:207], s[16:17], 0, v[134:135]
	ds_read_b128 v[160:163], v143 offset:32768
	ds_read_b128 v[164:167], v143 offset:33792
	ds_read_b128 v[168:171], v143 offset:34816
	ds_read_b128 v[172:175], v143 offset:35840
	ds_read_b128 v[186:189], v143 offset:36864
	ds_read_b128 v[190:193], v143 offset:37888
	ds_read_b128 v[198:201], v143 offset:38912
	ds_read_b128 v[202:205], v143 offset:39936
	global_load_lds_dwordx4 v[206:207], off
	v_lshl_add_u64 v[206:207], s[16:17], 0, v[132:133]
	s_mov_b32 m0, s26
	s_nop 0
	global_load_lds_dwordx4 v[206:207], off
	s_waitcnt lgkmcnt(8)
	s_waitcnt vmcnt(10)
	s_barrier
	s_waitcnt lgkmcnt(0)
	s_waitcnt lgkmcnt(0)
	v_mfma_f32_16x16x32_bf16 v[126:129], v[144:147], v[160:163], v[126:129]
	v_mfma_f32_16x16x32_bf16 v[118:121], v[152:155], v[160:163], v[118:121]
	v_mfma_f32_16x16x32_bf16 v[110:113], v[144:147], v[168:171], v[110:113]
	v_mfma_f32_16x16x32_bf16 v[102:105], v[152:155], v[168:171], v[102:105]
	v_mfma_f32_16x16x32_bf16 v[94:97], v[144:147], v[186:189], v[94:97]
	v_mfma_f32_16x16x32_bf16 v[86:89], v[152:155], v[186:189], v[86:89]
	v_mfma_f32_16x16x32_bf16 v[78:81], v[144:147], v[198:201], v[78:81]
	v_mfma_f32_16x16x32_bf16 v[70:73], v[152:155], v[198:201], v[70:73]
	v_mfma_f32_16x16x32_bf16 v[126:129], v[148:151], v[164:167], v[126:129]
	v_mfma_f32_16x16x32_bf16 v[118:121], v[156:159], v[164:167], v[118:121]
	v_mfma_f32_16x16x32_bf16 v[110:113], v[148:151], v[172:175], v[110:113]
	v_mfma_f32_16x16x32_bf16 v[102:105], v[156:159], v[172:175], v[102:105]
	v_mfma_f32_16x16x32_bf16 v[94:97], v[148:151], v[190:193], v[94:97]
	v_mfma_f32_16x16x32_bf16 v[86:89], v[156:159], v[190:193], v[86:89]
	v_mfma_f32_16x16x32_bf16 v[78:81], v[148:151], v[202:205], v[78:81]
	v_mfma_f32_16x16x32_bf16 v[70:73], v[156:159], v[202:205], v[70:73]
	s_barrier
	s_add_i32 s16, 16, 0x1c000
	s_add_i32 s17, s18, s22
	v_add_u32_e32 v194, s16, v142
	v_lshl_add_u64 v[176:177], v[176:177], 0, s[70:71]
	s_mov_b32 m0, s17
	ds_read_b128 v[206:209], v194
	ds_read_b128 v[214:217], v194 offset:1024
	ds_read_b128 v[218:221], v194 offset:2048
	ds_read_b128 v[222:225], v194 offset:3072
	global_load_lds_dwordx4 v[176:177], off
	v_lshl_add_u64 v[176:177], v[180:181], 0, s[70:71]
	s_add_i32 m0, s17, 0x2000
	s_nop 0
	global_load_lds_dwordx4 v[176:177], off
	s_waitcnt vmcnt(10)
	s_barrier
; #define PG8_STAGE(bufoff, gbase, voff) do { _Pragma("unroll") for (int _i = 0; _i < 2; ++_i) \
;     __builtin_amdgcn_global_load_lds((const unsigned*)((const char*)(gbase) + (voff)[_i]), (LAS unsigned*)(lds + (bufoff) + ldsw + _i * 8192), 16, 0, 0); } while (0)
; #define PG8_LDA(dst, b, h) do { _Pragma("unroll") for (int m = 0; m < 4; ++m) _Pragma("unroll") for (int k = 0; k < 2; ++k) dst[m][k] = *(const LAS bf16x8*)(lds + PG8_SA(b, h) + aoff + m * 2048 + k * 1024); } while (0)
; #define PG8_MMA(ai, bj, At, Bt) do { __builtin_amdgcn_s_setprio(1); _Pragma("unroll") for (int m = 0; m < 4; ++m) _Pragma("unroll") for (int n = 0; n < 2; ++n) _Pragma("unroll") for (int k = 0; k < 2; ++k) \
;     acc[ai][bj][m][n] = __builtin_amdgcn_mfma_f32_16x16x32_bf16(Bt[n][k], At[m][k], acc[ai][bj][m][n], 0, 0, 0); __builtin_amdgcn_s_setprio(0); } while (0)
; #define PG8_WAIT_V(n) asm volatile("s_waitcnt vmcnt(" #n ")" ::: "memory")
; #define PG8_WAIT_L(n) asm volatile("s_waitcnt lgkmcnt(" #n ")" ::: "memory")
; #define PG8_BAR __builtin_amdgcn_s_barrier()
; #define PG8_SCHED __builtin_amdgcn_sched_barrier(0)
; template <class Epi, class Sched>
; DI void gemm_phase(LAS unsigned char* lds, const Gemm g, const Sched& S, const Epi& E) {
;     ...
;       PG8_LDA(At, 1, 1); PG8_STAGE(PG8_SA(1, 0), a3, voffA);
;       PG8_BAR; PG8_WAIT_L(0); PG8_MMA(1, 0, At, B0); PG8_BAR; PG8_SCHED;
;       PG8_STAGE(PG8_SB(1, 1), b3 + hstepB, voffB);
;       PG8_WAIT_V(6); PG8_BAR; PG8_MMA(1, 1, At, B1); PG8_BAR;
;     }
	s_waitcnt lgkmcnt(0)
	s_waitcnt lgkmcnt(0)
	v_mfma_f32_16x16x32_bf16 v[122:125], v[206:209], v[160:163], v[122:125]
	v_mfma_f32_16x16x32_bf16 v[114:117], v[218:221], v[160:163], v[114:117]
	v_mfma_f32_16x16x32_bf16 v[106:109], v[206:209], v[168:171], v[106:109]
	v_mfma_f32_16x16x32_bf16 v[98:101], v[218:221], v[168:171], v[98:101]
	v_mfma_f32_16x16x32_bf16 v[90:93], v[206:209], v[186:189], v[90:93]
	v_mfma_f32_16x16x32_bf16 v[82:85], v[218:221], v[186:189], v[82:85]
	v_mfma_f32_16x16x32_bf16 v[74:77], v[206:209], v[198:201], v[74:77]
	v_mfma_f32_16x16x32_bf16 v[66:69], v[218:221], v[198:201], v[66:69]
	v_mfma_f32_16x16x32_bf16 v[122:125], v[214:217], v[164:167], v[122:125]
	v_mfma_f32_16x16x32_bf16 v[114:117], v[222:225], v[164:167], v[114:117]
	v_mfma_f32_16x16x32_bf16 v[106:109], v[214:217], v[172:175], v[106:109]
	v_mfma_f32_16x16x32_bf16 v[98:101], v[222:225], v[172:175], v[98:101]
	v_mfma_f32_16x16x32_bf16 v[90:93], v[214:217], v[190:193], v[90:93]
	v_mfma_f32_16x16x32_bf16 v[82:85], v[222:225], v[190:193], v[82:85]
	v_mfma_f32_16x16x32_bf16 v[74:77], v[214:217], v[202:205], v[74:77]
	v_mfma_f32_16x16x32_bf16 v[66:69], v[222:225], v[202:205], v[66:69]
	s_mov_b32 m0, s27
	v_lshl_add_u64 v[176:177], v[182:183], 0, s[70:71]
	s_barrier
	ds_read_b128 v[160:163], v143 offset:49152
	ds_read_b128 v[164:167], v143 offset:50176
	ds_read_b128 v[168:171], v143 offset:51200
	ds_read_b128 v[172:175], v143 offset:52224
	ds_read_b128 v[186:189], v143 offset:53248
	ds_read_b128 v[190:193], v143 offset:54272
	ds_read_b128 v[198:201], v143 offset:55296
	ds_read_b128 v[202:205], v143 offset:56320
	global_load_lds_dwordx4 v[176:177], off
	v_lshl_add_u64 v[176:177], v[184:185], 0, s[70:71]
	s_mov_b32 m0, s29
	s_nop 0
	global_load_lds_dwordx4 v[176:177], off
	s_barrier
	s_waitcnt lgkmcnt(0)
	s_waitcnt lgkmcnt(0)
	v_mfma_f32_16x16x32_bf16 v[62:65], v[144:147], v[160:163], v[62:65]
	v_mfma_f32_16x16x32_bf16 v[54:57], v[152:155], v[160:163], v[54:57]
	v_mfma_f32_16x16x32_bf16 v[46:49], v[144:147], v[168:171], v[46:49]
	v_mfma_f32_16x16x32_bf16 v[38:41], v[152:155], v[168:171], v[38:41]
	v_mfma_f32_16x16x32_bf16 v[30:33], v[144:147], v[186:189], v[30:33]
	v_mfma_f32_16x16x32_bf16 v[22:25], v[152:155], v[186:189], v[22:25]
	v_mfma_f32_16x16x32_bf16 v[14:17], v[144:147], v[198:201], v[14:17]
	v_mfma_f32_16x16x32_bf16 v[6:9], v[152:155], v[198:201], v[6:9]
	v_mfma_f32_16x16x32_bf16 v[62:65], v[148:151], v[164:167], v[62:65]
	v_mfma_f32_16x16x32_bf16 v[54:57], v[156:159], v[164:167], v[54:57]
	v_mfma_f32_16x16x32_bf16 v[46:49], v[148:151], v[172:175], v[46:49]
	v_mfma_f32_16x16x32_bf16 v[38:41], v[156:159], v[172:175], v[38:41]
	v_mfma_f32_16x16x32_bf16 v[30:33], v[148:151], v[190:193], v[30:33]
	v_mfma_f32_16x16x32_bf16 v[22:25], v[156:159], v[190:193], v[22:25]
	v_mfma_f32_16x16x32_bf16 v[14:17], v[148:151], v[202:205], v[14:17]
	v_mfma_f32_16x16x32_bf16 v[6:9], v[156:159], v[202:205], v[6:9]
	s_barrier
	s_add_i32 s16, s16, s22
	v_lshl_add_u64 v[144:145], v[226:227], 0, s[70:71]
	s_mov_b32 m0, s16
	s_nop 0
	global_load_lds_dwordx4 v[144:145], off
	v_lshl_add_u64 v[144:145], v[228:229], 0, s[70:71]
	s_add_i32 m0, s16, 0x2000
	s_nop 0
	global_load_lds_dwordx4 v[144:145], off
	s_waitcnt vmcnt(10)
	s_barrier
	v_mfma_f32_16x16x32_bf16 v[58:61], v[206:209], v[160:163], v[58:61]
	v_mfma_f32_16x16x32_bf16 v[50:53], v[218:221], v[160:163], v[50:53]
	v_mfma_f32_16x16x32_bf16 v[42:45], v[206:209], v[168:171], v[42:45]
	v_mfma_f32_16x16x32_bf16 v[34:37], v[218:221], v[168:171], v[34:37]
	v_mfma_f32_16x16x32_bf16 v[26:29], v[206:209], v[186:189], v[26:29]
	v_mfma_f32_16x16x32_bf16 v[18:21], v[218:221], v[186:189], v[18:21]
	v_mfma_f32_16x16x32_bf16 v[10:13], v[206:209], v[198:201], v[10:13]
	v_mfma_f32_16x16x32_bf16 v[2:5], v[218:221], v[198:201], v[2:5]
	v_mfma_f32_16x16x32_bf16 v[58:61], v[214:217], v[164:167], v[58:61]
	v_mfma_f32_16x16x32_bf16 v[50:53], v[222:225], v[164:167], v[50:53]
	v_mfma_f32_16x16x32_bf16 v[42:45], v[214:217], v[172:175], v[42:45]
	v_mfma_f32_16x16x32_bf16 v[34:37], v[222:225], v[172:175], v[34:37]
	v_mfma_f32_16x16x32_bf16 v[26:29], v[214:217], v[190:193], v[26:29]
	v_mfma_f32_16x16x32_bf16 v[18:21], v[222:225], v[190:193], v[18:21]
	v_mfma_f32_16x16x32_bf16 v[10:13], v[214:217], v[202:205], v[10:13]
	v_mfma_f32_16x16x32_bf16 v[2:5], v[222:225], v[202:205], v[2:5]
	s_add_u32 s14, s14, 0x100
	s_addc_u32 s15, s15, 0
	s_cmp_ge_i32 s34, s30
	s_mov_b32 s16, s34
	s_barrier
	s_cbranch_scc0 .LBB0_191

; #define PG8_STAGE(bufoff, gbase, voff) do { _Pragma("unroll") for (int _i = 0; _i < 2; ++_i) \
;     __builtin_amdgcn_global_load_lds((const unsigned*)((const char*)(gbase) + (voff)[_i]), (LAS unsigned*)(lds + (bufoff) + ldsw + _i * 8192), 16, 0, 0); } while (0)
; #define PG8_LDA(dst, b, h) do { _Pragma("unroll") for (int m = 0; m < 4; ++m) _Pragma("unroll") for (int k = 0; k < 2; ++k) dst[m][k] = *(const LAS bf16x8*)(lds + PG8_SA(b, h) + aoff + m * 2048 + k * 1024); } while (0)
; #define PG8_LDB(dst, b, h) do { _Pragma("unroll") for (int n = 0; n < 2; ++n) _Pragma("unroll") for (int k = 0; k < 2; ++k) dst[n][k] = *(const LAS bf16x8*)(lds + PG8_SB(b, h) + boff + n * 2048 + k * 1024); } while (0)
; #define PG8_MMA(ai, bj, At, Bt) do { __builtin_amdgcn_s_setprio(1); _Pragma("unroll") for (int m = 0; m < 4; ++m) _Pragma("unroll") for (int n = 0; n < 2; ++n) _Pragma("unroll") for (int k = 0; k < 2; ++k) \
;     acc[ai][bj][m][n] = __builtin_amdgcn_mfma_f32_16x16x32_bf16(Bt[n][k], At[m][k], acc[ai][bj][m][n], 0, 0, 0); __builtin_amdgcn_s_setprio(0); } while (0)
; #define PG8_WAIT_L(n) asm volatile("s_waitcnt lgkmcnt(" #n ")" ::: "memory")
; #define PG8_BAR __builtin_amdgcn_s_barrier()
; #define PG8_SCHED __builtin_amdgcn_sched_barrier(0)
; template <class Epi, class Sched>
; DI void gemm_phase(LAS unsigned char* lds, const Gemm g, const Sched& S, const Epi& E) {
;     ...
;     for (int t = 0; t < nt; t += 2) {
;       const bool last = (t == nt - 2);
;       const char* a1 = cA + (size_t)(t + 1) * kstep;
;       const char* a2 = last ? nA : cA + (size_t)(t + 2) * kstep; const char* b2 = last ? nB : cB + (size_t)(t + 2) * kstep;
;       const char* a3 = a2 + kstep; const char* b3 = b2 + kstep;
;       PG8_LDB(B0, 0, 0); PG8_SCHED; PG8_LDA(At, 0, 0); PG8_STAGE(PG8_SA(1, 1), a1 + hstep, voffA);
;       PG8_WAIT_L(8); PG8_BAR; PG8_WAIT_L(0); PG8_MMA(0, 0, At, B0); PG8_BAR; PG8_SCHED;
;       PG8_LDB(B1, 0, 1); PG8_STAGE(PG8_SB(0, 0), b2, voffB);
;       PG8_BAR; PG8_WAIT_L(0); PG8_MMA(0, 1, At, B1); PG8_BAR;
;       PG8_LDA(At, 0, 1); PG8_STAGE(PG8_SA(0, 0), a2, voffA);
;       PG8_BAR; PG8_WAIT_L(0); PG8_MMA(1, 0, At, B0); PG8_BAR; PG8_SCHED;
.LBB0_217:
	s_add_i32 s40, s3, 2
	s_add_u32 s18, s16, 0x80
	s_addc_u32 s19, s17, 0
	s_cmp_lg_u32 s39, s3
	s_cselect_b32 s20, s18, 0
	s_cselect_b32 s3, s19, 0
	s_add_u32 s18, s14, s20
	s_addc_u32 s19, s15, s3
	s_add_i32 s41, 16, 0x10000
	v_add_u32_e32 v139, s41, v137
	ds_read_b128 v[140:143], v139
	ds_read_b128 v[148:151], v139 offset:1024
	ds_read_b128 v[152:155], v139 offset:2048
	ds_read_b128 v[156:159], v139 offset:3072
	s_add_u32 s20, s12, s20
	s_addc_u32 s21, s13, s3
	v_lshl_add_u64 v[144:145], v[132:133], 0, s[16:17]
	s_add_i32 m0, s30, 0xc000
	ds_read_b128 v[160:163], v138
	ds_read_b128 v[164:167], v138 offset:1024
	ds_read_b128 v[168:171], v138 offset:2048
	ds_read_b128 v[172:175], v138 offset:3072
	ds_read_b128 v[186:189], v138 offset:4096
	ds_read_b128 v[190:193], v138 offset:5120
	ds_read_b128 v[198:201], v138 offset:6144
	ds_read_b128 v[202:205], v138 offset:7168
	global_load_lds_dwordx4 v[144:145], off
	v_lshl_add_u64 v[144:145], v[134:135], 0, s[16:17]
	s_add_i32 m0, s30, 0xe000
	s_nop 0
	global_load_lds_dwordx4 v[144:145], off
	s_waitcnt lgkmcnt(8)
	s_waitcnt vmcnt(10)
	s_barrier
	s_waitcnt lgkmcnt(0)
	s_waitcnt lgkmcnt(0)
	v_mfma_f32_16x16x32_bf16 v[126:129], v[140:143], v[160:163], v[126:129]
	v_mfma_f32_16x16x32_bf16 v[122:125], v[152:155], v[160:163], v[122:125]
	v_mfma_f32_16x16x32_bf16 v[110:113], v[140:143], v[168:171], v[110:113]
	v_mfma_f32_16x16x32_bf16 v[106:109], v[152:155], v[168:171], v[106:109]
	v_mfma_f32_16x16x32_bf16 v[94:97], v[140:143], v[186:189], v[94:97]
	v_mfma_f32_16x16x32_bf16 v[90:93], v[152:155], v[186:189], v[90:93]
	v_mfma_f32_16x16x32_bf16 v[78:81], v[140:143], v[198:201], v[78:81]
	v_mfma_f32_16x16x32_bf16 v[74:77], v[152:155], v[198:201], v[74:77]
	v_mfma_f32_16x16x32_bf16 v[126:129], v[148:151], v[164:167], v[126:129]
	v_mfma_f32_16x16x32_bf16 v[122:125], v[156:159], v[164:167], v[122:125]
	v_mfma_f32_16x16x32_bf16 v[110:113], v[148:151], v[172:175], v[110:113]
	v_mfma_f32_16x16x32_bf16 v[106:109], v[156:159], v[172:175], v[106:109]
	v_mfma_f32_16x16x32_bf16 v[94:97], v[148:151], v[190:193], v[94:97]
	v_mfma_f32_16x16x32_bf16 v[90:93], v[156:159], v[190:193], v[90:93]
	v_mfma_f32_16x16x32_bf16 v[78:81], v[148:151], v[202:205], v[78:81]
	v_mfma_f32_16x16x32_bf16 v[74:77], v[156:159], v[202:205], v[74:77]
	s_barrier
	s_add_i32 s3, 16, 0x14000
	s_add_i32 s41, s41, s29
	v_add_u32_e32 v139, s3, v137
	v_lshl_add_u64 v[144:145], s[20:21], 0, v[0:1]
	s_mov_b32 m0, s41
	ds_read_b128 v[206:209], v139
	ds_read_b128 v[214:217], v139 offset:1024
	ds_read_b128 v[218:221], v139 offset:2048
	ds_read_b128 v[222:225], v139 offset:3072
	global_load_lds_dwordx4 v[144:145], off
	v_lshl_add_u64 v[176:177], s[20:21], 0, v[130:131]
	s_add_i32 m0, s41, 0x2000
	s_nop 0
	global_load_lds_dwordx4 v[176:177], off
	s_waitcnt vmcnt(10)
	s_barrier
	s_waitcnt lgkmcnt(0)
	s_waitcnt lgkmcnt(0)
	v_mfma_f32_16x16x32_bf16 v[118:121], v[206:209], v[160:163], v[118:121]
	v_mfma_f32_16x16x32_bf16 v[114:117], v[218:221], v[160:163], v[114:117]
	v_mfma_f32_16x16x32_bf16 v[102:105], v[206:209], v[168:171], v[102:105]
	v_mfma_f32_16x16x32_bf16 v[98:101], v[218:221], v[168:171], v[98:101]
	v_mfma_f32_16x16x32_bf16 v[86:89], v[206:209], v[186:189], v[86:89]
	v_mfma_f32_16x16x32_bf16 v[82:85], v[218:221], v[186:189], v[82:85]
	v_mfma_f32_16x16x32_bf16 v[70:73], v[206:209], v[198:201], v[70:73]
	v_mfma_f32_16x16x32_bf16 v[66:69], v[218:221], v[198:201], v[66:69]
	v_mfma_f32_16x16x32_bf16 v[118:121], v[214:217], v[164:167], v[118:121]
	v_mfma_f32_16x16x32_bf16 v[114:117], v[222:225], v[164:167], v[114:117]
	v_mfma_f32_16x16x32_bf16 v[102:105], v[214:217], v[172:175], v[102:105]
	v_mfma_f32_16x16x32_bf16 v[98:101], v[222:225], v[172:175], v[98:101]
	v_mfma_f32_16x16x32_bf16 v[86:89], v[214:217], v[190:193], v[86:89]
	v_mfma_f32_16x16x32_bf16 v[82:85], v[222:225], v[190:193], v[82:85]
	v_mfma_f32_16x16x32_bf16 v[70:73], v[214:217], v[202:205], v[70:73]
	v_mfma_f32_16x16x32_bf16 v[66:69], v[222:225], v[202:205], v[66:69]
	s_mov_b32 m0, s30
	v_lshl_add_u64 v[180:181], s[18:19], 0, v[0:1]
	s_barrier
	ds_read_b128 v[160:163], v138 offset:16384
	ds_read_b128 v[164:167], v138 offset:17408
	ds_read_b128 v[168:171], v138 offset:18432
	ds_read_b128 v[172:175], v138 offset:19456
	ds_read_b128 v[186:189], v138 offset:20480
	ds_read_b128 v[190:193], v138 offset:21504
	ds_read_b128 v[198:201], v138 offset:22528
	ds_read_b128 v[202:205], v138 offset:23552
	global_load_lds_dwordx4 v[180:181], off
	v_lshl_add_u64 v[182:183], s[18:19], 0, v[130:131]
	s_mov_b32 m0, s31
	s_nop 0
	global_load_lds_dwordx4 v[182:183], off
	s_barrier
	s_waitcnt lgkmcnt(0)
	s_waitcnt lgkmcnt(0)
	v_mfma_f32_16x16x32_bf16 v[62:65], v[140:143], v[160:163], v[62:65]
	v_mfma_f32_16x16x32_bf16 v[58:61], v[152:155], v[160:163], v[58:61]
	v_mfma_f32_16x16x32_bf16 v[50:53], v[140:143], v[168:171], v[50:53]
	v_mfma_f32_16x16x32_bf16 v[42:45], v[152:155], v[168:171], v[42:45]
	v_mfma_f32_16x16x32_bf16 v[34:37], v[140:143], v[186:189], v[34:37]
	v_mfma_f32_16x16x32_bf16 v[26:29], v[152:155], v[186:189], v[26:29]
	v_mfma_f32_16x16x32_bf16 v[14:17], v[140:143], v[198:201], v[14:17]
	v_mfma_f32_16x16x32_bf16 v[10:13], v[152:155], v[198:201], v[10:13]
	v_mfma_f32_16x16x32_bf16 v[62:65], v[148:151], v[164:167], v[62:65]
	v_mfma_f32_16x16x32_bf16 v[58:61], v[156:159], v[164:167], v[58:61]
	v_mfma_f32_16x16x32_bf16 v[50:53], v[148:151], v[172:175], v[50:53]
	v_mfma_f32_16x16x32_bf16 v[42:45], v[156:159], v[172:175], v[42:45]
	v_mfma_f32_16x16x32_bf16 v[34:37], v[148:151], v[190:193], v[34:37]
	v_mfma_f32_16x16x32_bf16 v[26:29], v[156:159], v[190:193], v[26:29]
	v_mfma_f32_16x16x32_bf16 v[14:17], v[148:151], v[202:205], v[14:17]
	v_mfma_f32_16x16x32_bf16 v[10:13], v[156:159], v[202:205], v[10:13]
	s_barrier
; #define PG8_STAGE(bufoff, gbase, voff) do { _Pragma("unroll") for (int _i = 0; _i < 2; ++_i) \
;     __builtin_amdgcn_global_load_lds((const unsigned*)((const char*)(gbase) + (voff)[_i]), (LAS unsigned*)(lds + (bufoff) + ldsw + _i * 8192), 16, 0, 0); } while (0)
; #define PG8_LDA(dst, b, h) do { _Pragma("unroll") for (int m = 0; m < 4; ++m) _Pragma("unroll") for (int k = 0; k < 2; ++k) dst[m][k] = *(const LAS bf16x8*)(lds + PG8_SA(b, h) + aoff + m * 2048 + k * 1024); } while (0)
; #define PG8_LDB(dst, b, h) do { _Pragma("unroll") for (int n = 0; n < 2; ++n) _Pragma("unroll") for (int k = 0; k < 2; ++k) dst[n][k] = *(const LAS bf16x8*)(lds + PG8_SB(b, h) + boff + n * 2048 + k * 1024); } while (0)
; #define PG8_MMA(ai, bj, At, Bt) do { __builtin_amdgcn_s_setprio(1); _Pragma("unroll") for (int m = 0; m < 4; ++m) _Pragma("unroll") for (int n = 0; n < 2; ++n) _Pragma("unroll") for (int k = 0; k < 2; ++k) \
;     acc[ai][bj][m][n] = __builtin_amdgcn_mfma_f32_16x16x32_bf16(Bt[n][k], At[m][k], acc[ai][bj][m][n], 0, 0, 0); __builtin_amdgcn_s_setprio(0); } while (0)
; #define PG8_WAIT_V(n) asm volatile("s_waitcnt vmcnt(" #n ")" ::: "memory")
; #define PG8_WAIT_L(n) asm volatile("s_waitcnt lgkmcnt(" #n ")" ::: "memory")
; #define PG8_BAR __builtin_amdgcn_s_barrier()
; #define PG8_SCHED __builtin_amdgcn_sched_barrier(0)
; template <class Epi, class Sched>
; DI void gemm_phase(LAS unsigned char* lds, const Gemm g, const Sched& S, const Epi& E) {
;     ...
;       PG8_STAGE(PG8_SB(0, 1), b2 + hstepB, voffB);
;       PG8_WAIT_V(6); PG8_BAR; PG8_MMA(1, 1, At, B1); PG8_BAR;
;       PG8_LDB(B0, 1, 0); PG8_SCHED; PG8_LDA(At, 1, 0); PG8_STAGE(PG8_SA(0, 1), a2 + hstep, voffA);
;       PG8_WAIT_L(8); PG8_BAR; PG8_WAIT_L(0); PG8_MMA(0, 0, At, B0); PG8_BAR; PG8_SCHED;
;       PG8_LDB(B1, 1, 1); PG8_STAGE(PG8_SB(1, 0), b3, voffB);
;       PG8_BAR; PG8_WAIT_L(0); PG8_MMA(0, 1, At, B1); PG8_BAR;
	s_add_u32 s20, s20, s10
	s_addc_u32 s21, s21, s11
	s_add_i32 s3, s3, s29
	v_lshl_add_u64 v[184:185], s[20:21], 0, v[0:1]
	s_mov_b32 m0, s3
	v_lshl_add_u64 v[226:227], s[20:21], 0, v[130:131]
	global_load_lds_dwordx4 v[184:185], off
	s_add_i32 m0, s3, 0x2000
	s_nop 0
	global_load_lds_dwordx4 v[226:227], off
	s_waitcnt vmcnt(10)
	s_barrier
	v_mfma_f32_16x16x32_bf16 v[54:57], v[206:209], v[160:163], v[54:57]
	v_mfma_f32_16x16x32_bf16 v[46:49], v[218:221], v[160:163], v[46:49]
	v_mfma_f32_16x16x32_bf16 v[38:41], v[206:209], v[168:171], v[38:41]
	v_mfma_f32_16x16x32_bf16 v[30:33], v[218:221], v[168:171], v[30:33]
	v_mfma_f32_16x16x32_bf16 v[22:25], v[206:209], v[186:189], v[22:25]
	v_mfma_f32_16x16x32_bf16 v[18:21], v[218:221], v[186:189], v[18:21]
	v_mfma_f32_16x16x32_bf16 v[6:9], v[206:209], v[198:201], v[6:9]
	v_mfma_f32_16x16x32_bf16 v[2:5], v[218:221], v[198:201], v[2:5]
	v_mfma_f32_16x16x32_bf16 v[54:57], v[214:217], v[164:167], v[54:57]
	v_mfma_f32_16x16x32_bf16 v[46:49], v[222:225], v[164:167], v[46:49]
	v_mfma_f32_16x16x32_bf16 v[38:41], v[214:217], v[172:175], v[38:41]
	v_mfma_f32_16x16x32_bf16 v[30:33], v[222:225], v[172:175], v[30:33]
	v_mfma_f32_16x16x32_bf16 v[22:25], v[214:217], v[190:193], v[22:25]
	v_mfma_f32_16x16x32_bf16 v[18:21], v[222:225], v[190:193], v[18:21]
	v_mfma_f32_16x16x32_bf16 v[6:9], v[214:217], v[202:205], v[6:9]
	v_mfma_f32_16x16x32_bf16 v[2:5], v[222:225], v[202:205], v[2:5]
	s_add_i32 s3, 16, 0x18000
	v_add_u32_e32 v139, s3, v137
	s_barrier
	ds_read_b128 v[140:143], v139
	ds_read_b128 v[148:151], v139 offset:1024
	ds_read_b128 v[152:155], v139 offset:2048
	ds_read_b128 v[156:159], v139 offset:3072
	s_add_u32 s18, s18, s10
	s_addc_u32 s19, s19, s11
	s_mov_b32 m0, s34
	v_lshl_add_u64 v[206:207], s[18:19], 0, v[0:1]
	ds_read_b128 v[160:163], v138 offset:32768
	ds_read_b128 v[164:167], v138 offset:33792
	ds_read_b128 v[168:171], v138 offset:34816
	ds_read_b128 v[172:175], v138 offset:35840
	ds_read_b128 v[186:189], v138 offset:36864
	ds_read_b128 v[190:193], v138 offset:37888
	ds_read_b128 v[198:201], v138 offset:38912
	ds_read_b128 v[202:205], v138 offset:39936
	global_load_lds_dwordx4 v[206:207], off
	v_lshl_add_u64 v[206:207], s[18:19], 0, v[130:131]
	s_mov_b32 m0, s35
	s_nop 0
	global_load_lds_dwordx4 v[206:207], off
	s_waitcnt lgkmcnt(8)
	s_waitcnt vmcnt(10)
	s_barrier
	s_waitcnt lgkmcnt(0)
	s_waitcnt lgkmcnt(0)
	v_mfma_f32_16x16x32_bf16 v[126:129], v[140:143], v[160:163], v[126:129]
	v_mfma_f32_16x16x32_bf16 v[122:125], v[152:155], v[160:163], v[122:125]
	v_mfma_f32_16x16x32_bf16 v[110:113], v[140:143], v[168:171], v[110:113]
	v_mfma_f32_16x16x32_bf16 v[106:109], v[152:155], v[168:171], v[106:109]
	v_mfma_f32_16x16x32_bf16 v[94:97], v[140:143], v[186:189], v[94:97]
	v_mfma_f32_16x16x32_bf16 v[90:93], v[152:155], v[186:189], v[90:93]
	v_mfma_f32_16x16x32_bf16 v[78:81], v[140:143], v[198:201], v[78:81]
	v_mfma_f32_16x16x32_bf16 v[74:77], v[152:155], v[198:201], v[74:77]
	v_mfma_f32_16x16x32_bf16 v[126:129], v[148:151], v[164:167], v[126:129]
	v_mfma_f32_16x16x32_bf16 v[122:125], v[156:159], v[164:167], v[122:125]
	v_mfma_f32_16x16x32_bf16 v[110:113], v[148:151], v[172:175], v[110:113]
	v_mfma_f32_16x16x32_bf16 v[106:109], v[156:159], v[172:175], v[106:109]
	v_mfma_f32_16x16x32_bf16 v[94:97], v[148:151], v[190:193], v[94:97]
	v_mfma_f32_16x16x32_bf16 v[90:93], v[156:159], v[190:193], v[90:93]
	v_mfma_f32_16x16x32_bf16 v[78:81], v[148:151], v[202:205], v[78:81]
	v_mfma_f32_16x16x32_bf16 v[74:77], v[156:159], v[202:205], v[74:77]
	s_barrier
	s_add_i32 s18, 16, 0x1c000
	s_add_i32 s3, s3, s29
	v_add_u32_e32 v139, s18, v137
	v_lshl_add_u64 v[144:145], v[144:145], 0, s[70:71]
	s_mov_b32 m0, s3
	ds_read_b128 v[206:209], v139
	ds_read_b128 v[214:217], v139 offset:1024
	ds_read_b128 v[218:221], v139 offset:2048
	ds_read_b128 v[222:225], v139 offset:3072
	global_load_lds_dwordx4 v[144:145], off
	v_lshl_add_u64 v[144:145], v[176:177], 0, s[70:71]
	s_add_i32 m0, s3, 0x2000
	s_nop 0
	global_load_lds_dwordx4 v[144:145], off
	s_waitcnt vmcnt(10)
	s_barrier
; #define PG8_STAGE(bufoff, gbase, voff) do { _Pragma("unroll") for (int _i = 0; _i < 2; ++_i) \
;     __builtin_amdgcn_global_load_lds((const unsigned*)((const char*)(gbase) + (voff)[_i]), (LAS unsigned*)(lds + (bufoff) + ldsw + _i * 8192), 16, 0, 0); } while (0)
; #define PG8_LDA(dst, b, h) do { _Pragma("unroll") for (int m = 0; m < 4; ++m) _Pragma("unroll") for (int k = 0; k < 2; ++k) dst[m][k] = *(const LAS bf16x8*)(lds + PG8_SA(b, h) + aoff + m * 2048 + k * 1024); } while (0)
; #define PG8_MMA(ai, bj, At, Bt) do { __builtin_amdgcn_s_setprio(1); _Pragma("unroll") for (int m = 0; m < 4; ++m) _Pragma("unroll") for (int n = 0; n < 2; ++n) _Pragma("unroll") for (int k = 0; k < 2; ++k) \
;     acc[ai][bj][m][n] = __builtin_amdgcn_mfma_f32_16x16x32_bf16(Bt[n][k], At[m][k], acc[ai][bj][m][n], 0, 0, 0); __builtin_amdgcn_s_setprio(0); } while (0)
; #define PG8_WAIT_V(n) asm volatile("s_waitcnt vmcnt(" #n ")" ::: "memory")
; #define PG8_WAIT_L(n) asm volatile("s_waitcnt lgkmcnt(" #n ")" ::: "memory")
; #define PG8_BAR __builtin_amdgcn_s_barrier()
; #define PG8_SCHED __builtin_amdgcn_sched_barrier(0)
; template <class Epi, class Sched>
; DI void gemm_phase(LAS unsigned char* lds, const Gemm g, const Sched& S, const Epi& E) {
;     ...
;       PG8_LDA(At, 1, 1); PG8_STAGE(PG8_SA(1, 0), a3, voffA);
;       PG8_BAR; PG8_WAIT_L(0); PG8_MMA(1, 0, At, B0); PG8_BAR; PG8_SCHED;
;       PG8_STAGE(PG8_SB(1, 1), b3 + hstepB, voffB);
;       PG8_WAIT_V(6); PG8_BAR; PG8_MMA(1, 1, At, B1); PG8_BAR;
;     }
	s_waitcnt lgkmcnt(0)
	s_waitcnt lgkmcnt(0)
	v_mfma_f32_16x16x32_bf16 v[118:121], v[206:209], v[160:163], v[118:121]
	v_mfma_f32_16x16x32_bf16 v[114:117], v[218:221], v[160:163], v[114:117]
	v_mfma_f32_16x16x32_bf16 v[102:105], v[206:209], v[168:171], v[102:105]
	v_mfma_f32_16x16x32_bf16 v[98:101], v[218:221], v[168:171], v[98:101]
	v_mfma_f32_16x16x32_bf16 v[86:89], v[206:209], v[186:189], v[86:89]
	v_mfma_f32_16x16x32_bf16 v[82:85], v[218:221], v[186:189], v[82:85]
	v_mfma_f32_16x16x32_bf16 v[70:73], v[206:209], v[198:201], v[70:73]
	v_mfma_f32_16x16x32_bf16 v[66:69], v[218:221], v[198:201], v[66:69]
	v_mfma_f32_16x16x32_bf16 v[118:121], v[214:217], v[164:167], v[118:121]
	v_mfma_f32_16x16x32_bf16 v[114:117], v[222:225], v[164:167], v[114:117]
	v_mfma_f32_16x16x32_bf16 v[102:105], v[214:217], v[172:175], v[102:105]
	v_mfma_f32_16x16x32_bf16 v[98:101], v[222:225], v[172:175], v[98:101]
	v_mfma_f32_16x16x32_bf16 v[86:89], v[214:217], v[190:193], v[86:89]
	v_mfma_f32_16x16x32_bf16 v[82:85], v[222:225], v[190:193], v[82:85]
	v_mfma_f32_16x16x32_bf16 v[70:73], v[214:217], v[202:205], v[70:73]
	v_mfma_f32_16x16x32_bf16 v[66:69], v[222:225], v[202:205], v[66:69]
	s_mov_b32 m0, s36
	v_lshl_add_u64 v[144:145], v[180:181], 0, s[70:71]
	s_barrier
	ds_read_b128 v[160:163], v138 offset:49152
	ds_read_b128 v[164:167], v138 offset:50176
	ds_read_b128 v[168:171], v138 offset:51200
	ds_read_b128 v[172:175], v138 offset:52224
	ds_read_b128 v[186:189], v138 offset:53248
	ds_read_b128 v[190:193], v138 offset:54272
	ds_read_b128 v[198:201], v138 offset:55296
	ds_read_b128 v[202:205], v138 offset:56320
	global_load_lds_dwordx4 v[144:145], off
	v_lshl_add_u64 v[144:145], v[182:183], 0, s[70:71]
	s_mov_b32 m0, s37
	s_nop 0
	global_load_lds_dwordx4 v[144:145], off
	s_barrier
	s_waitcnt lgkmcnt(0)
	s_waitcnt lgkmcnt(0)
	v_mfma_f32_16x16x32_bf16 v[62:65], v[140:143], v[160:163], v[62:65]
	v_mfma_f32_16x16x32_bf16 v[58:61], v[152:155], v[160:163], v[58:61]
	v_mfma_f32_16x16x32_bf16 v[50:53], v[140:143], v[168:171], v[50:53]
	v_mfma_f32_16x16x32_bf16 v[42:45], v[152:155], v[168:171], v[42:45]
	v_mfma_f32_16x16x32_bf16 v[34:37], v[140:143], v[186:189], v[34:37]
	v_mfma_f32_16x16x32_bf16 v[26:29], v[152:155], v[186:189], v[26:29]
	v_mfma_f32_16x16x32_bf16 v[14:17], v[140:143], v[198:201], v[14:17]
	v_mfma_f32_16x16x32_bf16 v[10:13], v[152:155], v[198:201], v[10:13]
	v_mfma_f32_16x16x32_bf16 v[62:65], v[148:151], v[164:167], v[62:65]
	v_mfma_f32_16x16x32_bf16 v[58:61], v[156:159], v[164:167], v[58:61]
	v_mfma_f32_16x16x32_bf16 v[50:53], v[148:151], v[172:175], v[50:53]
	v_mfma_f32_16x16x32_bf16 v[42:45], v[156:159], v[172:175], v[42:45]
	v_mfma_f32_16x16x32_bf16 v[34:37], v[148:151], v[190:193], v[34:37]
	v_mfma_f32_16x16x32_bf16 v[26:29], v[156:159], v[190:193], v[26:29]
	v_mfma_f32_16x16x32_bf16 v[14:17], v[148:151], v[202:205], v[14:17]
	v_mfma_f32_16x16x32_bf16 v[10:13], v[156:159], v[202:205], v[10:13]
	s_barrier
	s_add_i32 s3, s18, s29
	v_lshl_add_u64 v[140:141], v[184:185], 0, s[70:71]
	s_mov_b32 m0, s3
	s_nop 0
	global_load_lds_dwordx4 v[140:141], off
	v_lshl_add_u64 v[140:141], v[226:227], 0, s[70:71]
	s_add_i32 m0, s3, 0x2000
	s_nop 0
	global_load_lds_dwordx4 v[140:141], off
	s_waitcnt vmcnt(10)
	s_barrier
	v_mfma_f32_16x16x32_bf16 v[54:57], v[206:209], v[160:163], v[54:57]
	v_mfma_f32_16x16x32_bf16 v[46:49], v[218:221], v[160:163], v[46:49]
	v_mfma_f32_16x16x32_bf16 v[38:41], v[206:209], v[168:171], v[38:41]
	v_mfma_f32_16x16x32_bf16 v[30:33], v[218:221], v[168:171], v[30:33]
	v_mfma_f32_16x16x32_bf16 v[22:25], v[206:209], v[186:189], v[22:25]
	v_mfma_f32_16x16x32_bf16 v[18:21], v[218:221], v[186:189], v[18:21]
	v_mfma_f32_16x16x32_bf16 v[6:9], v[206:209], v[198:201], v[6:9]
	v_mfma_f32_16x16x32_bf16 v[2:5], v[218:221], v[198:201], v[2:5]
	v_mfma_f32_16x16x32_bf16 v[54:57], v[214:217], v[164:167], v[54:57]
	v_mfma_f32_16x16x32_bf16 v[46:49], v[222:225], v[164:167], v[46:49]
	v_mfma_f32_16x16x32_bf16 v[38:41], v[214:217], v[172:175], v[38:41]
	v_mfma_f32_16x16x32_bf16 v[30:33], v[222:225], v[172:175], v[30:33]
	v_mfma_f32_16x16x32_bf16 v[22:25], v[214:217], v[190:193], v[22:25]
	v_mfma_f32_16x16x32_bf16 v[18:21], v[222:225], v[190:193], v[18:21]
	v_mfma_f32_16x16x32_bf16 v[6:9], v[214:217], v[202:205], v[6:9]
	v_mfma_f32_16x16x32_bf16 v[2:5], v[222:225], v[202:205], v[2:5]
	s_add_u32 s16, s16, 0x100
	s_addc_u32 s17, s17, 0
	s_cmp_ge_i32 s40, s38
	s_mov_b32 s3, s40
	s_barrier
	s_cbranch_scc0 .LBB0_217

; #define PG8_STAGE(bufoff, gbase, voff) do { _Pragma("unroll") for (int _i = 0; _i < 2; ++_i) \
;     __builtin_amdgcn_global_load_lds((const unsigned*)((const char*)(gbase) + (voff)[_i]), (LAS unsigned*)(lds + (bufoff) + ldsw + _i * 8192), 16, 0, 0); } while (0)
; #define PG8_LDA(dst, b, h) do { _Pragma("unroll") for (int m = 0; m < 4; ++m) _Pragma("unroll") for (int k = 0; k < 2; ++k) dst[m][k] = *(const LAS bf16x8*)(lds + PG8_SA(b, h) + aoff + m * 2048 + k * 1024); } while (0)
; #define PG8_LDB(dst, b, h) do { _Pragma("unroll") for (int n = 0; n < 2; ++n) _Pragma("unroll") for (int k = 0; k < 2; ++k) dst[n][k] = *(const LAS bf16x8*)(lds + PG8_SB(b, h) + boff + n * 2048 + k * 1024); } while (0)
; #define PG8_MMA(ai, bj, At, Bt) do { __builtin_amdgcn_s_setprio(1); _Pragma("unroll") for (int m = 0; m < 4; ++m) _Pragma("unroll") for (int n = 0; n < 2; ++n) _Pragma("unroll") for (int k = 0; k < 2; ++k) \
;     acc[ai][bj][m][n] = __builtin_amdgcn_mfma_f32_16x16x32_bf16(Bt[n][k], At[m][k], acc[ai][bj][m][n], 0, 0, 0); __builtin_amdgcn_s_setprio(0); } while (0)
; #define PG8_WAIT_L(n) asm volatile("s_waitcnt lgkmcnt(" #n ")" ::: "memory")
; #define PG8_BAR __builtin_amdgcn_s_barrier()
; #define PG8_SCHED __builtin_amdgcn_sched_barrier(0)
; template <class Epi, class Sched>
; DI void gemm_phase(LAS unsigned char* lds, const Gemm g, const Sched& S, const Epi& E) {
;     ...
;     for (int t = 0; t < nt; t += 2) {
;       const bool last = (t == nt - 2);
;       const char* a1 = cA + (size_t)(t + 1) * kstep;
;       const char* a2 = last ? nA : cA + (size_t)(t + 2) * kstep; const char* b2 = last ? nB : cB + (size_t)(t + 2) * kstep;
;       const char* a3 = a2 + kstep; const char* b3 = b2 + kstep;
;       PG8_LDB(B0, 0, 0); PG8_SCHED; PG8_LDA(At, 0, 0); PG8_STAGE(PG8_SA(1, 1), a1 + hstep, voffA);
;       PG8_WAIT_L(8); PG8_BAR; PG8_WAIT_L(0); PG8_MMA(0, 0, At, B0); PG8_BAR; PG8_SCHED;
;       PG8_LDB(B1, 0, 1); PG8_STAGE(PG8_SB(0, 0), b2, voffB);
;       PG8_BAR; PG8_WAIT_L(0); PG8_MMA(0, 1, At, B1); PG8_BAR;
;       PG8_LDA(At, 0, 1); PG8_STAGE(PG8_SA(0, 0), a2, voffA);
;       PG8_BAR; PG8_WAIT_L(0); PG8_MMA(1, 0, At, B0); PG8_BAR; PG8_SCHED;
.LBB0_491:
	s_add_i32 s26, s8, 2
	s_add_u32 s9, s6, 0xfe000080
	s_addc_u32 s10, s7, -1
	s_cmp_lg_u32 s25, s8
	s_cselect_b32 s11, s10, 0
	s_cselect_b32 s10, s9, 0
	s_add_u32 s8, s4, s10
	s_addc_u32 s9, s5, s11
	s_add_i32 s27, 16, 0x10000
	v_add_u32_e32 v139, s27, v133
	ds_read_b128 v[140:143], v139
	ds_read_b128 v[148:151], v139 offset:1024
	ds_read_b128 v[152:155], v139 offset:2048
	ds_read_b128 v[156:159], v139 offset:3072
	s_add_u32 s10, s2, s10
	s_addc_u32 s11, s3, s11
	v_lshl_add_u64 v[144:145], v[128:129], 0, s[6:7]
	s_add_i32 m0, s18, 0xc000
	ds_read_b128 v[160:163], v138
	ds_read_b128 v[164:167], v138 offset:1024
	ds_read_b128 v[168:171], v138 offset:2048
	ds_read_b128 v[172:175], v138 offset:3072
	ds_read_b128 v[186:189], v138 offset:4096
	ds_read_b128 v[190:193], v138 offset:5120
	ds_read_b128 v[198:201], v138 offset:6144
	ds_read_b128 v[202:205], v138 offset:7168
	global_load_lds_dwordx4 v[144:145], off
	v_lshl_add_u64 v[144:145], v[130:131], 0, s[6:7]
	s_add_i32 m0, s18, 0xe000
	s_nop 0
	global_load_lds_dwordx4 v[144:145], off
	s_waitcnt lgkmcnt(8)
	s_waitcnt vmcnt(10)
	s_barrier
	s_waitcnt lgkmcnt(0)
	s_waitcnt lgkmcnt(0)
	v_mfma_f32_16x16x32_bf16 v[134:137], v[140:143], v[160:163], v[134:137]
	v_mfma_f32_16x16x32_bf16 v[122:125], v[152:155], v[160:163], v[122:125]
	v_mfma_f32_16x16x32_bf16 v[110:113], v[140:143], v[168:171], v[110:113]
	v_mfma_f32_16x16x32_bf16 v[106:109], v[152:155], v[168:171], v[106:109]
	v_mfma_f32_16x16x32_bf16 v[94:97], v[140:143], v[186:189], v[94:97]
	v_mfma_f32_16x16x32_bf16 v[90:93], v[152:155], v[186:189], v[90:93]
	v_mfma_f32_16x16x32_bf16 v[78:81], v[140:143], v[198:201], v[78:81]
	v_mfma_f32_16x16x32_bf16 v[74:77], v[152:155], v[198:201], v[74:77]
	v_mfma_f32_16x16x32_bf16 v[134:137], v[148:151], v[164:167], v[134:137]
	v_mfma_f32_16x16x32_bf16 v[122:125], v[156:159], v[164:167], v[122:125]
	v_mfma_f32_16x16x32_bf16 v[110:113], v[148:151], v[172:175], v[110:113]
	v_mfma_f32_16x16x32_bf16 v[106:109], v[156:159], v[172:175], v[106:109]
	v_mfma_f32_16x16x32_bf16 v[94:97], v[148:151], v[190:193], v[94:97]
	v_mfma_f32_16x16x32_bf16 v[90:93], v[156:159], v[190:193], v[90:93]
	v_mfma_f32_16x16x32_bf16 v[78:81], v[148:151], v[202:205], v[78:81]
	v_mfma_f32_16x16x32_bf16 v[74:77], v[156:159], v[202:205], v[74:77]
	s_barrier
	s_add_i32 s28, 16, 0x14000
	s_add_i32 s27, s27, s17
	v_add_u32_e32 v139, s28, v133
	v_lshl_add_u64 v[144:145], s[10:11], 0, v[0:1]
	s_mov_b32 m0, s27
	ds_read_b128 v[206:209], v139
	ds_read_b128 v[214:217], v139 offset:1024
	ds_read_b128 v[218:221], v139 offset:2048
	ds_read_b128 v[222:225], v139 offset:3072
	global_load_lds_dwordx4 v[144:145], off
	v_lshl_add_u64 v[176:177], s[10:11], 0, v[126:127]
	s_add_i32 m0, s27, 0x2000
	s_nop 0
	global_load_lds_dwordx4 v[176:177], off
	s_waitcnt vmcnt(10)
	s_barrier
	s_waitcnt lgkmcnt(0)
	s_waitcnt lgkmcnt(0)
	v_mfma_f32_16x16x32_bf16 v[118:121], v[206:209], v[160:163], v[118:121]
	v_mfma_f32_16x16x32_bf16 v[114:117], v[218:221], v[160:163], v[114:117]
	v_mfma_f32_16x16x32_bf16 v[102:105], v[206:209], v[168:171], v[102:105]
	v_mfma_f32_16x16x32_bf16 v[98:101], v[218:221], v[168:171], v[98:101]
	v_mfma_f32_16x16x32_bf16 v[86:89], v[206:209], v[186:189], v[86:89]
	v_mfma_f32_16x16x32_bf16 v[82:85], v[218:221], v[186:189], v[82:85]
	v_mfma_f32_16x16x32_bf16 v[70:73], v[206:209], v[198:201], v[70:73]
	v_mfma_f32_16x16x32_bf16 v[66:69], v[218:221], v[198:201], v[66:69]
	v_mfma_f32_16x16x32_bf16 v[118:121], v[214:217], v[164:167], v[118:121]
	v_mfma_f32_16x16x32_bf16 v[114:117], v[222:225], v[164:167], v[114:117]
	v_mfma_f32_16x16x32_bf16 v[102:105], v[214:217], v[172:175], v[102:105]
	v_mfma_f32_16x16x32_bf16 v[98:101], v[222:225], v[172:175], v[98:101]
	v_mfma_f32_16x16x32_bf16 v[86:89], v[214:217], v[190:193], v[86:89]
	v_mfma_f32_16x16x32_bf16 v[82:85], v[222:225], v[190:193], v[82:85]
	v_mfma_f32_16x16x32_bf16 v[70:73], v[214:217], v[202:205], v[70:73]
	v_mfma_f32_16x16x32_bf16 v[66:69], v[222:225], v[202:205], v[66:69]
	s_mov_b32 m0, s18
	v_lshl_add_u64 v[180:181], s[8:9], 0, v[0:1]
	s_barrier
	ds_read_b128 v[160:163], v138 offset:16384
	ds_read_b128 v[164:167], v138 offset:17408
	ds_read_b128 v[168:171], v138 offset:18432
	ds_read_b128 v[172:175], v138 offset:19456
	ds_read_b128 v[186:189], v138 offset:20480
	ds_read_b128 v[190:193], v138 offset:21504
	ds_read_b128 v[198:201], v138 offset:22528
	ds_read_b128 v[202:205], v138 offset:23552
	global_load_lds_dwordx4 v[180:181], off
	v_lshl_add_u64 v[182:183], s[8:9], 0, v[126:127]
	s_mov_b32 m0, s19
	s_nop 0
	global_load_lds_dwordx4 v[182:183], off
	s_barrier
	s_waitcnt lgkmcnt(0)
	s_waitcnt lgkmcnt(0)
	v_mfma_f32_16x16x32_bf16 v[62:65], v[140:143], v[160:163], v[62:65]
	v_mfma_f32_16x16x32_bf16 v[58:61], v[152:155], v[160:163], v[58:61]
	v_mfma_f32_16x16x32_bf16 v[50:53], v[140:143], v[168:171], v[50:53]
	v_mfma_f32_16x16x32_bf16 v[42:45], v[152:155], v[168:171], v[42:45]
	v_mfma_f32_16x16x32_bf16 v[34:37], v[140:143], v[186:189], v[34:37]
	v_mfma_f32_16x16x32_bf16 v[26:29], v[152:155], v[186:189], v[26:29]
	v_mfma_f32_16x16x32_bf16 v[18:21], v[140:143], v[198:201], v[18:21]
	v_mfma_f32_16x16x32_bf16 v[10:13], v[152:155], v[198:201], v[10:13]
	v_mfma_f32_16x16x32_bf16 v[62:65], v[148:151], v[164:167], v[62:65]
	v_mfma_f32_16x16x32_bf16 v[58:61], v[156:159], v[164:167], v[58:61]
	v_mfma_f32_16x16x32_bf16 v[50:53], v[148:151], v[172:175], v[50:53]
	v_mfma_f32_16x16x32_bf16 v[42:45], v[156:159], v[172:175], v[42:45]
	v_mfma_f32_16x16x32_bf16 v[34:37], v[148:151], v[190:193], v[34:37]
	v_mfma_f32_16x16x32_bf16 v[26:29], v[156:159], v[190:193], v[26:29]
	v_mfma_f32_16x16x32_bf16 v[18:21], v[148:151], v[202:205], v[18:21]
	v_mfma_f32_16x16x32_bf16 v[10:13], v[156:159], v[202:205], v[10:13]
	s_barrier
; #define PG8_STAGE(bufoff, gbase, voff) do { _Pragma("unroll") for (int _i = 0; _i < 2; ++_i) \
;     __builtin_amdgcn_global_load_lds((const unsigned*)((const char*)(gbase) + (voff)[_i]), (LAS unsigned*)(lds + (bufoff) + ldsw + _i * 8192), 16, 0, 0); } while (0)
; #define PG8_LDA(dst, b, h) do { _Pragma("unroll") for (int m = 0; m < 4; ++m) _Pragma("unroll") for (int k = 0; k < 2; ++k) dst[m][k] = *(const LAS bf16x8*)(lds + PG8_SA(b, h) + aoff + m * 2048 + k * 1024); } while (0)
; #define PG8_LDB(dst, b, h) do { _Pragma("unroll") for (int n = 0; n < 2; ++n) _Pragma("unroll") for (int k = 0; k < 2; ++k) dst[n][k] = *(const LAS bf16x8*)(lds + PG8_SB(b, h) + boff + n * 2048 + k * 1024); } while (0)
; #define PG8_MMA(ai, bj, At, Bt) do { __builtin_amdgcn_s_setprio(1); _Pragma("unroll") for (int m = 0; m < 4; ++m) _Pragma("unroll") for (int n = 0; n < 2; ++n) _Pragma("unroll") for (int k = 0; k < 2; ++k) \
;     acc[ai][bj][m][n] = __builtin_amdgcn_mfma_f32_16x16x32_bf16(Bt[n][k], At[m][k], acc[ai][bj][m][n], 0, 0, 0); __builtin_amdgcn_s_setprio(0); } while (0)
; #define PG8_WAIT_V(n) asm volatile("s_waitcnt vmcnt(" #n ")" ::: "memory")
; #define PG8_WAIT_L(n) asm volatile("s_waitcnt lgkmcnt(" #n ")" ::: "memory")
; #define PG8_BAR __builtin_amdgcn_s_barrier()
; #define PG8_SCHED __builtin_amdgcn_sched_barrier(0)
; template <class Epi, class Sched>
; DI void gemm_phase(LAS unsigned char* lds, const Gemm g, const Sched& S, const Epi& E) {
;     ...
;       PG8_STAGE(PG8_SB(0, 1), b2 + hstepB, voffB);
;       PG8_WAIT_V(6); PG8_BAR; PG8_MMA(1, 1, At, B1); PG8_BAR;
;       PG8_LDB(B0, 1, 0); PG8_SCHED; PG8_LDA(At, 1, 0); PG8_STAGE(PG8_SA(0, 1), a2 + hstep, voffA);
;       PG8_WAIT_L(8); PG8_BAR; PG8_WAIT_L(0); PG8_MMA(0, 0, At, B0); PG8_BAR; PG8_SCHED;
;       PG8_LDB(B1, 1, 1); PG8_STAGE(PG8_SB(1, 0), b3, voffB);
;       PG8_BAR; PG8_WAIT_L(0); PG8_MMA(0, 1, At, B1); PG8_BAR;
	s_add_u32 s10, s10, s0
	s_addc_u32 s11, s11, s1
	s_add_i32 s27, s28, s17
	v_lshl_add_u64 v[184:185], s[10:11], 0, v[0:1]
	s_mov_b32 m0, s27
	v_lshl_add_u64 v[226:227], s[10:11], 0, v[126:127]
	global_load_lds_dwordx4 v[184:185], off
	s_add_i32 m0, s27, 0x2000
	s_nop 0
	global_load_lds_dwordx4 v[226:227], off
	s_waitcnt vmcnt(10)
	s_barrier
	v_mfma_f32_16x16x32_bf16 v[54:57], v[206:209], v[160:163], v[54:57]
	v_mfma_f32_16x16x32_bf16 v[46:49], v[218:221], v[160:163], v[46:49]
	v_mfma_f32_16x16x32_bf16 v[38:41], v[206:209], v[168:171], v[38:41]
	v_mfma_f32_16x16x32_bf16 v[30:33], v[218:221], v[168:171], v[30:33]
	v_mfma_f32_16x16x32_bf16 v[22:25], v[206:209], v[186:189], v[22:25]
	v_mfma_f32_16x16x32_bf16 v[14:17], v[218:221], v[186:189], v[14:17]
	v_mfma_f32_16x16x32_bf16 v[6:9], v[206:209], v[198:201], v[6:9]
	v_mfma_f32_16x16x32_bf16 v[2:5], v[218:221], v[198:201], v[2:5]
	v_mfma_f32_16x16x32_bf16 v[54:57], v[214:217], v[164:167], v[54:57]
	v_mfma_f32_16x16x32_bf16 v[46:49], v[222:225], v[164:167], v[46:49]
	v_mfma_f32_16x16x32_bf16 v[38:41], v[214:217], v[172:175], v[38:41]
	v_mfma_f32_16x16x32_bf16 v[30:33], v[222:225], v[172:175], v[30:33]
	v_mfma_f32_16x16x32_bf16 v[22:25], v[214:217], v[190:193], v[22:25]
	v_mfma_f32_16x16x32_bf16 v[14:17], v[222:225], v[190:193], v[14:17]
	v_mfma_f32_16x16x32_bf16 v[6:9], v[214:217], v[202:205], v[6:9]
	v_mfma_f32_16x16x32_bf16 v[2:5], v[222:225], v[202:205], v[2:5]
	s_add_i32 s10, 16, 0x18000
	v_add_u32_e32 v139, s10, v133
	s_barrier
	ds_read_b128 v[140:143], v139
	ds_read_b128 v[148:151], v139 offset:1024
	ds_read_b128 v[152:155], v139 offset:2048
	ds_read_b128 v[156:159], v139 offset:3072
	s_add_u32 s8, s8, s0
	s_addc_u32 s9, s9, s1
	s_mov_b32 m0, s20
	v_lshl_add_u64 v[206:207], s[8:9], 0, v[0:1]
	ds_read_b128 v[160:163], v138 offset:32768
	ds_read_b128 v[164:167], v138 offset:33792
	ds_read_b128 v[168:171], v138 offset:34816
	ds_read_b128 v[172:175], v138 offset:35840
	ds_read_b128 v[186:189], v138 offset:36864
	ds_read_b128 v[190:193], v138 offset:37888
	ds_read_b128 v[198:201], v138 offset:38912
	ds_read_b128 v[202:205], v138 offset:39936
	global_load_lds_dwordx4 v[206:207], off
	v_lshl_add_u64 v[206:207], s[8:9], 0, v[126:127]
	s_mov_b32 m0, s21
	s_nop 0
	global_load_lds_dwordx4 v[206:207], off
	s_waitcnt lgkmcnt(8)
	s_waitcnt vmcnt(10)
	s_barrier
	s_waitcnt lgkmcnt(0)
	s_waitcnt lgkmcnt(0)
	v_mfma_f32_16x16x32_bf16 v[134:137], v[140:143], v[160:163], v[134:137]
	v_mfma_f32_16x16x32_bf16 v[122:125], v[152:155], v[160:163], v[122:125]
	v_mfma_f32_16x16x32_bf16 v[110:113], v[140:143], v[168:171], v[110:113]
	v_mfma_f32_16x16x32_bf16 v[106:109], v[152:155], v[168:171], v[106:109]
	v_mfma_f32_16x16x32_bf16 v[94:97], v[140:143], v[186:189], v[94:97]
	v_mfma_f32_16x16x32_bf16 v[90:93], v[152:155], v[186:189], v[90:93]
	v_mfma_f32_16x16x32_bf16 v[78:81], v[140:143], v[198:201], v[78:81]
	v_mfma_f32_16x16x32_bf16 v[74:77], v[152:155], v[198:201], v[74:77]
	v_mfma_f32_16x16x32_bf16 v[134:137], v[148:151], v[164:167], v[134:137]
	v_mfma_f32_16x16x32_bf16 v[122:125], v[156:159], v[164:167], v[122:125]
	v_mfma_f32_16x16x32_bf16 v[110:113], v[148:151], v[172:175], v[110:113]
	v_mfma_f32_16x16x32_bf16 v[106:109], v[156:159], v[172:175], v[106:109]
	v_mfma_f32_16x16x32_bf16 v[94:97], v[148:151], v[190:193], v[94:97]
	v_mfma_f32_16x16x32_bf16 v[90:93], v[156:159], v[190:193], v[90:93]
	v_mfma_f32_16x16x32_bf16 v[78:81], v[148:151], v[202:205], v[78:81]
	v_mfma_f32_16x16x32_bf16 v[74:77], v[156:159], v[202:205], v[74:77]
	s_barrier
	s_add_i32 s8, 16, 0x1c000
	s_add_i32 s9, s10, s17
	v_add_u32_e32 v139, s8, v133
	v_lshl_add_u64 v[144:145], v[144:145], 0, s[70:71]
	s_mov_b32 m0, s9
	ds_read_b128 v[206:209], v139
	ds_read_b128 v[214:217], v139 offset:1024
	ds_read_b128 v[218:221], v139 offset:2048
	ds_read_b128 v[222:225], v139 offset:3072
	global_load_lds_dwordx4 v[144:145], off
	v_lshl_add_u64 v[144:145], v[176:177], 0, s[70:71]
	s_add_i32 m0, s9, 0x2000
	s_nop 0
	global_load_lds_dwordx4 v[144:145], off
	s_waitcnt vmcnt(10)
	s_barrier
; #define PG8_STAGE(bufoff, gbase, voff) do { _Pragma("unroll") for (int _i = 0; _i < 2; ++_i) \
;     __builtin_amdgcn_global_load_lds((const unsigned*)((const char*)(gbase) + (voff)[_i]), (LAS unsigned*)(lds + (bufoff) + ldsw + _i * 8192), 16, 0, 0); } while (0)
; #define PG8_LDA(dst, b, h) do { _Pragma("unroll") for (int m = 0; m < 4; ++m) _Pragma("unroll") for (int k = 0; k < 2; ++k) dst[m][k] = *(const LAS bf16x8*)(lds + PG8_SA(b, h) + aoff + m * 2048 + k * 1024); } while (0)
; #define PG8_MMA(ai, bj, At, Bt) do { __builtin_amdgcn_s_setprio(1); _Pragma("unroll") for (int m = 0; m < 4; ++m) _Pragma("unroll") for (int n = 0; n < 2; ++n) _Pragma("unroll") for (int k = 0; k < 2; ++k) \
;     acc[ai][bj][m][n] = __builtin_amdgcn_mfma_f32_16x16x32_bf16(Bt[n][k], At[m][k], acc[ai][bj][m][n], 0, 0, 0); __builtin_amdgcn_s_setprio(0); } while (0)
; #define PG8_WAIT_V(n) asm volatile("s_waitcnt vmcnt(" #n ")" ::: "memory")
; #define PG8_WAIT_L(n) asm volatile("s_waitcnt lgkmcnt(" #n ")" ::: "memory")
; #define PG8_BAR __builtin_amdgcn_s_barrier()
; #define PG8_SCHED __builtin_amdgcn_sched_barrier(0)
; template <class Epi, class Sched>
; DI void gemm_phase(LAS unsigned char* lds, const Gemm g, const Sched& S, const Epi& E) {
;     ...
;       PG8_LDA(At, 1, 1); PG8_STAGE(PG8_SA(1, 0), a3, voffA);
;       PG8_BAR; PG8_WAIT_L(0); PG8_MMA(1, 0, At, B0); PG8_BAR; PG8_SCHED;
;       PG8_STAGE(PG8_SB(1, 1), b3 + hstepB, voffB);
;       PG8_WAIT_V(6); PG8_BAR; PG8_MMA(1, 1, At, B1); PG8_BAR;
;     }
	s_waitcnt lgkmcnt(0)
	s_waitcnt lgkmcnt(0)
	v_mfma_f32_16x16x32_bf16 v[118:121], v[206:209], v[160:163], v[118:121]
	v_mfma_f32_16x16x32_bf16 v[114:117], v[218:221], v[160:163], v[114:117]
	v_mfma_f32_16x16x32_bf16 v[102:105], v[206:209], v[168:171], v[102:105]
	v_mfma_f32_16x16x32_bf16 v[98:101], v[218:221], v[168:171], v[98:101]
	v_mfma_f32_16x16x32_bf16 v[86:89], v[206:209], v[186:189], v[86:89]
	v_mfma_f32_16x16x32_bf16 v[82:85], v[218:221], v[186:189], v[82:85]
	v_mfma_f32_16x16x32_bf16 v[70:73], v[206:209], v[198:201], v[70:73]
	v_mfma_f32_16x16x32_bf16 v[66:69], v[218:221], v[198:201], v[66:69]
	v_mfma_f32_16x16x32_bf16 v[118:121], v[214:217], v[164:167], v[118:121]
	v_mfma_f32_16x16x32_bf16 v[114:117], v[222:225], v[164:167], v[114:117]
	v_mfma_f32_16x16x32_bf16 v[102:105], v[214:217], v[172:175], v[102:105]
	v_mfma_f32_16x16x32_bf16 v[98:101], v[222:225], v[172:175], v[98:101]
	v_mfma_f32_16x16x32_bf16 v[86:89], v[214:217], v[190:193], v[86:89]
	v_mfma_f32_16x16x32_bf16 v[82:85], v[222:225], v[190:193], v[82:85]
	v_mfma_f32_16x16x32_bf16 v[70:73], v[214:217], v[202:205], v[70:73]
	v_mfma_f32_16x16x32_bf16 v[66:69], v[222:225], v[202:205], v[66:69]
	s_mov_b32 m0, s22
	v_lshl_add_u64 v[144:145], v[180:181], 0, s[70:71]
	s_barrier
	ds_read_b128 v[160:163], v138 offset:49152
	ds_read_b128 v[164:167], v138 offset:50176
	ds_read_b128 v[168:171], v138 offset:51200
	ds_read_b128 v[172:175], v138 offset:52224
	ds_read_b128 v[186:189], v138 offset:53248
	ds_read_b128 v[190:193], v138 offset:54272
	ds_read_b128 v[198:201], v138 offset:55296
	ds_read_b128 v[202:205], v138 offset:56320
	global_load_lds_dwordx4 v[144:145], off
	v_lshl_add_u64 v[144:145], v[182:183], 0, s[70:71]
	s_mov_b32 m0, s23
	s_nop 0
	global_load_lds_dwordx4 v[144:145], off
	s_barrier
	s_waitcnt lgkmcnt(0)
	s_waitcnt lgkmcnt(0)
	v_mfma_f32_16x16x32_bf16 v[62:65], v[140:143], v[160:163], v[62:65]
	v_mfma_f32_16x16x32_bf16 v[58:61], v[152:155], v[160:163], v[58:61]
	v_mfma_f32_16x16x32_bf16 v[50:53], v[140:143], v[168:171], v[50:53]
	v_mfma_f32_16x16x32_bf16 v[42:45], v[152:155], v[168:171], v[42:45]
	v_mfma_f32_16x16x32_bf16 v[34:37], v[140:143], v[186:189], v[34:37]
	v_mfma_f32_16x16x32_bf16 v[26:29], v[152:155], v[186:189], v[26:29]
	v_mfma_f32_16x16x32_bf16 v[18:21], v[140:143], v[198:201], v[18:21]
	v_mfma_f32_16x16x32_bf16 v[10:13], v[152:155], v[198:201], v[10:13]
	v_mfma_f32_16x16x32_bf16 v[62:65], v[148:151], v[164:167], v[62:65]
	v_mfma_f32_16x16x32_bf16 v[58:61], v[156:159], v[164:167], v[58:61]
	v_mfma_f32_16x16x32_bf16 v[50:53], v[148:151], v[172:175], v[50:53]
	v_mfma_f32_16x16x32_bf16 v[42:45], v[156:159], v[172:175], v[42:45]
	v_mfma_f32_16x16x32_bf16 v[34:37], v[148:151], v[190:193], v[34:37]
	v_mfma_f32_16x16x32_bf16 v[26:29], v[156:159], v[190:193], v[26:29]
	v_mfma_f32_16x16x32_bf16 v[18:21], v[148:151], v[202:205], v[18:21]
	v_mfma_f32_16x16x32_bf16 v[10:13], v[156:159], v[202:205], v[10:13]
	s_barrier
	s_add_i32 s8, s8, s17
	v_lshl_add_u64 v[140:141], v[184:185], 0, s[70:71]
	s_mov_b32 m0, s8
	s_nop 0
	global_load_lds_dwordx4 v[140:141], off
	v_lshl_add_u64 v[140:141], v[226:227], 0, s[70:71]
	s_add_i32 m0, s8, 0x2000
	s_nop 0
	global_load_lds_dwordx4 v[140:141], off
	s_waitcnt vmcnt(10)
	s_barrier
	v_mfma_f32_16x16x32_bf16 v[54:57], v[206:209], v[160:163], v[54:57]
	v_mfma_f32_16x16x32_bf16 v[46:49], v[218:221], v[160:163], v[46:49]
	v_mfma_f32_16x16x32_bf16 v[38:41], v[206:209], v[168:171], v[38:41]
	v_mfma_f32_16x16x32_bf16 v[30:33], v[218:221], v[168:171], v[30:33]
	v_mfma_f32_16x16x32_bf16 v[22:25], v[206:209], v[186:189], v[22:25]
	v_mfma_f32_16x16x32_bf16 v[14:17], v[218:221], v[186:189], v[14:17]
	v_mfma_f32_16x16x32_bf16 v[6:9], v[206:209], v[198:201], v[6:9]
	v_mfma_f32_16x16x32_bf16 v[2:5], v[218:221], v[198:201], v[2:5]
	v_mfma_f32_16x16x32_bf16 v[54:57], v[214:217], v[164:167], v[54:57]
	v_mfma_f32_16x16x32_bf16 v[46:49], v[222:225], v[164:167], v[46:49]
	v_mfma_f32_16x16x32_bf16 v[38:41], v[214:217], v[172:175], v[38:41]
	v_mfma_f32_16x16x32_bf16 v[30:33], v[222:225], v[172:175], v[30:33]
	v_mfma_f32_16x16x32_bf16 v[22:25], v[214:217], v[190:193], v[22:25]
	v_mfma_f32_16x16x32_bf16 v[14:17], v[222:225], v[190:193], v[14:17]
	v_mfma_f32_16x16x32_bf16 v[6:9], v[214:217], v[202:205], v[6:9]
	v_mfma_f32_16x16x32_bf16 v[2:5], v[222:225], v[202:205], v[2:5]
	s_add_u32 s6, s6, 0x100
	s_addc_u32 s7, s7, 0
	s_cmp_ge_i32 s26, s24
	s_mov_b32 s8, s26
	s_barrier
	s_cbranch_scc0 .LBB0_491
	s_movk_i32 s27, 0xffd0
	s_movk_i32 s28, 0x2200

; #define PG8_STAGE(bufoff, gbase, voff) do { _Pragma("unroll") for (int _i = 0; _i < 2; ++_i) \
;     __builtin_amdgcn_global_load_lds((const unsigned*)((const char*)(gbase) + (voff)[_i]), (LAS unsigned*)(lds + (bufoff) + ldsw + _i * 8192), 16, 0, 0); } while (0)
; #define PG8_LDA(dst, b, h) do { _Pragma("unroll") for (int m = 0; m < 4; ++m) _Pragma("unroll") for (int k = 0; k < 2; ++k) dst[m][k] = *(const LAS bf16x8*)(lds + PG8_SA(b, h) + aoff + m * 2048 + k * 1024); } while (0)
; #define PG8_LDB(dst, b, h) do { _Pragma("unroll") for (int n = 0; n < 2; ++n) _Pragma("unroll") for (int k = 0; k < 2; ++k) dst[n][k] = *(const LAS bf16x8*)(lds + PG8_SB(b, h) + boff + n * 2048 + k * 1024); } while (0)
; #define PG8_MMA(ai, bj, At, Bt) do { __builtin_amdgcn_s_setprio(1); _Pragma("unroll") for (int m = 0; m < 4; ++m) _Pragma("unroll") for (int n = 0; n < 2; ++n) _Pragma("unroll") for (int k = 0; k < 2; ++k) \
;     acc[ai][bj][m][n] = __builtin_amdgcn_mfma_f32_16x16x32_bf16(Bt[n][k], At[m][k], acc[ai][bj][m][n], 0, 0, 0); __builtin_amdgcn_s_setprio(0); } while (0)
; #define PG8_WAIT_L(n) asm volatile("s_waitcnt lgkmcnt(" #n ")" ::: "memory")
; #define PG8_BAR __builtin_amdgcn_s_barrier()
; #define PG8_SCHED __builtin_amdgcn_sched_barrier(0)
; template <class Epi, class Sched>
; DI void gemm_phase(LAS unsigned char* lds, const Gemm g, const Sched& S, const Epi& E) {
;     ...
;     for (int t = 0; t < nt; t += 2) {
;       const bool last = (t == nt - 2);
;       const char* a1 = cA + (size_t)(t + 1) * kstep;
;       const char* a2 = last ? nA : cA + (size_t)(t + 2) * kstep; const char* b2 = last ? nB : cB + (size_t)(t + 2) * kstep;
;       const char* a3 = a2 + kstep; const char* b3 = b2 + kstep;
;       PG8_LDB(B0, 0, 0); PG8_SCHED; PG8_LDA(At, 0, 0); PG8_STAGE(PG8_SA(1, 1), a1 + hstep, voffA);
;       PG8_WAIT_L(8); PG8_BAR; PG8_WAIT_L(0); PG8_MMA(0, 0, At, B0); PG8_BAR; PG8_SCHED;
;       PG8_LDB(B1, 0, 1); PG8_STAGE(PG8_SB(0, 0), b2, voffB);
;       PG8_BAR; PG8_WAIT_L(0); PG8_MMA(0, 1, At, B1); PG8_BAR;
;       PG8_LDA(At, 0, 1); PG8_STAGE(PG8_SA(0, 0), a2, voffA);
;       PG8_BAR; PG8_WAIT_L(0); PG8_MMA(1, 0, At, B0); PG8_BAR; PG8_SCHED;
.LBB0_519:
	s_add_i32 s23, s6, 2
	s_add_u32 s8, s2, 0x80
	s_addc_u32 s7, s3, 0
	s_add_i32 s24, 16, 0x10000
	v_add_u32_e32 v0, s24, v215
	ds_read_b128 v[66:69], v0
	ds_read_b128 v[70:73], v0 offset:1024
	ds_read_b128 v[74:77], v0 offset:2048
	ds_read_b128 v[78:81], v0 offset:3072
	s_cmp_eq_u32 s41, s6
	s_cselect_b32 s6, s0, s8
	s_cselect_b32 s7, s1, s7
	s_cselect_b32 s9, s21, s22
	s_cselect_b32 s8, s20, s11
	v_lshl_add_u64 v[206:207], s[2:3], 0, v[202:203]
	s_add_i32 m0, s30, 0xc000
	ds_read_b128 v[82:85], v216
	ds_read_b128 v[86:89], v216 offset:1024
	ds_read_b128 v[94:97], v216 offset:2048
	ds_read_b128 v[98:101], v216 offset:3072
	ds_read_b128 v[114:117], v216 offset:4096
	ds_read_b128 v[118:121], v216 offset:5120
	ds_read_b128 v[122:125], v216 offset:6144
	ds_read_b128 v[126:129], v216 offset:7168
	global_load_lds_dwordx4 v[206:207], off
	v_lshl_add_u64 v[206:207], s[2:3], 0, v[204:205]
	s_add_i32 m0, s30, 0xe000
	s_nop 0
	global_load_lds_dwordx4 v[206:207], off
	s_waitcnt lgkmcnt(8)
	s_waitcnt vmcnt(10)
	s_barrier
	s_waitcnt lgkmcnt(0)
	s_waitcnt lgkmcnt(0)
	v_mfma_f32_16x16x32_bf16 v[174:177], v[66:69], v[82:85], v[174:177]
	v_mfma_f32_16x16x32_bf16 v[170:173], v[74:77], v[82:85], v[170:173]
	v_mfma_f32_16x16x32_bf16 v[158:161], v[66:69], v[94:97], v[158:161]
	v_mfma_f32_16x16x32_bf16 v[154:157], v[74:77], v[94:97], v[154:157]
	v_mfma_f32_16x16x32_bf16 v[142:145], v[66:69], v[114:117], v[142:145]
	v_mfma_f32_16x16x32_bf16 v[138:141], v[74:77], v[114:117], v[138:141]
	v_mfma_f32_16x16x32_bf16 v[110:113], v[66:69], v[122:125], v[110:113]
	v_mfma_f32_16x16x32_bf16 v[106:109], v[74:77], v[122:125], v[106:109]
	v_mfma_f32_16x16x32_bf16 v[174:177], v[70:73], v[86:89], v[174:177]
	v_mfma_f32_16x16x32_bf16 v[170:173], v[78:81], v[86:89], v[170:173]
	v_mfma_f32_16x16x32_bf16 v[158:161], v[70:73], v[98:101], v[158:161]
	v_mfma_f32_16x16x32_bf16 v[154:157], v[78:81], v[98:101], v[154:157]
	v_mfma_f32_16x16x32_bf16 v[142:145], v[70:73], v[118:121], v[142:145]
	v_mfma_f32_16x16x32_bf16 v[138:141], v[78:81], v[118:121], v[138:141]
	v_mfma_f32_16x16x32_bf16 v[110:113], v[70:73], v[126:129], v[110:113]
	v_mfma_f32_16x16x32_bf16 v[106:109], v[78:81], v[126:129], v[106:109]
	s_barrier
	s_add_i32 s25, 16, 0x14000
	s_add_i32 s24, s24, s29
	v_add_u32_e32 v0, s25, v215
	v_lshl_add_u64 v[246:247], s[8:9], 0, v[190:191]
	s_mov_b32 m0, s24
	ds_read_b128 v[206:209], v0
	ds_read_b128 v[218:221], v0 offset:1024
	ds_read_b128 v[222:225], v0 offset:2048
	ds_read_b128 v[226:229], v0 offset:3072
	global_load_lds_dwordx4 v[246:247], off
	v_lshl_add_u64 v[248:249], s[8:9], 0, v[186:187]
	s_add_i32 m0, s24, 0x2000
	s_nop 0
	global_load_lds_dwordx4 v[248:249], off
	s_waitcnt vmcnt(10)
	s_barrier
	s_waitcnt lgkmcnt(0)
	s_waitcnt lgkmcnt(0)
	v_mfma_f32_16x16x32_bf16 v[166:169], v[206:209], v[82:85], v[166:169]
	v_mfma_f32_16x16x32_bf16 v[82:85], v[222:225], v[82:85], v[162:165]
	v_mfma_f32_16x16x32_bf16 v[166:169], v[218:221], v[86:89], v[166:169]
	v_mfma_f32_16x16x32_bf16 v[82:85], v[226:229], v[86:89], v[82:85]
	v_mfma_f32_16x16x32_bf16 v[86:89], v[206:209], v[94:97], v[150:153]
	v_mfma_f32_16x16x32_bf16 v[94:97], v[222:225], v[94:97], v[146:149]
	v_mfma_f32_16x16x32_bf16 v[102:105], v[206:209], v[122:125], v[102:105]
	v_mfma_f32_16x16x32_bf16 v[90:93], v[222:225], v[122:125], v[90:93]
	v_mfma_f32_16x16x32_bf16 v[86:89], v[218:221], v[98:101], v[86:89]
	v_mfma_f32_16x16x32_bf16 v[94:97], v[226:229], v[98:101], v[94:97]
	v_mfma_f32_16x16x32_bf16 v[98:101], v[206:209], v[114:117], v[134:137]
	v_mfma_f32_16x16x32_bf16 v[114:117], v[222:225], v[114:117], v[130:133]
	v_mfma_f32_16x16x32_bf16 v[102:105], v[218:221], v[126:129], v[102:105]
	v_mfma_f32_16x16x32_bf16 v[90:93], v[226:229], v[126:129], v[90:93]
	v_mfma_f32_16x16x32_bf16 v[98:101], v[218:221], v[118:121], v[98:101]
	v_mfma_f32_16x16x32_bf16 v[114:117], v[226:229], v[118:121], v[114:117]
	s_mov_b32 m0, s30
	v_lshl_add_u64 v[250:251], s[6:7], 0, v[192:193]
	s_barrier
	ds_read_b128 v[118:121], v216 offset:16384
	ds_read_b128 v[122:125], v216 offset:17408
	ds_read_b128 v[126:129], v216 offset:18432
	ds_read_b128 v[130:133], v216 offset:19456
	ds_read_b128 v[134:137], v216 offset:20480
	ds_read_b128 v[146:149], v216 offset:21504
	ds_read_b128 v[150:153], v216 offset:22528
	ds_read_b128 v[162:165], v216 offset:23552
	global_load_lds_dwordx4 v[250:251], off
	v_lshl_add_u64 v[180:181], s[6:7], 0, v[188:189]
	s_mov_b32 m0, s31
	s_nop 0
	global_load_lds_dwordx4 v[180:181], off
	s_barrier
	s_waitcnt lgkmcnt(0)
	s_waitcnt lgkmcnt(0)
	v_mfma_f32_16x16x32_bf16 v[62:65], v[66:69], v[118:121], v[62:65]
	v_mfma_f32_16x16x32_bf16 v[58:61], v[74:77], v[118:121], v[58:61]
	v_mfma_f32_16x16x32_bf16 v[46:49], v[66:69], v[126:129], v[46:49]
	v_mfma_f32_16x16x32_bf16 v[42:45], v[74:77], v[126:129], v[42:45]
	v_mfma_f32_16x16x32_bf16 v[30:33], v[66:69], v[134:137], v[30:33]
	v_mfma_f32_16x16x32_bf16 v[26:29], v[74:77], v[134:137], v[26:29]
	v_mfma_f32_16x16x32_bf16 v[14:17], v[66:69], v[150:153], v[14:17]
	v_mfma_f32_16x16x32_bf16 v[10:13], v[74:77], v[150:153], v[10:13]
	v_mfma_f32_16x16x32_bf16 v[62:65], v[70:73], v[122:125], v[62:65]
	v_mfma_f32_16x16x32_bf16 v[58:61], v[78:81], v[122:125], v[58:61]
	v_mfma_f32_16x16x32_bf16 v[46:49], v[70:73], v[130:133], v[46:49]
	v_mfma_f32_16x16x32_bf16 v[42:45], v[78:81], v[130:133], v[42:45]
	v_mfma_f32_16x16x32_bf16 v[30:33], v[70:73], v[146:149], v[30:33]
	v_mfma_f32_16x16x32_bf16 v[26:29], v[78:81], v[146:149], v[26:29]
	v_mfma_f32_16x16x32_bf16 v[14:17], v[70:73], v[162:165], v[14:17]
	v_mfma_f32_16x16x32_bf16 v[10:13], v[78:81], v[162:165], v[10:13]
	s_barrier
; #define PG8_STAGE(bufoff, gbase, voff) do { _Pragma("unroll") for (int _i = 0; _i < 2; ++_i) \
;     __builtin_amdgcn_global_load_lds((const unsigned*)((const char*)(gbase) + (voff)[_i]), (LAS unsigned*)(lds + (bufoff) + ldsw + _i * 8192), 16, 0, 0); } while (0)
; #define PG8_LDA(dst, b, h) do { _Pragma("unroll") for (int m = 0; m < 4; ++m) _Pragma("unroll") for (int k = 0; k < 2; ++k) dst[m][k] = *(const LAS bf16x8*)(lds + PG8_SA(b, h) + aoff + m * 2048 + k * 1024); } while (0)
; #define PG8_LDB(dst, b, h) do { _Pragma("unroll") for (int n = 0; n < 2; ++n) _Pragma("unroll") for (int k = 0; k < 2; ++k) dst[n][k] = *(const LAS bf16x8*)(lds + PG8_SB(b, h) + boff + n * 2048 + k * 1024); } while (0)
; #define PG8_MMA(ai, bj, At, Bt) do { __builtin_amdgcn_s_setprio(1); _Pragma("unroll") for (int m = 0; m < 4; ++m) _Pragma("unroll") for (int n = 0; n < 2; ++n) _Pragma("unroll") for (int k = 0; k < 2; ++k) \
;     acc[ai][bj][m][n] = __builtin_amdgcn_mfma_f32_16x16x32_bf16(Bt[n][k], At[m][k], acc[ai][bj][m][n], 0, 0, 0); __builtin_amdgcn_s_setprio(0); } while (0)
; #define PG8_WAIT_V(n) asm volatile("s_waitcnt vmcnt(" #n ")" ::: "memory")
; #define PG8_WAIT_L(n) asm volatile("s_waitcnt lgkmcnt(" #n ")" ::: "memory")
; #define PG8_BAR __builtin_amdgcn_s_barrier()
; #define PG8_SCHED __builtin_amdgcn_sched_barrier(0)
; template <class Epi, class Sched>
; DI void gemm_phase(LAS unsigned char* lds, const Gemm g, const Sched& S, const Epi& E) {
;     ...
;       PG8_STAGE(PG8_SB(0, 1), b2 + hstepB, voffB);
;       PG8_WAIT_V(6); PG8_BAR; PG8_MMA(1, 1, At, B1); PG8_BAR;
;       PG8_LDB(B0, 1, 0); PG8_SCHED; PG8_LDA(At, 1, 0); PG8_STAGE(PG8_SA(0, 1), a2 + hstep, voffA);
;       PG8_WAIT_L(8); PG8_BAR; PG8_WAIT_L(0); PG8_MMA(0, 0, At, B0); PG8_BAR; PG8_SCHED;
;       PG8_LDB(B1, 1, 1); PG8_STAGE(PG8_SB(1, 0), b3, voffB);
;       PG8_BAR; PG8_WAIT_L(0); PG8_MMA(0, 1, At, B1); PG8_BAR;
	s_add_u32 s8, s8, s14
	s_addc_u32 s9, s9, s15
	s_add_i32 s24, s25, s29
	v_lshl_add_u64 v[182:183], s[8:9], 0, v[190:191]
	s_mov_b32 m0, s24
	v_lshl_add_u64 v[184:185], s[8:9], 0, v[186:187]
	global_load_lds_dwordx4 v[182:183], off
	s_add_i32 m0, s24, 0x2000
	s_nop 0
	global_load_lds_dwordx4 v[184:185], off
	s_waitcnt vmcnt(10)
	s_barrier
	v_mfma_f32_16x16x32_bf16 v[54:57], v[206:209], v[118:121], v[54:57]
	v_mfma_f32_16x16x32_bf16 v[50:53], v[222:225], v[118:121], v[50:53]
	v_mfma_f32_16x16x32_bf16 v[38:41], v[206:209], v[126:129], v[38:41]
	v_mfma_f32_16x16x32_bf16 v[34:37], v[222:225], v[126:129], v[34:37]
	v_mfma_f32_16x16x32_bf16 v[22:25], v[206:209], v[134:137], v[22:25]
	v_mfma_f32_16x16x32_bf16 v[18:21], v[222:225], v[134:137], v[18:21]
	v_mfma_f32_16x16x32_bf16 v[6:9], v[206:209], v[150:153], v[6:9]
	v_mfma_f32_16x16x32_bf16 v[2:5], v[222:225], v[150:153], v[2:5]
	v_mfma_f32_16x16x32_bf16 v[54:57], v[218:221], v[122:125], v[54:57]
	v_mfma_f32_16x16x32_bf16 v[50:53], v[226:229], v[122:125], v[50:53]
	v_mfma_f32_16x16x32_bf16 v[38:41], v[218:221], v[130:133], v[38:41]
	v_mfma_f32_16x16x32_bf16 v[34:37], v[226:229], v[130:133], v[34:37]
	v_mfma_f32_16x16x32_bf16 v[22:25], v[218:221], v[146:149], v[22:25]
	v_mfma_f32_16x16x32_bf16 v[18:21], v[226:229], v[146:149], v[18:21]
	v_mfma_f32_16x16x32_bf16 v[6:9], v[218:221], v[162:165], v[6:9]
	v_mfma_f32_16x16x32_bf16 v[2:5], v[226:229], v[162:165], v[2:5]
	s_add_i32 s8, 16, 0x18000
	v_add_u32_e32 v0, s8, v215
	s_barrier
	ds_read_b128 v[66:69], v0
	ds_read_b128 v[70:73], v0 offset:1024
	ds_read_b128 v[74:77], v0 offset:2048
	ds_read_b128 v[78:81], v0 offset:3072
	s_add_u32 s6, s6, s12
	s_addc_u32 s7, s7, s13
	s_mov_b32 m0, s34
	v_lshl_add_u64 v[134:135], s[6:7], 0, v[192:193]
	ds_read_b128 v[118:121], v216 offset:32768
	ds_read_b128 v[122:125], v216 offset:33792
	ds_read_b128 v[126:129], v216 offset:34816
	ds_read_b128 v[130:133], v216 offset:35840
	ds_read_b128 v[206:209], v216 offset:36864
	ds_read_b128 v[218:221], v216 offset:37888
	ds_read_b128 v[222:225], v216 offset:38912
	ds_read_b128 v[226:229], v216 offset:39936
	global_load_lds_dwordx4 v[134:135], off
	v_lshl_add_u64 v[134:135], s[6:7], 0, v[188:189]
	s_mov_b32 m0, s35
	s_nop 0
	global_load_lds_dwordx4 v[134:135], off
	s_waitcnt lgkmcnt(8)
	s_waitcnt vmcnt(10)
	s_barrier
	s_waitcnt lgkmcnt(0)
	s_waitcnt lgkmcnt(0)
	v_mfma_f32_16x16x32_bf16 v[134:137], v[66:69], v[118:121], v[174:177]
	v_mfma_f32_16x16x32_bf16 v[174:177], v[70:73], v[122:125], v[134:137]
	v_mfma_f32_16x16x32_bf16 v[134:137], v[74:77], v[118:121], v[170:173]
	v_mfma_f32_16x16x32_bf16 v[170:173], v[78:81], v[122:125], v[134:137]
	v_mfma_f32_16x16x32_bf16 v[134:137], v[66:69], v[126:129], v[158:161]
	v_mfma_f32_16x16x32_bf16 v[158:161], v[70:73], v[130:133], v[134:137]
	v_mfma_f32_16x16x32_bf16 v[134:137], v[74:77], v[126:129], v[154:157]
	v_mfma_f32_16x16x32_bf16 v[154:157], v[78:81], v[130:133], v[134:137]
	v_mfma_f32_16x16x32_bf16 v[134:137], v[66:69], v[206:209], v[142:145]
	v_mfma_f32_16x16x32_bf16 v[142:145], v[70:73], v[218:221], v[134:137]
	v_mfma_f32_16x16x32_bf16 v[134:137], v[74:77], v[206:209], v[138:141]
	v_mfma_f32_16x16x32_bf16 v[110:113], v[66:69], v[222:225], v[110:113]
	v_mfma_f32_16x16x32_bf16 v[106:109], v[74:77], v[222:225], v[106:109]
	v_mfma_f32_16x16x32_bf16 v[138:141], v[78:81], v[218:221], v[134:137]
	v_mfma_f32_16x16x32_bf16 v[110:113], v[70:73], v[226:229], v[110:113]
	v_mfma_f32_16x16x32_bf16 v[106:109], v[78:81], v[226:229], v[106:109]
	s_barrier
	s_add_i32 s6, 16, 0x1c000
	s_add_i32 s7, s8, s29
	v_add_u32_e32 v0, s6, v215
	v_lshl_add_u64 v[134:135], v[246:247], 0, s[70:71]
	s_mov_b32 m0, s7
	ds_read_b128 v[230:233], v0
	ds_read_b128 v[234:237], v0 offset:1024
	ds_read_b128 v[238:241], v0 offset:2048
	ds_read_b128 v[242:245], v0 offset:3072
	global_load_lds_dwordx4 v[134:135], off
	v_lshl_add_u64 v[134:135], v[248:249], 0, s[70:71]
	s_add_i32 m0, s7, 0x2000
	s_nop 0
	global_load_lds_dwordx4 v[134:135], off
	s_waitcnt vmcnt(10)
	s_barrier
; #define PG8_STAGE(bufoff, gbase, voff) do { _Pragma("unroll") for (int _i = 0; _i < 2; ++_i) \
;     __builtin_amdgcn_global_load_lds((const unsigned*)((const char*)(gbase) + (voff)[_i]), (LAS unsigned*)(lds + (bufoff) + ldsw + _i * 8192), 16, 0, 0); } while (0)
; #define PG8_LDA(dst, b, h) do { _Pragma("unroll") for (int m = 0; m < 4; ++m) _Pragma("unroll") for (int k = 0; k < 2; ++k) dst[m][k] = *(const LAS bf16x8*)(lds + PG8_SA(b, h) + aoff + m * 2048 + k * 1024); } while (0)
; #define PG8_MMA(ai, bj, At, Bt) do { __builtin_amdgcn_s_setprio(1); _Pragma("unroll") for (int m = 0; m < 4; ++m) _Pragma("unroll") for (int n = 0; n < 2; ++n) _Pragma("unroll") for (int k = 0; k < 2; ++k) \
;     acc[ai][bj][m][n] = __builtin_amdgcn_mfma_f32_16x16x32_bf16(Bt[n][k], At[m][k], acc[ai][bj][m][n], 0, 0, 0); __builtin_amdgcn_s_setprio(0); } while (0)
; #define PG8_WAIT_V(n) asm volatile("s_waitcnt vmcnt(" #n ")" ::: "memory")
; #define PG8_WAIT_L(n) asm volatile("s_waitcnt lgkmcnt(" #n ")" ::: "memory")
; #define PG8_BAR __builtin_amdgcn_s_barrier()
; #define PG8_SCHED __builtin_amdgcn_sched_barrier(0)
; template <class Epi, class Sched>
; DI void gemm_phase(LAS unsigned char* lds, const Gemm g, const Sched& S, const Epi& E) {
;     ...
;       PG8_LDA(At, 1, 1); PG8_STAGE(PG8_SA(1, 0), a3, voffA);
;       PG8_BAR; PG8_WAIT_L(0); PG8_MMA(1, 0, At, B0); PG8_BAR; PG8_SCHED;
;       PG8_STAGE(PG8_SB(1, 1), b3 + hstepB, voffB);
;       PG8_WAIT_V(6); PG8_BAR; PG8_MMA(1, 1, At, B1); PG8_BAR;
;     }
	s_waitcnt lgkmcnt(0)
	s_waitcnt lgkmcnt(0)
	v_mfma_f32_16x16x32_bf16 v[82:85], v[238:241], v[118:121], v[82:85]
	v_mfma_f32_16x16x32_bf16 v[162:165], v[242:245], v[122:125], v[82:85]
	v_mfma_f32_16x16x32_bf16 v[82:85], v[230:233], v[126:129], v[86:89]
	v_mfma_f32_16x16x32_bf16 v[150:153], v[234:237], v[130:133], v[82:85]
	v_mfma_f32_16x16x32_bf16 v[82:85], v[238:241], v[126:129], v[94:97]
	v_mfma_f32_16x16x32_bf16 v[134:137], v[230:233], v[118:121], v[166:169]
	v_mfma_f32_16x16x32_bf16 v[146:149], v[242:245], v[130:133], v[82:85]
	v_mfma_f32_16x16x32_bf16 v[82:85], v[230:233], v[206:209], v[98:101]
	v_mfma_f32_16x16x32_bf16 v[166:169], v[234:237], v[122:125], v[134:137]
	v_mfma_f32_16x16x32_bf16 v[134:137], v[234:237], v[218:221], v[82:85]
	v_mfma_f32_16x16x32_bf16 v[82:85], v[238:241], v[206:209], v[114:117]
	v_mfma_f32_16x16x32_bf16 v[130:133], v[242:245], v[218:221], v[82:85]
	v_mfma_f32_16x16x32_bf16 v[82:85], v[230:233], v[222:225], v[102:105]
	v_mfma_f32_16x16x32_bf16 v[102:105], v[234:237], v[226:229], v[82:85]
	v_mfma_f32_16x16x32_bf16 v[82:85], v[238:241], v[222:225], v[90:93]
	v_mfma_f32_16x16x32_bf16 v[90:93], v[242:245], v[226:229], v[82:85]
	s_mov_b32 m0, s36
	v_lshl_add_u64 v[206:207], v[250:251], 0, s[70:71]
	s_barrier
	s_nop 2
	ds_read_b128 v[82:85], v216 offset:49152
	ds_read_b128 v[86:89], v216 offset:50176
	ds_read_b128 v[94:97], v216 offset:51200
	ds_read_b128 v[98:101], v216 offset:52224
	ds_read_b128 v[114:117], v216 offset:53248
	ds_read_b128 v[118:121], v216 offset:54272
	ds_read_b128 v[122:125], v216 offset:55296
	ds_read_b128 v[126:129], v216 offset:56320
	global_load_lds_dwordx4 v[206:207], off
	v_lshl_add_u64 v[180:181], v[180:181], 0, s[70:71]
	s_mov_b32 m0, s37
	s_nop 0
	global_load_lds_dwordx4 v[180:181], off
	s_barrier
	s_waitcnt lgkmcnt(0)
	s_waitcnt lgkmcnt(0)
	v_mfma_f32_16x16x32_bf16 v[62:65], v[66:69], v[82:85], v[62:65]
	v_mfma_f32_16x16x32_bf16 v[58:61], v[74:77], v[82:85], v[58:61]
	v_mfma_f32_16x16x32_bf16 v[46:49], v[66:69], v[94:97], v[46:49]
	v_mfma_f32_16x16x32_bf16 v[42:45], v[74:77], v[94:97], v[42:45]
	v_mfma_f32_16x16x32_bf16 v[30:33], v[66:69], v[114:117], v[30:33]
	v_mfma_f32_16x16x32_bf16 v[26:29], v[74:77], v[114:117], v[26:29]
	v_mfma_f32_16x16x32_bf16 v[14:17], v[66:69], v[122:125], v[14:17]
	v_mfma_f32_16x16x32_bf16 v[10:13], v[74:77], v[122:125], v[10:13]
	v_mfma_f32_16x16x32_bf16 v[62:65], v[70:73], v[86:89], v[62:65]
	v_mfma_f32_16x16x32_bf16 v[58:61], v[78:81], v[86:89], v[58:61]
	v_mfma_f32_16x16x32_bf16 v[46:49], v[70:73], v[98:101], v[46:49]
	v_mfma_f32_16x16x32_bf16 v[42:45], v[78:81], v[98:101], v[42:45]
	v_mfma_f32_16x16x32_bf16 v[30:33], v[70:73], v[118:121], v[30:33]
	v_mfma_f32_16x16x32_bf16 v[26:29], v[78:81], v[118:121], v[26:29]
	v_mfma_f32_16x16x32_bf16 v[14:17], v[70:73], v[126:129], v[14:17]
	v_mfma_f32_16x16x32_bf16 v[10:13], v[78:81], v[126:129], v[10:13]
	s_barrier
	s_add_i32 s6, s6, s29
	v_lshl_add_u64 v[66:67], v[182:183], 0, s[70:71]
	s_mov_b32 m0, s6
	s_nop 0
	global_load_lds_dwordx4 v[66:67], off
	v_lshl_add_u64 v[66:67], v[184:185], 0, s[70:71]
	s_add_i32 m0, s6, 0x2000
	s_nop 0
	global_load_lds_dwordx4 v[66:67], off
	s_waitcnt vmcnt(10)
	s_barrier
	v_mfma_f32_16x16x32_bf16 v[54:57], v[230:233], v[82:85], v[54:57]
	v_mfma_f32_16x16x32_bf16 v[50:53], v[238:241], v[82:85], v[50:53]
	v_mfma_f32_16x16x32_bf16 v[38:41], v[230:233], v[94:97], v[38:41]
	v_mfma_f32_16x16x32_bf16 v[34:37], v[238:241], v[94:97], v[34:37]
	v_mfma_f32_16x16x32_bf16 v[22:25], v[230:233], v[114:117], v[22:25]
	v_mfma_f32_16x16x32_bf16 v[18:21], v[238:241], v[114:117], v[18:21]
	v_mfma_f32_16x16x32_bf16 v[6:9], v[230:233], v[122:125], v[6:9]
	v_mfma_f32_16x16x32_bf16 v[2:5], v[238:241], v[122:125], v[2:5]
	v_mfma_f32_16x16x32_bf16 v[54:57], v[234:237], v[86:89], v[54:57]
	v_mfma_f32_16x16x32_bf16 v[50:53], v[242:245], v[86:89], v[50:53]
	v_mfma_f32_16x16x32_bf16 v[38:41], v[234:237], v[98:101], v[38:41]
	v_mfma_f32_16x16x32_bf16 v[34:37], v[242:245], v[98:101], v[34:37]
	v_mfma_f32_16x16x32_bf16 v[22:25], v[234:237], v[118:121], v[22:25]
	v_mfma_f32_16x16x32_bf16 v[18:21], v[242:245], v[118:121], v[18:21]
	v_mfma_f32_16x16x32_bf16 v[6:9], v[234:237], v[126:129], v[6:9]
	v_mfma_f32_16x16x32_bf16 v[2:5], v[242:245], v[126:129], v[2:5]
	s_add_u32 s2, s2, 0x100
	s_addc_u32 s3, s3, 0
	s_add_u32 s11, s11, 0x100
	s_addc_u32 s22, s22, 0
	s_cmp_ge_i32 s23, s39
	s_mov_b32 s6, s23
	s_barrier
	s_cbranch_scc0 .LBB0_519
	v_mov_b64_e32 v[244:245], v[178:179]
	v_mov_b64_e32 v[178:179], 0xff
	v_mov_b64_e32 v[246:247], 0x1ff
	v_mov_b32_e32 v195, v217
	v_mov_b32_e32 v248, v210
	v_mov_b32_e32 v210, v201
	v_mov_b32_e32 v184, v200

; #define PG8_STAGE(bufoff, gbase, voff) do { _Pragma("unroll") for (int _i = 0; _i < 2; ++_i) \
;     __builtin_amdgcn_global_load_lds((const unsigned*)((const char*)(gbase) + (voff)[_i]), (LAS unsigned*)(lds + (bufoff) + ldsw + _i * 8192), 16, 0, 0); } while (0)
; #define PG8_LDA(dst, b, h) do { _Pragma("unroll") for (int m = 0; m < 4; ++m) _Pragma("unroll") for (int k = 0; k < 2; ++k) dst[m][k] = *(const LAS bf16x8*)(lds + PG8_SA(b, h) + aoff + m * 2048 + k * 1024); } while (0)
; #define PG8_LDB(dst, b, h) do { _Pragma("unroll") for (int n = 0; n < 2; ++n) _Pragma("unroll") for (int k = 0; k < 2; ++k) dst[n][k] = *(const LAS bf16x8*)(lds + PG8_SB(b, h) + boff + n * 2048 + k * 1024); } while (0)
; #define PG8_MMA(ai, bj, At, Bt) do { __builtin_amdgcn_s_setprio(1); _Pragma("unroll") for (int m = 0; m < 4; ++m) _Pragma("unroll") for (int n = 0; n < 2; ++n) _Pragma("unroll") for (int k = 0; k < 2; ++k) \
;     acc[ai][bj][m][n] = __builtin_amdgcn_mfma_f32_16x16x32_bf16(Bt[n][k], At[m][k], acc[ai][bj][m][n], 0, 0, 0); __builtin_amdgcn_s_setprio(0); } while (0)
; #define PG8_WAIT_L(n) asm volatile("s_waitcnt lgkmcnt(" #n ")" ::: "memory")
; #define PG8_BAR __builtin_amdgcn_s_barrier()
; #define PG8_SCHED __builtin_amdgcn_sched_barrier(0)
; template <class Epi, class Sched>
; DI void gemm_phase(LAS unsigned char* lds, const Gemm g, const Sched& S, const Epi& E) {
;     ...
;     for (int t = 0; t < nt; t += 2) {
;       const bool last = (t == nt - 2);
;       const char* a1 = cA + (size_t)(t + 1) * kstep;
;       const char* a2 = last ? nA : cA + (size_t)(t + 2) * kstep; const char* b2 = last ? nB : cB + (size_t)(t + 2) * kstep;
;       const char* a3 = a2 + kstep; const char* b3 = b2 + kstep;
;       PG8_LDB(B0, 0, 0); PG8_SCHED; PG8_LDA(At, 0, 0); PG8_STAGE(PG8_SA(1, 1), a1 + hstep, voffA);
;       PG8_WAIT_L(8); PG8_BAR; PG8_WAIT_L(0); PG8_MMA(0, 0, At, B0); PG8_BAR; PG8_SCHED;
;       PG8_LDB(B1, 0, 1); PG8_STAGE(PG8_SB(0, 0), b2, voffB);
;       PG8_BAR; PG8_WAIT_L(0); PG8_MMA(0, 1, At, B1); PG8_BAR;
;       PG8_LDA(At, 0, 1); PG8_STAGE(PG8_SA(0, 0), a2, voffA);
;       PG8_BAR; PG8_WAIT_L(0); PG8_MMA(1, 0, At, B0); PG8_BAR; PG8_SCHED;
.LBB0_831:
	s_add_i32 s26, s10, 2
	s_add_u32 s11, s8, 0xfe000080
	s_addc_u32 s12, s9, -1
	s_cmp_lg_u32 s25, s10
	s_cselect_b32 s13, s12, 0
	s_cselect_b32 s12, s11, 0
	s_add_u32 s10, s6, s12
	s_addc_u32 s11, s7, s13
	s_add_i32 s27, 16, 0x10000
	v_add_u32_e32 v146, s27, v92
	ds_read_b128 v[94:97], v146
	ds_read_b128 v[152:155], v146 offset:1024
	ds_read_b128 v[156:159], v146 offset:2048
	ds_read_b128 v[160:163], v146 offset:3072
	s_add_u32 s12, s4, s12
	s_addc_u32 s13, s5, s13
	v_lshl_add_u64 v[146:147], v[88:89], 0, s[8:9]
	s_add_i32 m0, s18, 0xc000
	ds_read_b128 v[164:167], v93
	ds_read_b128 v[168:171], v93 offset:1024
	ds_read_b128 v[172:175], v93 offset:2048
	ds_read_b128 v[186:189], v93 offset:3072
	ds_read_b128 v[190:193], v93 offset:4096
	ds_read_b128 v[198:201], v93 offset:5120
	ds_read_b128 v[202:205], v93 offset:6144
	ds_read_b128 v[206:209], v93 offset:7168
	global_load_lds_dwordx4 v[146:147], off
	v_lshl_add_u64 v[146:147], v[90:91], 0, s[8:9]
	s_add_i32 m0, s18, 0xe000
	s_nop 0
	global_load_lds_dwordx4 v[146:147], off
	s_waitcnt lgkmcnt(8)
	s_waitcnt vmcnt(10)
	s_barrier
	s_waitcnt lgkmcnt(0)
	s_waitcnt lgkmcnt(0)
	v_mfma_f32_16x16x32_bf16 v[142:145], v[94:97], v[164:167], v[142:145]
	v_mfma_f32_16x16x32_bf16 v[138:141], v[156:159], v[164:167], v[138:141]
	v_mfma_f32_16x16x32_bf16 v[126:129], v[94:97], v[172:175], v[126:129]
	v_mfma_f32_16x16x32_bf16 v[122:125], v[156:159], v[172:175], v[122:125]
	v_mfma_f32_16x16x32_bf16 v[110:113], v[94:97], v[190:193], v[110:113]
	v_mfma_f32_16x16x32_bf16 v[106:109], v[156:159], v[190:193], v[106:109]
	v_mfma_f32_16x16x32_bf16 v[78:81], v[94:97], v[202:205], v[78:81]
	v_mfma_f32_16x16x32_bf16 v[74:77], v[156:159], v[202:205], v[74:77]
	v_mfma_f32_16x16x32_bf16 v[142:145], v[152:155], v[168:171], v[142:145]
	v_mfma_f32_16x16x32_bf16 v[138:141], v[160:163], v[168:171], v[138:141]
	v_mfma_f32_16x16x32_bf16 v[126:129], v[152:155], v[186:189], v[126:129]
	v_mfma_f32_16x16x32_bf16 v[122:125], v[160:163], v[186:189], v[122:125]
	v_mfma_f32_16x16x32_bf16 v[110:113], v[152:155], v[198:201], v[110:113]
	v_mfma_f32_16x16x32_bf16 v[106:109], v[160:163], v[198:201], v[106:109]
	v_mfma_f32_16x16x32_bf16 v[78:81], v[152:155], v[206:209], v[78:81]
	v_mfma_f32_16x16x32_bf16 v[74:77], v[160:163], v[206:209], v[74:77]
	s_barrier
	s_add_i32 s28, 16, 0x14000
	v_add_u32_e32 v146, s28, v92
	s_add_i32 s27, s27, s17
	ds_read_b128 v[214:217], v146
	ds_read_b128 v[218:221], v146 offset:1024
	ds_read_b128 v[222:225], v146 offset:2048
	ds_read_b128 v[226:229], v146 offset:3072
	v_lshl_add_u64 v[146:147], s[12:13], 0, v[0:1]
	s_mov_b32 m0, s27
	v_lshl_add_u64 v[176:177], s[12:13], 0, v[82:83]
	global_load_lds_dwordx4 v[146:147], off
	s_add_i32 m0, s27, 0x2000
	s_nop 0
	global_load_lds_dwordx4 v[176:177], off
	s_waitcnt vmcnt(10)
	s_barrier
	s_waitcnt lgkmcnt(0)
	s_waitcnt lgkmcnt(0)
	v_mfma_f32_16x16x32_bf16 v[134:137], v[214:217], v[164:167], v[134:137]
	v_mfma_f32_16x16x32_bf16 v[130:133], v[222:225], v[164:167], v[130:133]
	v_mfma_f32_16x16x32_bf16 v[118:121], v[214:217], v[172:175], v[118:121]
	v_mfma_f32_16x16x32_bf16 v[114:117], v[222:225], v[172:175], v[114:117]
	v_mfma_f32_16x16x32_bf16 v[102:105], v[214:217], v[190:193], v[102:105]
	v_mfma_f32_16x16x32_bf16 v[98:101], v[222:225], v[190:193], v[98:101]
	v_mfma_f32_16x16x32_bf16 v[70:73], v[214:217], v[202:205], v[70:73]
	v_mfma_f32_16x16x32_bf16 v[66:69], v[222:225], v[202:205], v[66:69]
	v_mfma_f32_16x16x32_bf16 v[134:137], v[218:221], v[168:171], v[134:137]
	v_mfma_f32_16x16x32_bf16 v[130:133], v[226:229], v[168:171], v[130:133]
	v_mfma_f32_16x16x32_bf16 v[118:121], v[218:221], v[186:189], v[118:121]
	v_mfma_f32_16x16x32_bf16 v[114:117], v[226:229], v[186:189], v[114:117]
	v_mfma_f32_16x16x32_bf16 v[102:105], v[218:221], v[198:201], v[102:105]
	v_mfma_f32_16x16x32_bf16 v[98:101], v[226:229], v[198:201], v[98:101]
	v_mfma_f32_16x16x32_bf16 v[70:73], v[218:221], v[206:209], v[70:73]
	v_mfma_f32_16x16x32_bf16 v[66:69], v[226:229], v[206:209], v[66:69]
	s_mov_b32 m0, s18
	v_lshl_add_u64 v[230:231], s[10:11], 0, v[86:87]
	s_barrier
	ds_read_b128 v[164:167], v93 offset:16384
	ds_read_b128 v[168:171], v93 offset:17408
	ds_read_b128 v[172:175], v93 offset:18432
	ds_read_b128 v[186:189], v93 offset:19456
	ds_read_b128 v[190:193], v93 offset:20480
	ds_read_b128 v[198:201], v93 offset:21504
	ds_read_b128 v[202:205], v93 offset:22528
	ds_read_b128 v[206:209], v93 offset:23552
	global_load_lds_dwordx4 v[230:231], off
	v_lshl_add_u64 v[232:233], s[10:11], 0, v[84:85]
	s_mov_b32 m0, s19
	s_nop 0
	global_load_lds_dwordx4 v[232:233], off
	s_barrier
	s_waitcnt lgkmcnt(0)
	s_waitcnt lgkmcnt(0)
	v_mfma_f32_16x16x32_bf16 v[62:65], v[94:97], v[164:167], v[62:65]
	v_mfma_f32_16x16x32_bf16 v[58:61], v[156:159], v[164:167], v[58:61]
	v_mfma_f32_16x16x32_bf16 v[46:49], v[94:97], v[172:175], v[46:49]
	v_mfma_f32_16x16x32_bf16 v[42:45], v[156:159], v[172:175], v[42:45]
	v_mfma_f32_16x16x32_bf16 v[30:33], v[94:97], v[190:193], v[30:33]
	v_mfma_f32_16x16x32_bf16 v[26:29], v[156:159], v[190:193], v[26:29]
	v_mfma_f32_16x16x32_bf16 v[14:17], v[94:97], v[202:205], v[14:17]
	v_mfma_f32_16x16x32_bf16 v[10:13], v[156:159], v[202:205], v[10:13]
	v_mfma_f32_16x16x32_bf16 v[62:65], v[152:155], v[168:171], v[62:65]
	v_mfma_f32_16x16x32_bf16 v[58:61], v[160:163], v[168:171], v[58:61]
	v_mfma_f32_16x16x32_bf16 v[46:49], v[152:155], v[186:189], v[46:49]
	v_mfma_f32_16x16x32_bf16 v[42:45], v[160:163], v[186:189], v[42:45]
	v_mfma_f32_16x16x32_bf16 v[30:33], v[152:155], v[198:201], v[30:33]
	v_mfma_f32_16x16x32_bf16 v[26:29], v[160:163], v[198:201], v[26:29]
	v_mfma_f32_16x16x32_bf16 v[14:17], v[152:155], v[206:209], v[14:17]
	v_mfma_f32_16x16x32_bf16 v[10:13], v[160:163], v[206:209], v[10:13]
	s_barrier
; #define PG8_STAGE(bufoff, gbase, voff) do { _Pragma("unroll") for (int _i = 0; _i < 2; ++_i) \
;     __builtin_amdgcn_global_load_lds((const unsigned*)((const char*)(gbase) + (voff)[_i]), (LAS unsigned*)(lds + (bufoff) + ldsw + _i * 8192), 16, 0, 0); } while (0)
; #define PG8_LDA(dst, b, h) do { _Pragma("unroll") for (int m = 0; m < 4; ++m) _Pragma("unroll") for (int k = 0; k < 2; ++k) dst[m][k] = *(const LAS bf16x8*)(lds + PG8_SA(b, h) + aoff + m * 2048 + k * 1024); } while (0)
; #define PG8_LDB(dst, b, h) do { _Pragma("unroll") for (int n = 0; n < 2; ++n) _Pragma("unroll") for (int k = 0; k < 2; ++k) dst[n][k] = *(const LAS bf16x8*)(lds + PG8_SB(b, h) + boff + n * 2048 + k * 1024); } while (0)
; #define PG8_MMA(ai, bj, At, Bt) do { __builtin_amdgcn_s_setprio(1); _Pragma("unroll") for (int m = 0; m < 4; ++m) _Pragma("unroll") for (int n = 0; n < 2; ++n) _Pragma("unroll") for (int k = 0; k < 2; ++k) \
;     acc[ai][bj][m][n] = __builtin_amdgcn_mfma_f32_16x16x32_bf16(Bt[n][k], At[m][k], acc[ai][bj][m][n], 0, 0, 0); __builtin_amdgcn_s_setprio(0); } while (0)
; #define PG8_WAIT_V(n) asm volatile("s_waitcnt vmcnt(" #n ")" ::: "memory")
; #define PG8_WAIT_L(n) asm volatile("s_waitcnt lgkmcnt(" #n ")" ::: "memory")
; #define PG8_BAR __builtin_amdgcn_s_barrier()
; #define PG8_SCHED __builtin_amdgcn_sched_barrier(0)
; template <class Epi, class Sched>
; DI void gemm_phase(LAS unsigned char* lds, const Gemm g, const Sched& S, const Epi& E) {
;     ...
;       PG8_STAGE(PG8_SB(0, 1), b2 + hstepB, voffB);
;       PG8_WAIT_V(6); PG8_BAR; PG8_MMA(1, 1, At, B1); PG8_BAR;
;       PG8_LDB(B0, 1, 0); PG8_SCHED; PG8_LDA(At, 1, 0); PG8_STAGE(PG8_SA(0, 1), a2 + hstep, voffA);
;       PG8_WAIT_L(8); PG8_BAR; PG8_WAIT_L(0); PG8_MMA(0, 0, At, B0); PG8_BAR; PG8_SCHED;
;       PG8_LDB(B1, 1, 1); PG8_STAGE(PG8_SB(1, 0), b3, voffB);
;       PG8_BAR; PG8_WAIT_L(0); PG8_MMA(0, 1, At, B1); PG8_BAR;
	s_add_u32 s12, s12, s2
	s_addc_u32 s13, s13, s3
	s_add_i32 s27, s28, s17
	v_lshl_add_u64 v[234:235], s[12:13], 0, v[0:1]
	s_mov_b32 m0, s27
	v_lshl_add_u64 v[236:237], s[12:13], 0, v[82:83]
	global_load_lds_dwordx4 v[234:235], off
	s_add_i32 m0, s27, 0x2000
	s_nop 0
	global_load_lds_dwordx4 v[236:237], off
	s_waitcnt vmcnt(10)
	s_barrier
	v_mfma_f32_16x16x32_bf16 v[54:57], v[214:217], v[164:167], v[54:57]
	v_mfma_f32_16x16x32_bf16 v[50:53], v[222:225], v[164:167], v[50:53]
	v_mfma_f32_16x16x32_bf16 v[38:41], v[214:217], v[172:175], v[38:41]
	v_mfma_f32_16x16x32_bf16 v[34:37], v[222:225], v[172:175], v[34:37]
	v_mfma_f32_16x16x32_bf16 v[22:25], v[214:217], v[190:193], v[22:25]
	v_mfma_f32_16x16x32_bf16 v[18:21], v[222:225], v[190:193], v[18:21]
	v_mfma_f32_16x16x32_bf16 v[6:9], v[214:217], v[202:205], v[6:9]
	v_mfma_f32_16x16x32_bf16 v[2:5], v[222:225], v[202:205], v[2:5]
	v_mfma_f32_16x16x32_bf16 v[54:57], v[218:221], v[168:171], v[54:57]
	v_mfma_f32_16x16x32_bf16 v[50:53], v[226:229], v[168:171], v[50:53]
	v_mfma_f32_16x16x32_bf16 v[38:41], v[218:221], v[186:189], v[38:41]
	v_mfma_f32_16x16x32_bf16 v[34:37], v[226:229], v[186:189], v[34:37]
	v_mfma_f32_16x16x32_bf16 v[22:25], v[218:221], v[198:201], v[22:25]
	v_mfma_f32_16x16x32_bf16 v[18:21], v[226:229], v[198:201], v[18:21]
	v_mfma_f32_16x16x32_bf16 v[6:9], v[218:221], v[206:209], v[6:9]
	v_mfma_f32_16x16x32_bf16 v[2:5], v[226:229], v[206:209], v[2:5]
	s_add_i32 s12, 16, 0x18000
	v_add_u32_e32 v149, s12, v92
	s_barrier
	ds_read_b128 v[94:97], v149
	ds_read_b128 v[152:155], v149 offset:1024
	ds_read_b128 v[156:159], v149 offset:2048
	ds_read_b128 v[160:163], v149 offset:3072
	s_add_u32 s10, s10, s0
	s_addc_u32 s11, s11, s1
	s_mov_b32 m0, s20
	v_lshl_add_u64 v[214:215], s[10:11], 0, v[86:87]
	ds_read_b128 v[164:167], v93 offset:32768
	ds_read_b128 v[168:171], v93 offset:33792
	ds_read_b128 v[172:175], v93 offset:34816
	ds_read_b128 v[186:189], v93 offset:35840
	ds_read_b128 v[190:193], v93 offset:36864
	ds_read_b128 v[198:201], v93 offset:37888
	ds_read_b128 v[202:205], v93 offset:38912
	ds_read_b128 v[206:209], v93 offset:39936
	global_load_lds_dwordx4 v[214:215], off
	v_lshl_add_u64 v[214:215], s[10:11], 0, v[84:85]
	s_mov_b32 m0, s21
	s_nop 0
	global_load_lds_dwordx4 v[214:215], off
	s_waitcnt lgkmcnt(8)
	s_waitcnt vmcnt(10)
	s_barrier
	s_waitcnt lgkmcnt(0)
	s_waitcnt lgkmcnt(0)
	v_mfma_f32_16x16x32_bf16 v[142:145], v[94:97], v[164:167], v[142:145]
	v_mfma_f32_16x16x32_bf16 v[138:141], v[156:159], v[164:167], v[138:141]
	v_mfma_f32_16x16x32_bf16 v[126:129], v[94:97], v[172:175], v[126:129]
	v_mfma_f32_16x16x32_bf16 v[122:125], v[156:159], v[172:175], v[122:125]
	v_mfma_f32_16x16x32_bf16 v[110:113], v[94:97], v[190:193], v[110:113]
	v_mfma_f32_16x16x32_bf16 v[106:109], v[156:159], v[190:193], v[106:109]
	v_mfma_f32_16x16x32_bf16 v[78:81], v[94:97], v[202:205], v[78:81]
	v_mfma_f32_16x16x32_bf16 v[74:77], v[156:159], v[202:205], v[74:77]
	v_mfma_f32_16x16x32_bf16 v[142:145], v[152:155], v[168:171], v[142:145]
	v_mfma_f32_16x16x32_bf16 v[138:141], v[160:163], v[168:171], v[138:141]
	v_mfma_f32_16x16x32_bf16 v[126:129], v[152:155], v[186:189], v[126:129]
	v_mfma_f32_16x16x32_bf16 v[122:125], v[160:163], v[186:189], v[122:125]
	v_mfma_f32_16x16x32_bf16 v[110:113], v[152:155], v[198:201], v[110:113]
	v_mfma_f32_16x16x32_bf16 v[106:109], v[160:163], v[198:201], v[106:109]
	v_mfma_f32_16x16x32_bf16 v[78:81], v[152:155], v[206:209], v[78:81]
	v_mfma_f32_16x16x32_bf16 v[74:77], v[160:163], v[206:209], v[74:77]
	s_barrier
	s_add_i32 s10, 16, 0x1c000
	s_add_i32 s11, s12, s17
	v_add_u32_e32 v149, s10, v92
	v_lshl_add_u64 v[146:147], v[146:147], 0, s[70:71]
	s_mov_b32 m0, s11
	ds_read_b128 v[214:217], v149
	ds_read_b128 v[218:221], v149 offset:1024
	ds_read_b128 v[222:225], v149 offset:2048
	ds_read_b128 v[226:229], v149 offset:3072
	global_load_lds_dwordx4 v[146:147], off
	v_lshl_add_u64 v[146:147], v[176:177], 0, s[70:71]
	s_add_i32 m0, s11, 0x2000
	s_nop 0
	global_load_lds_dwordx4 v[146:147], off
	s_waitcnt vmcnt(10)
	s_barrier
; #define PG8_STAGE(bufoff, gbase, voff) do { _Pragma("unroll") for (int _i = 0; _i < 2; ++_i) \
;     __builtin_amdgcn_global_load_lds((const unsigned*)((const char*)(gbase) + (voff)[_i]), (LAS unsigned*)(lds + (bufoff) + ldsw + _i * 8192), 16, 0, 0); } while (0)
; #define PG8_LDA(dst, b, h) do { _Pragma("unroll") for (int m = 0; m < 4; ++m) _Pragma("unroll") for (int k = 0; k < 2; ++k) dst[m][k] = *(const LAS bf16x8*)(lds + PG8_SA(b, h) + aoff + m * 2048 + k * 1024); } while (0)
; #define PG8_MMA(ai, bj, At, Bt) do { __builtin_amdgcn_s_setprio(1); _Pragma("unroll") for (int m = 0; m < 4; ++m) _Pragma("unroll") for (int n = 0; n < 2; ++n) _Pragma("unroll") for (int k = 0; k < 2; ++k) \
;     acc[ai][bj][m][n] = __builtin_amdgcn_mfma_f32_16x16x32_bf16(Bt[n][k], At[m][k], acc[ai][bj][m][n], 0, 0, 0); __builtin_amdgcn_s_setprio(0); } while (0)
; #define PG8_WAIT_V(n) asm volatile("s_waitcnt vmcnt(" #n ")" ::: "memory")
; #define PG8_WAIT_L(n) asm volatile("s_waitcnt lgkmcnt(" #n ")" ::: "memory")
; #define PG8_BAR __builtin_amdgcn_s_barrier()
; #define PG8_SCHED __builtin_amdgcn_sched_barrier(0)
; template <class Epi, class Sched>
; DI void gemm_phase(LAS unsigned char* lds, const Gemm g, const Sched& S, const Epi& E) {
;     ...
;     for (int t = 0; t < nt; t += 2) {
;     ...
;       PG8_BAR; PG8_WAIT_L(0); PG8_MMA(0, 1, At, B1); PG8_BAR;
;       PG8_LDA(At, 1, 1); PG8_STAGE(PG8_SA(1, 0), a3, voffA);
;       PG8_BAR; PG8_WAIT_L(0); PG8_MMA(1, 0, At, B0); PG8_BAR; PG8_SCHED;
;       PG8_STAGE(PG8_SB(1, 1), b3 + hstepB, voffB);
;       PG8_WAIT_V(6); PG8_BAR; PG8_MMA(1, 1, At, B1); PG8_BAR;
	s_waitcnt lgkmcnt(0)
	s_waitcnt lgkmcnt(0)
	v_mfma_f32_16x16x32_bf16 v[134:137], v[214:217], v[164:167], v[134:137]
	v_mfma_f32_16x16x32_bf16 v[130:133], v[222:225], v[164:167], v[130:133]
	v_mfma_f32_16x16x32_bf16 v[118:121], v[214:217], v[172:175], v[118:121]
	v_mfma_f32_16x16x32_bf16 v[114:117], v[222:225], v[172:175], v[114:117]
	v_mfma_f32_16x16x32_bf16 v[102:105], v[214:217], v[190:193], v[102:105]
	v_mfma_f32_16x16x32_bf16 v[98:101], v[222:225], v[190:193], v[98:101]
	v_mfma_f32_16x16x32_bf16 v[70:73], v[214:217], v[202:205], v[70:73]
	v_mfma_f32_16x16x32_bf16 v[66:69], v[222:225], v[202:205], v[66:69]
	v_mfma_f32_16x16x32_bf16 v[134:137], v[218:221], v[168:171], v[134:137]
	v_mfma_f32_16x16x32_bf16 v[130:133], v[226:229], v[168:171], v[130:133]
	v_mfma_f32_16x16x32_bf16 v[118:121], v[218:221], v[186:189], v[118:121]
	v_mfma_f32_16x16x32_bf16 v[114:117], v[226:229], v[186:189], v[114:117]
	v_mfma_f32_16x16x32_bf16 v[102:105], v[218:221], v[198:201], v[102:105]
	v_mfma_f32_16x16x32_bf16 v[98:101], v[226:229], v[198:201], v[98:101]
	v_mfma_f32_16x16x32_bf16 v[70:73], v[218:221], v[206:209], v[70:73]
	v_mfma_f32_16x16x32_bf16 v[66:69], v[226:229], v[206:209], v[66:69]
	s_mov_b32 m0, s22
	v_lshl_add_u64 v[146:147], v[230:231], 0, s[70:71]
	s_barrier
	ds_read_b128 v[164:167], v93 offset:49152
	ds_read_b128 v[168:171], v93 offset:50176
	ds_read_b128 v[172:175], v93 offset:51200
	ds_read_b128 v[186:189], v93 offset:52224
	ds_read_b128 v[190:193], v93 offset:53248
	ds_read_b128 v[198:201], v93 offset:54272
	ds_read_b128 v[202:205], v93 offset:55296
	ds_read_b128 v[206:209], v93 offset:56320
	global_load_lds_dwordx4 v[146:147], off
	v_lshl_add_u64 v[146:147], v[232:233], 0, s[70:71]
	s_mov_b32 m0, s23
	s_nop 0
	global_load_lds_dwordx4 v[146:147], off
	s_barrier
	s_waitcnt lgkmcnt(0)
	s_waitcnt lgkmcnt(0)
	v_mfma_f32_16x16x32_bf16 v[62:65], v[94:97], v[164:167], v[62:65]
	v_mfma_f32_16x16x32_bf16 v[58:61], v[156:159], v[164:167], v[58:61]
	v_mfma_f32_16x16x32_bf16 v[46:49], v[94:97], v[172:175], v[46:49]
	v_mfma_f32_16x16x32_bf16 v[42:45], v[156:159], v[172:175], v[42:45]
	v_mfma_f32_16x16x32_bf16 v[30:33], v[94:97], v[190:193], v[30:33]
	v_mfma_f32_16x16x32_bf16 v[26:29], v[156:159], v[190:193], v[26:29]
	v_mfma_f32_16x16x32_bf16 v[14:17], v[94:97], v[202:205], v[14:17]
	v_mfma_f32_16x16x32_bf16 v[10:13], v[156:159], v[202:205], v[10:13]
	v_mfma_f32_16x16x32_bf16 v[62:65], v[152:155], v[168:171], v[62:65]
	v_mfma_f32_16x16x32_bf16 v[58:61], v[160:163], v[168:171], v[58:61]
	v_mfma_f32_16x16x32_bf16 v[46:49], v[152:155], v[186:189], v[46:49]
	v_mfma_f32_16x16x32_bf16 v[42:45], v[160:163], v[186:189], v[42:45]
	v_mfma_f32_16x16x32_bf16 v[30:33], v[152:155], v[198:201], v[30:33]
	v_mfma_f32_16x16x32_bf16 v[26:29], v[160:163], v[198:201], v[26:29]
	v_mfma_f32_16x16x32_bf16 v[14:17], v[152:155], v[206:209], v[14:17]
	v_mfma_f32_16x16x32_bf16 v[10:13], v[160:163], v[206:209], v[10:13]
	s_barrier
	s_add_i32 s10, s10, s17
	v_lshl_add_u64 v[94:95], v[234:235], 0, s[70:71]
	s_mov_b32 m0, s10
	s_nop 0
	global_load_lds_dwordx4 v[94:95], off
	v_lshl_add_u64 v[94:95], v[236:237], 0, s[70:71]
	s_add_i32 m0, s10, 0x2000
	s_nop 0
	global_load_lds_dwordx4 v[94:95], off
	s_waitcnt vmcnt(10)
	s_barrier
	v_mfma_f32_16x16x32_bf16 v[54:57], v[214:217], v[164:167], v[54:57]
	v_mfma_f32_16x16x32_bf16 v[50:53], v[222:225], v[164:167], v[50:53]
	v_mfma_f32_16x16x32_bf16 v[38:41], v[214:217], v[172:175], v[38:41]
	v_mfma_f32_16x16x32_bf16 v[34:37], v[222:225], v[172:175], v[34:37]
	v_mfma_f32_16x16x32_bf16 v[22:25], v[214:217], v[190:193], v[22:25]
	v_mfma_f32_16x16x32_bf16 v[18:21], v[222:225], v[190:193], v[18:21]
	v_mfma_f32_16x16x32_bf16 v[6:9], v[214:217], v[202:205], v[6:9]
	v_mfma_f32_16x16x32_bf16 v[2:5], v[222:225], v[202:205], v[2:5]
	v_mfma_f32_16x16x32_bf16 v[54:57], v[218:221], v[168:171], v[54:57]
	v_mfma_f32_16x16x32_bf16 v[50:53], v[226:229], v[168:171], v[50:53]
	v_mfma_f32_16x16x32_bf16 v[38:41], v[218:221], v[186:189], v[38:41]
	v_mfma_f32_16x16x32_bf16 v[34:37], v[226:229], v[186:189], v[34:37]
	v_mfma_f32_16x16x32_bf16 v[22:25], v[218:221], v[198:201], v[22:25]
	v_mfma_f32_16x16x32_bf16 v[18:21], v[226:229], v[198:201], v[18:21]
	v_mfma_f32_16x16x32_bf16 v[6:9], v[218:221], v[206:209], v[6:9]
	v_mfma_f32_16x16x32_bf16 v[2:5], v[226:229], v[206:209], v[2:5]
	s_add_u32 s8, s8, 0x100
	s_addc_u32 s9, s9, 0
	s_cmp_ge_i32 s26, s24
	s_mov_b32 s10, s26
	s_barrier
	s_cbranch_scc0 .LBB0_831
